# static priority raise for the younger wave half (waves 4-7) around each GEMM inner loop, no per-segment toggles (on top of v103)
# speedup vs baseline: 1.0047x; 1.0047x over previous
.LBB0_157:
	s_add_u32 s24, s24, 0x80080
	s_addc_u32 s25, s25, 0
	s_add_u32 s59, s26, 0x100
	v_mov_b32_e32 v0, 0
	s_addc_u32 s60, s27, 0
	s_mov_b32 s61, -2
	v_mov_b32_e32 v1, v0
	v_mov_b32_e32 v2, v0
	v_mov_b32_e32 v3, v0
	v_mov_b32_e32 v4, v0
	v_mov_b32_e32 v5, v0
	v_mov_b32_e32 v6, v0
	v_mov_b32_e32 v7, v0
	v_mov_b32_e32 v16, v0
	v_mov_b32_e32 v17, v0
	v_mov_b32_e32 v18, v0
	v_mov_b32_e32 v19, v0
	v_mov_b32_e32 v20, v0
	v_mov_b32_e32 v21, v0
	v_mov_b32_e32 v22, v0
	v_mov_b32_e32 v23, v0
	v_mov_b32_e32 v32, v0
	v_mov_b32_e32 v33, v0
	v_mov_b32_e32 v34, v0
	v_mov_b32_e32 v35, v0
	v_mov_b32_e32 v36, v0
	v_mov_b32_e32 v37, v0
	v_mov_b32_e32 v38, v0
	v_mov_b32_e32 v39, v0
	v_mov_b32_e32 v48, v0
	v_mov_b32_e32 v49, v0
	v_mov_b32_e32 v50, v0
	v_mov_b32_e32 v51, v0
	v_mov_b32_e32 v52, v0
	v_mov_b32_e32 v53, v0
	v_mov_b32_e32 v54, v0
	v_mov_b32_e32 v55, v0
	v_mov_b32_e32 v8, v0
	v_mov_b32_e32 v9, v0
	v_mov_b32_e32 v10, v0
	v_mov_b32_e32 v11, v0
	v_mov_b32_e32 v12, v0
	v_mov_b32_e32 v13, v0
	v_mov_b32_e32 v14, v0
	v_mov_b32_e32 v15, v0
	v_mov_b32_e32 v24, v0
	v_mov_b32_e32 v25, v0
	v_mov_b32_e32 v26, v0
	v_mov_b32_e32 v27, v0
	v_mov_b32_e32 v28, v0
	v_mov_b32_e32 v29, v0
	v_mov_b32_e32 v30, v0
	v_mov_b32_e32 v31, v0
	v_mov_b32_e32 v40, v0
	v_mov_b32_e32 v41, v0
	v_mov_b32_e32 v42, v0
	v_mov_b32_e32 v43, v0
	v_mov_b32_e32 v44, v0
	v_mov_b32_e32 v45, v0
	v_mov_b32_e32 v46, v0
	v_mov_b32_e32 v47, v0
	v_mov_b32_e32 v56, v0
	v_mov_b32_e32 v57, v0
	v_mov_b32_e32 v58, v0
	v_mov_b32_e32 v59, v0
	v_mov_b32_e32 v60, v0
	v_mov_b32_e32 v61, v0
	v_mov_b32_e32 v62, v0
	v_mov_b32_e32 v63, v0
	v_mov_b32_e32 v64, v0
	v_mov_b32_e32 v65, v0
	v_mov_b32_e32 v66, v0
	v_mov_b32_e32 v67, v0
	v_mov_b32_e32 v68, v0
	v_mov_b32_e32 v69, v0
	v_mov_b32_e32 v70, v0
	v_mov_b32_e32 v71, v0
	v_mov_b32_e32 v80, v0
	v_mov_b32_e32 v81, v0
	v_mov_b32_e32 v82, v0
	v_mov_b32_e32 v83, v0
	v_mov_b32_e32 v84, v0
	v_mov_b32_e32 v85, v0
	v_mov_b32_e32 v86, v0
	v_mov_b32_e32 v87, v0
	v_mov_b32_e32 v96, v0
	v_mov_b32_e32 v97, v0
	v_mov_b32_e32 v98, v0
	v_mov_b32_e32 v99, v0
	v_mov_b32_e32 v100, v0
	v_mov_b32_e32 v101, v0
	v_mov_b32_e32 v102, v0
	v_mov_b32_e32 v103, v0
	v_mov_b32_e32 v112, v0
	v_mov_b32_e32 v113, v0
	v_mov_b32_e32 v114, v0
	v_mov_b32_e32 v115, v0
	v_mov_b32_e32 v116, v0
	v_mov_b32_e32 v117, v0
	v_mov_b32_e32 v118, v0
	v_mov_b32_e32 v119, v0
	v_mov_b32_e32 v72, v0
	v_mov_b32_e32 v73, v0
	v_mov_b32_e32 v74, v0
	v_mov_b32_e32 v75, v0
	v_mov_b32_e32 v76, v0
	v_mov_b32_e32 v77, v0
	v_mov_b32_e32 v78, v0
	v_mov_b32_e32 v79, v0
	v_mov_b32_e32 v88, v0
	v_mov_b32_e32 v89, v0
	v_mov_b32_e32 v90, v0
	v_mov_b32_e32 v91, v0
	v_mov_b32_e32 v92, v0
	v_mov_b32_e32 v93, v0
	v_mov_b32_e32 v94, v0
	v_mov_b32_e32 v95, v0
	v_mov_b32_e32 v104, v0
	v_mov_b32_e32 v105, v0
	v_mov_b32_e32 v106, v0
	v_mov_b32_e32 v107, v0
	v_mov_b32_e32 v108, v0
	v_mov_b32_e32 v109, v0
	v_mov_b32_e32 v110, v0
	v_mov_b32_e32 v111, v0
	v_mov_b32_e32 v120, v0
	v_mov_b32_e32 v121, v0
	v_mov_b32_e32 v122, v0
	v_mov_b32_e32 v123, v0
	v_mov_b32_e32 v124, v0
	v_mov_b32_e32 v125, v0
	v_mov_b32_e32 v126, v0
	v_mov_b32_e32 v127, v0
	s_cmp_eq_u64 s[16:17], 0
	s_cbranch_scc0 .Lprio_skip_0
	s_setprio 1
.Lprio_skip_0:
.LBB0_158:
	ds_read_b128 v[158:161], v155
	ds_read_b128 v[162:165], v155 offset:1024
	ds_read_b128 v[166:169], v155 offset:2048
	ds_read_b128 v[170:173], v155 offset:3072
	ds_read_b128 v[174:177], v156
	ds_read_b128 v[178:181], v156 offset:1024
	ds_read_b128 v[182:185], v156 offset:2048
	ds_read_b128 v[186:189], v156 offset:3072
	s_add_u32 s26, s24, 0xfff80080
	s_addc_u32 s27, s25, -1
	s_cmp_eq_u32 s61, 28
	s_cselect_b32 s37, s21, s27
	s_cselect_b32 s36, s20, s26
	s_cselect_b32 s27, s23, s60
	s_cselect_b32 s26, s22, s59
	v_lshl_add_u64 v[222:223], s[24:25], 0, v[138:139]
	s_add_i32 m0, s39, 0xc000
	ds_read_b128 v[190:193], v157
	ds_read_b128 v[194:197], v157 offset:1024
	ds_read_b128 v[198:201], v157 offset:2048
	ds_read_b128 v[202:205], v157 offset:3072
	ds_read_b128 v[206:209], v157 offset:4096
	ds_read_b128 v[210:213], v157 offset:5120
	ds_read_b128 v[214:217], v157 offset:6144
	ds_read_b128 v[218:221], v157 offset:7168
	global_load_lds_dwordx4 v[222:223], off
	v_lshl_add_u64 v[222:223], s[24:25], 0, v[140:141]
	s_add_i32 m0, s39, 0xe000
	s_nop 0
	global_load_lds_dwordx4 v[222:223], off
	s_waitcnt vmcnt(8)
	s_waitcnt lgkmcnt(0)
	s_barrier
	s_waitcnt lgkmcnt(0)
	v_mfma_f32_16x16x32_bf16 v[124:127], v[158:161], v[190:193], v[124:127]
	v_mfma_f32_16x16x32_bf16 v[120:123], v[166:169], v[190:193], v[120:123]
	v_mfma_f32_16x16x32_bf16 v[108:111], v[158:161], v[198:201], v[108:111]
	v_mfma_f32_16x16x32_bf16 v[104:107], v[166:169], v[198:201], v[104:107]
	v_mfma_f32_16x16x32_bf16 v[92:95], v[158:161], v[206:209], v[92:95]
	v_mfma_f32_16x16x32_bf16 v[88:91], v[166:169], v[206:209], v[88:91]
	v_mfma_f32_16x16x32_bf16 v[76:79], v[158:161], v[214:217], v[76:79]
	v_mfma_f32_16x16x32_bf16 v[72:75], v[166:169], v[214:217], v[72:75]
	v_mfma_f32_16x16x32_bf16 v[124:127], v[162:165], v[194:197], v[124:127]
	v_mfma_f32_16x16x32_bf16 v[120:123], v[170:173], v[194:197], v[120:123]
	v_mfma_f32_16x16x32_bf16 v[108:111], v[162:165], v[202:205], v[108:111]
	v_mfma_f32_16x16x32_bf16 v[104:107], v[170:173], v[202:205], v[104:107]
	v_mfma_f32_16x16x32_bf16 v[92:95], v[162:165], v[210:213], v[92:95]
	v_mfma_f32_16x16x32_bf16 v[88:91], v[170:173], v[210:213], v[88:91]
	v_mfma_f32_16x16x32_bf16 v[76:79], v[162:165], v[218:221], v[76:79]
	v_mfma_f32_16x16x32_bf16 v[72:75], v[170:173], v[218:221], v[72:75]
	v_mfma_f32_16x16x32_bf16 v[116:119], v[174:177], v[190:193], v[116:119]
	v_mfma_f32_16x16x32_bf16 v[112:115], v[182:185], v[190:193], v[112:115]
	v_mfma_f32_16x16x32_bf16 v[100:103], v[174:177], v[198:201], v[100:103]
	v_mfma_f32_16x16x32_bf16 v[96:99], v[182:185], v[198:201], v[96:99]
	v_mfma_f32_16x16x32_bf16 v[84:87], v[174:177], v[206:209], v[84:87]
	v_mfma_f32_16x16x32_bf16 v[80:83], v[182:185], v[206:209], v[80:83]
	v_mfma_f32_16x16x32_bf16 v[68:71], v[174:177], v[214:217], v[68:71]
	v_mfma_f32_16x16x32_bf16 v[64:67], v[182:185], v[214:217], v[64:67]
	v_mfma_f32_16x16x32_bf16 v[116:119], v[178:181], v[194:197], v[116:119]
	v_mfma_f32_16x16x32_bf16 v[112:115], v[186:189], v[194:197], v[112:115]
	v_mfma_f32_16x16x32_bf16 v[100:103], v[178:181], v[202:205], v[100:103]
	v_mfma_f32_16x16x32_bf16 v[96:99], v[186:189], v[202:205], v[96:99]
	v_mfma_f32_16x16x32_bf16 v[84:87], v[178:181], v[210:213], v[84:87]
	v_mfma_f32_16x16x32_bf16 v[80:83], v[186:189], v[210:213], v[80:83]
	v_mfma_f32_16x16x32_bf16 v[68:71], v[178:181], v[218:221], v[68:71]
	v_mfma_f32_16x16x32_bf16 v[64:67], v[186:189], v[218:221], v[64:67]
	s_barrier
	s_add_i32 s62, s47, s38
	v_lshl_add_u64 v[222:223], s[26:27], 0, v[130:131]
	s_mov_b32 m0, s62
	ds_read_b128 v[190:193], v157 offset:16384
	ds_read_b128 v[194:197], v157 offset:17408
	ds_read_b128 v[198:201], v157 offset:18432
	ds_read_b128 v[202:205], v157 offset:19456
	ds_read_b128 v[206:209], v157 offset:20480
	ds_read_b128 v[210:213], v157 offset:21504
	ds_read_b128 v[214:217], v157 offset:22528
	ds_read_b128 v[218:221], v157 offset:23552
	global_load_lds_dwordx4 v[222:223], off
	s_add_i32 m0, s62, 0x2000
	s_add_u32 s62, s26, 0x80000
	v_lshl_add_u64 v[224:225], s[26:27], 0, v[134:135]
	s_addc_u32 s63, s27, 0
	s_add_i32 s64, s54, s38
	global_load_lds_dwordx4 v[224:225], off
	v_lshl_add_u64 v[226:227], s[62:63], 0, v[130:131]
	s_mov_b32 m0, s64
	v_lshl_add_u64 v[228:229], s[36:37], 0, v[132:133]
	global_load_lds_dwordx4 v[226:227], off
	v_lshl_add_u64 v[226:227], s[62:63], 0, v[134:135]
	s_add_i32 m0, s64, 0x2000
	s_nop 0
	global_load_lds_dwordx4 v[226:227], off
	v_lshl_add_u64 v[226:227], s[36:37], 0, v[128:129]
	s_mov_b32 m0, s39
	s_nop 0
	global_load_lds_dwordx4 v[226:227], off
	s_mov_b32 m0, s40
	s_nop 0
	global_load_lds_dwordx4 v[228:229], off
	s_waitcnt vmcnt(8)
	s_waitcnt lgkmcnt(0)
	s_barrier
	s_waitcnt lgkmcnt(0)
	v_mfma_f32_16x16x32_bf16 v[60:63], v[158:161], v[190:193], v[60:63]
	v_mfma_f32_16x16x32_bf16 v[56:59], v[166:169], v[190:193], v[56:59]
	v_mfma_f32_16x16x32_bf16 v[44:47], v[158:161], v[198:201], v[44:47]
	v_mfma_f32_16x16x32_bf16 v[40:43], v[166:169], v[198:201], v[40:43]
	v_mfma_f32_16x16x32_bf16 v[28:31], v[158:161], v[206:209], v[28:31]
	v_mfma_f32_16x16x32_bf16 v[24:27], v[166:169], v[206:209], v[24:27]
	v_mfma_f32_16x16x32_bf16 v[12:15], v[158:161], v[214:217], v[12:15]
	v_mfma_f32_16x16x32_bf16 v[8:11], v[166:169], v[214:217], v[8:11]
	v_mfma_f32_16x16x32_bf16 v[60:63], v[162:165], v[194:197], v[60:63]
	v_mfma_f32_16x16x32_bf16 v[56:59], v[170:173], v[194:197], v[56:59]
	v_mfma_f32_16x16x32_bf16 v[44:47], v[162:165], v[202:205], v[44:47]
	v_mfma_f32_16x16x32_bf16 v[40:43], v[170:173], v[202:205], v[40:43]
	v_mfma_f32_16x16x32_bf16 v[28:31], v[162:165], v[210:213], v[28:31]
	v_mfma_f32_16x16x32_bf16 v[24:27], v[170:173], v[210:213], v[24:27]
	v_mfma_f32_16x16x32_bf16 v[12:15], v[162:165], v[218:221], v[12:15]
	v_mfma_f32_16x16x32_bf16 v[8:11], v[170:173], v[218:221], v[8:11]
	v_mfma_f32_16x16x32_bf16 v[52:55], v[174:177], v[190:193], v[52:55]
	v_mfma_f32_16x16x32_bf16 v[48:51], v[182:185], v[190:193], v[48:51]
	v_mfma_f32_16x16x32_bf16 v[36:39], v[174:177], v[198:201], v[36:39]
	v_mfma_f32_16x16x32_bf16 v[32:35], v[182:185], v[198:201], v[32:35]
	v_mfma_f32_16x16x32_bf16 v[20:23], v[174:177], v[206:209], v[20:23]
	v_mfma_f32_16x16x32_bf16 v[16:19], v[182:185], v[206:209], v[16:19]
	v_mfma_f32_16x16x32_bf16 v[4:7], v[174:177], v[214:217], v[4:7]
	v_mfma_f32_16x16x32_bf16 v[0:3], v[182:185], v[214:217], v[0:3]
	v_mfma_f32_16x16x32_bf16 v[52:55], v[178:181], v[194:197], v[52:55]
	v_mfma_f32_16x16x32_bf16 v[48:51], v[186:189], v[194:197], v[48:51]
	v_mfma_f32_16x16x32_bf16 v[36:39], v[178:181], v[202:205], v[36:39]
	v_mfma_f32_16x16x32_bf16 v[32:35], v[186:189], v[202:205], v[32:35]
	v_mfma_f32_16x16x32_bf16 v[20:23], v[178:181], v[210:213], v[20:23]
	v_mfma_f32_16x16x32_bf16 v[16:19], v[186:189], v[210:213], v[16:19]
	v_mfma_f32_16x16x32_bf16 v[4:7], v[178:181], v[218:221], v[4:7]
	v_mfma_f32_16x16x32_bf16 v[0:3], v[186:189], v[218:221], v[0:3]
	s_barrier
	s_add_i32 s62, 0, 0x18000
	s_add_i32 s63, 0, 0x1c000
	v_add_u32_e32 v170, s62, v154
	v_add_u32_e32 v186, s63, v154
	ds_read_b128 v[158:161], v170
	ds_read_b128 v[162:165], v170 offset:1024
	ds_read_b128 v[166:169], v170 offset:2048
	ds_read_b128 v[170:173], v170 offset:3072
	ds_read_b128 v[174:177], v186
	ds_read_b128 v[178:181], v186 offset:1024
	ds_read_b128 v[182:185], v186 offset:2048
	ds_read_b128 v[186:189], v186 offset:3072
	s_add_u32 s36, s36, 0x80000
	s_addc_u32 s37, s37, 0
	s_mov_b32 m0, s41
	v_lshl_add_u64 v[232:233], s[36:37], 0, v[128:129]
	ds_read_b128 v[190:193], v157 offset:32768
	ds_read_b128 v[194:197], v157 offset:33792
	ds_read_b128 v[198:201], v157 offset:34816
	ds_read_b128 v[202:205], v157 offset:35840
	ds_read_b128 v[206:209], v157 offset:36864
	ds_read_b128 v[210:213], v157 offset:37888
	ds_read_b128 v[214:217], v157 offset:38912
	ds_read_b128 v[218:221], v157 offset:39936
	global_load_lds_dwordx4 v[232:233], off
	v_lshl_add_u64 v[232:233], s[36:37], 0, v[132:133]
	s_mov_b32 m0, s42
	s_nop 0
	global_load_lds_dwordx4 v[232:233], off
	s_waitcnt vmcnt(8)
	s_waitcnt lgkmcnt(0)
	s_barrier
	s_waitcnt lgkmcnt(0)
	v_mfma_f32_16x16x32_bf16 v[124:127], v[158:161], v[190:193], v[124:127]
	v_mfma_f32_16x16x32_bf16 v[120:123], v[166:169], v[190:193], v[120:123]
	v_mfma_f32_16x16x32_bf16 v[108:111], v[158:161], v[198:201], v[108:111]
	v_mfma_f32_16x16x32_bf16 v[104:107], v[166:169], v[198:201], v[104:107]
	v_mfma_f32_16x16x32_bf16 v[92:95], v[158:161], v[206:209], v[92:95]
	v_mfma_f32_16x16x32_bf16 v[88:91], v[166:169], v[206:209], v[88:91]
	v_mfma_f32_16x16x32_bf16 v[76:79], v[158:161], v[214:217], v[76:79]
	v_mfma_f32_16x16x32_bf16 v[72:75], v[166:169], v[214:217], v[72:75]
	v_mfma_f32_16x16x32_bf16 v[124:127], v[162:165], v[194:197], v[124:127]
	v_mfma_f32_16x16x32_bf16 v[120:123], v[170:173], v[194:197], v[120:123]
	v_mfma_f32_16x16x32_bf16 v[108:111], v[162:165], v[202:205], v[108:111]
	v_mfma_f32_16x16x32_bf16 v[104:107], v[170:173], v[202:205], v[104:107]
	v_mfma_f32_16x16x32_bf16 v[92:95], v[162:165], v[210:213], v[92:95]
	v_mfma_f32_16x16x32_bf16 v[88:91], v[170:173], v[210:213], v[88:91]
	v_mfma_f32_16x16x32_bf16 v[76:79], v[162:165], v[218:221], v[76:79]
	v_mfma_f32_16x16x32_bf16 v[72:75], v[170:173], v[218:221], v[72:75]
	v_mfma_f32_16x16x32_bf16 v[116:119], v[174:177], v[190:193], v[116:119]
	v_mfma_f32_16x16x32_bf16 v[112:115], v[182:185], v[190:193], v[112:115]
	v_mfma_f32_16x16x32_bf16 v[100:103], v[174:177], v[198:201], v[100:103]
	v_mfma_f32_16x16x32_bf16 v[96:99], v[182:185], v[198:201], v[96:99]
	v_mfma_f32_16x16x32_bf16 v[84:87], v[174:177], v[206:209], v[84:87]
	v_mfma_f32_16x16x32_bf16 v[80:83], v[182:185], v[206:209], v[80:83]
	v_mfma_f32_16x16x32_bf16 v[68:71], v[174:177], v[214:217], v[68:71]
	v_mfma_f32_16x16x32_bf16 v[64:67], v[182:185], v[214:217], v[64:67]
	v_mfma_f32_16x16x32_bf16 v[116:119], v[178:181], v[194:197], v[116:119]
	v_mfma_f32_16x16x32_bf16 v[112:115], v[186:189], v[194:197], v[112:115]
	v_mfma_f32_16x16x32_bf16 v[100:103], v[178:181], v[202:205], v[100:103]
	v_mfma_f32_16x16x32_bf16 v[96:99], v[186:189], v[202:205], v[96:99]
	v_mfma_f32_16x16x32_bf16 v[84:87], v[178:181], v[210:213], v[84:87]
	v_mfma_f32_16x16x32_bf16 v[80:83], v[186:189], v[210:213], v[80:83]
	v_mfma_f32_16x16x32_bf16 v[68:71], v[178:181], v[218:221], v[68:71]
	v_mfma_f32_16x16x32_bf16 v[64:67], v[186:189], v[218:221], v[64:67]
	s_barrier
	s_add_i32 s36, s62, s38
	v_lshl_add_u64 v[222:223], v[222:223], 0, s[14:15]
	s_mov_b32 m0, s36
	ds_read_b128 v[190:193], v157 offset:49152
	ds_read_b128 v[194:197], v157 offset:50176
	ds_read_b128 v[198:201], v157 offset:51200
	ds_read_b128 v[202:205], v157 offset:52224
	ds_read_b128 v[206:209], v157 offset:53248
	ds_read_b128 v[210:213], v157 offset:54272
	ds_read_b128 v[214:217], v157 offset:55296
	ds_read_b128 v[218:221], v157 offset:56320
	global_load_lds_dwordx4 v[222:223], off
	s_add_i32 m0, s36, 0x2000
	s_add_u32 s26, s26, 0x80080
	v_lshl_add_u64 v[222:223], v[224:225], 0, s[14:15]
	s_addc_u32 s27, s27, 0
	s_add_i32 s36, s63, s38
	global_load_lds_dwordx4 v[222:223], off
	v_lshl_add_u64 v[222:223], s[26:27], 0, v[130:131]
	s_mov_b32 m0, s36
	s_nop 0
	global_load_lds_dwordx4 v[222:223], off
	v_lshl_add_u64 v[222:223], s[26:27], 0, v[134:135]
	s_add_i32 m0, s36, 0x2000
	s_nop 0
	global_load_lds_dwordx4 v[222:223], off
	v_lshl_add_u64 v[222:223], v[226:227], 0, s[14:15]
	s_mov_b32 m0, s45
	s_nop 0
	global_load_lds_dwordx4 v[222:223], off
	v_lshl_add_u64 v[222:223], v[228:229], 0, s[14:15]
	s_mov_b32 m0, s46
	s_nop 0
	global_load_lds_dwordx4 v[222:223], off
	s_waitcnt vmcnt(8)
	s_waitcnt lgkmcnt(0)
	s_barrier
	s_waitcnt lgkmcnt(0)
	v_mfma_f32_16x16x32_bf16 v[60:63], v[158:161], v[190:193], v[60:63]
	v_mfma_f32_16x16x32_bf16 v[56:59], v[166:169], v[190:193], v[56:59]
	v_mfma_f32_16x16x32_bf16 v[44:47], v[158:161], v[198:201], v[44:47]
	v_mfma_f32_16x16x32_bf16 v[40:43], v[166:169], v[198:201], v[40:43]
	v_mfma_f32_16x16x32_bf16 v[28:31], v[158:161], v[206:209], v[28:31]
	v_mfma_f32_16x16x32_bf16 v[24:27], v[166:169], v[206:209], v[24:27]
	v_mfma_f32_16x16x32_bf16 v[12:15], v[158:161], v[214:217], v[12:15]
	v_mfma_f32_16x16x32_bf16 v[8:11], v[166:169], v[214:217], v[8:11]
	v_mfma_f32_16x16x32_bf16 v[60:63], v[162:165], v[194:197], v[60:63]
	v_mfma_f32_16x16x32_bf16 v[56:59], v[170:173], v[194:197], v[56:59]
	v_mfma_f32_16x16x32_bf16 v[44:47], v[162:165], v[202:205], v[44:47]
	v_mfma_f32_16x16x32_bf16 v[40:43], v[170:173], v[202:205], v[40:43]
	v_mfma_f32_16x16x32_bf16 v[28:31], v[162:165], v[210:213], v[28:31]
	v_mfma_f32_16x16x32_bf16 v[24:27], v[170:173], v[210:213], v[24:27]
	v_mfma_f32_16x16x32_bf16 v[12:15], v[162:165], v[218:221], v[12:15]
	v_mfma_f32_16x16x32_bf16 v[8:11], v[170:173], v[218:221], v[8:11]
	v_mfma_f32_16x16x32_bf16 v[52:55], v[174:177], v[190:193], v[52:55]
	v_mfma_f32_16x16x32_bf16 v[48:51], v[182:185], v[190:193], v[48:51]
	v_mfma_f32_16x16x32_bf16 v[36:39], v[174:177], v[198:201], v[36:39]
	v_mfma_f32_16x16x32_bf16 v[32:35], v[182:185], v[198:201], v[32:35]
	v_mfma_f32_16x16x32_bf16 v[20:23], v[174:177], v[206:209], v[20:23]
	v_mfma_f32_16x16x32_bf16 v[16:19], v[182:185], v[206:209], v[16:19]
	v_mfma_f32_16x16x32_bf16 v[4:7], v[174:177], v[214:217], v[4:7]
	v_mfma_f32_16x16x32_bf16 v[0:3], v[182:185], v[214:217], v[0:3]
	v_mfma_f32_16x16x32_bf16 v[52:55], v[178:181], v[194:197], v[52:55]
	v_mfma_f32_16x16x32_bf16 v[48:51], v[186:189], v[194:197], v[48:51]
	v_mfma_f32_16x16x32_bf16 v[36:39], v[178:181], v[202:205], v[36:39]
	v_mfma_f32_16x16x32_bf16 v[32:35], v[186:189], v[202:205], v[32:35]
	v_mfma_f32_16x16x32_bf16 v[20:23], v[178:181], v[210:213], v[20:23]
	v_mfma_f32_16x16x32_bf16 v[16:19], v[186:189], v[210:213], v[16:19]
	v_mfma_f32_16x16x32_bf16 v[4:7], v[178:181], v[218:221], v[4:7]
	v_mfma_f32_16x16x32_bf16 v[0:3], v[186:189], v[218:221], v[0:3]
	s_barrier
	s_add_i32 s61, s61, 2
	s_add_u32 s24, s24, 0x100
	s_addc_u32 s25, s25, 0
	s_add_u32 s59, s59, 0x100
	s_addc_u32 s60, s60, 0
	s_cmp_gt_u32 s61, 29
	s_cbranch_scc0 .LBB0_158
	s_and_b64 vcc, exec, s[16:17]
	s_cbranch_vccz .LBB0_161
	s_barrier
.LBB0_161:
	s_setprio 0
	v_add_u32_e32 v158, s58, v153
	s_lshl_b32 s24, s12, 7
	s_ashr_i32 s25, s24, 31
	v_cmp_gt_i32_e32 vcc, s55, v158
	s_and_saveexec_b64 s[26:27], vcc
	s_cbranch_execz .LBB0_163
	v_mul_f32_e32 v159, 0xbfb8aa3b, v124
	v_exp_f32_e32 v159, v159
	v_mul_f32_e32 v160, 0xbfb8aa3b, v125
	v_exp_f32_e32 v160, v160
	v_mul_f32_e32 v161, 0xbfb8aa3b, v126
	v_add_f32_e32 v159, 1.0, v159
	v_rcp_f32_e32 v159, v159
	v_add_f32_e32 v160, 1.0, v160
	v_rcp_f32_e32 v160, v160
	s_lshl_b32 s12, s44, 1
	v_mul_f32_e32 v124, v124, v159
	v_mul_f32_e32 v116, v124, v116
	v_exp_f32_e32 v124, v161
	v_mul_f32_e32 v159, 0xbfb8aa3b, v127
	v_exp_f32_e32 v159, v159
	v_mul_f32_e32 v125, v125, v160
	v_add_f32_e32 v124, 1.0, v124
	v_mul_f32_e32 v117, v125, v117
	v_rcp_f32_e32 v124, v124
	v_add_f32_e32 v125, 1.0, v159
	v_mul_f32_e32 v159, 0xbfb8aa3b, v120
	v_rcp_f32_e32 v125, v125
	v_exp_f32_e32 v159, v159
	v_mul_f32_e32 v124, v126, v124
	v_mul_f32_e32 v118, v124, v118
	v_mul_f32_e32 v124, v127, v125
	v_add_f32_e32 v125, 1.0, v159
	v_rcp_f32_e32 v125, v125
	v_mul_f32_e32 v126, 0xbfb8aa3b, v121
	v_exp_f32_e32 v126, v126
	v_mul_f32_e32 v119, v124, v119
	v_mul_f32_e32 v120, v120, v125
	v_mul_f32_e32 v120, v120, v112
	v_add_f32_e32 v112, 1.0, v126
	v_mul_f32_e32 v124, 0xbfb8aa3b, v122
	v_rcp_f32_e32 v112, v112
	v_exp_f32_e32 v124, v124
	v_mul_f32_e32 v125, 0xbfb8aa3b, v123
	v_exp_f32_e32 v125, v125
	v_mul_f32_e32 v112, v121, v112
	v_add_f32_e32 v121, 1.0, v124
	v_rcp_f32_e32 v121, v121
	v_add_f32_e32 v124, 1.0, v125
	v_rcp_f32_e32 v124, v124
	v_mul_f32_e32 v125, v112, v113
	v_mul_f32_e32 v112, v122, v121
	v_mul_f32_e32 v121, v112, v114
	v_mul_f32_e32 v112, v123, v124
	v_mul_f32_e32 v115, v112, v115
	v_cvt_pk_bf16_f32 v112, v116, v117
	v_mov_b64_e32 v[116:117], s[52:53]
	v_mad_i64_i32 v[116:117], s[36:37], v158, s56, v[116:117]
	v_lshl_add_u64 v[116:117], s[24:25], 1, v[116:117]
	v_lshl_add_u64 v[116:117], v[116:117], 0, s[12:13]
	v_lshl_add_u64 v[116:117], v[116:117], 0, v[136:137]
	v_cvt_pk_bf16_f32 v113, v118, v119
	v_cvt_pk_bf16_f32 v114, v120, v125
	v_cvt_pk_bf16_f32 v115, v121, v115
	global_store_dwordx4 v[116:117], v[112:115], off

.LBB0_195:
	s_add_u32 s6, s6, 0x80080
	s_addc_u32 s7, s7, 0
	s_add_u32 s70, s40, 0x100
	v_mov_b32_e32 v0, 0
	s_addc_u32 s71, s41, 0
	s_mov_b32 s72, -2
	v_mov_b32_e32 v1, v0
	v_mov_b32_e32 v2, v0
	v_mov_b32_e32 v3, v0
	v_mov_b32_e32 v4, v0
	v_mov_b32_e32 v5, v0
	v_mov_b32_e32 v6, v0
	v_mov_b32_e32 v7, v0
	v_mov_b32_e32 v16, v0
	v_mov_b32_e32 v17, v0
	v_mov_b32_e32 v18, v0
	v_mov_b32_e32 v19, v0
	v_mov_b32_e32 v20, v0
	v_mov_b32_e32 v21, v0
	v_mov_b32_e32 v22, v0
	v_mov_b32_e32 v23, v0
	v_mov_b32_e32 v32, v0
	v_mov_b32_e32 v33, v0
	v_mov_b32_e32 v34, v0
	v_mov_b32_e32 v35, v0
	v_mov_b32_e32 v36, v0
	v_mov_b32_e32 v37, v0
	v_mov_b32_e32 v38, v0
	v_mov_b32_e32 v39, v0
	v_mov_b32_e32 v48, v0
	v_mov_b32_e32 v49, v0
	v_mov_b32_e32 v50, v0
	v_mov_b32_e32 v51, v0
	v_mov_b32_e32 v52, v0
	v_mov_b32_e32 v53, v0
	v_mov_b32_e32 v54, v0
	v_mov_b32_e32 v55, v0
	v_mov_b32_e32 v8, v0
	v_mov_b32_e32 v9, v0
	v_mov_b32_e32 v10, v0
	v_mov_b32_e32 v11, v0
	v_mov_b32_e32 v12, v0
	v_mov_b32_e32 v13, v0
	v_mov_b32_e32 v14, v0
	v_mov_b32_e32 v15, v0
	v_mov_b32_e32 v24, v0
	v_mov_b32_e32 v25, v0
	v_mov_b32_e32 v26, v0
	v_mov_b32_e32 v27, v0
	v_mov_b32_e32 v28, v0
	v_mov_b32_e32 v29, v0
	v_mov_b32_e32 v30, v0
	v_mov_b32_e32 v31, v0
	v_mov_b32_e32 v40, v0
	v_mov_b32_e32 v41, v0
	v_mov_b32_e32 v42, v0
	v_mov_b32_e32 v43, v0
	v_mov_b32_e32 v44, v0
	v_mov_b32_e32 v45, v0
	v_mov_b32_e32 v46, v0
	v_mov_b32_e32 v47, v0
	v_mov_b32_e32 v56, v0
	v_mov_b32_e32 v57, v0
	v_mov_b32_e32 v58, v0
	v_mov_b32_e32 v59, v0
	v_mov_b32_e32 v60, v0
	v_mov_b32_e32 v61, v0
	v_mov_b32_e32 v62, v0
	v_mov_b32_e32 v63, v0
	v_mov_b32_e32 v64, v0
	v_mov_b32_e32 v65, v0
	v_mov_b32_e32 v66, v0
	v_mov_b32_e32 v67, v0
	v_mov_b32_e32 v68, v0
	v_mov_b32_e32 v69, v0
	v_mov_b32_e32 v70, v0
	v_mov_b32_e32 v71, v0
	v_mov_b32_e32 v80, v0
	v_mov_b32_e32 v81, v0
	v_mov_b32_e32 v82, v0
	v_mov_b32_e32 v83, v0
	v_mov_b32_e32 v84, v0
	v_mov_b32_e32 v85, v0
	v_mov_b32_e32 v86, v0
	v_mov_b32_e32 v87, v0
	v_mov_b32_e32 v96, v0
	v_mov_b32_e32 v97, v0
	v_mov_b32_e32 v98, v0
	v_mov_b32_e32 v99, v0
	v_mov_b32_e32 v100, v0
	v_mov_b32_e32 v101, v0
	v_mov_b32_e32 v102, v0
	v_mov_b32_e32 v103, v0
	v_mov_b32_e32 v112, v0
	v_mov_b32_e32 v113, v0
	v_mov_b32_e32 v114, v0
	v_mov_b32_e32 v115, v0
	v_mov_b32_e32 v116, v0
	v_mov_b32_e32 v117, v0
	v_mov_b32_e32 v118, v0
	v_mov_b32_e32 v119, v0
	v_mov_b32_e32 v72, v0
	v_mov_b32_e32 v73, v0
	v_mov_b32_e32 v74, v0
	v_mov_b32_e32 v75, v0
	v_mov_b32_e32 v76, v0
	v_mov_b32_e32 v77, v0
	v_mov_b32_e32 v78, v0
	v_mov_b32_e32 v79, v0
	v_mov_b32_e32 v88, v0
	v_mov_b32_e32 v89, v0
	v_mov_b32_e32 v90, v0
	v_mov_b32_e32 v91, v0
	v_mov_b32_e32 v92, v0
	v_mov_b32_e32 v93, v0
	v_mov_b32_e32 v94, v0
	v_mov_b32_e32 v95, v0
	v_mov_b32_e32 v104, v0
	v_mov_b32_e32 v105, v0
	v_mov_b32_e32 v106, v0
	v_mov_b32_e32 v107, v0
	v_mov_b32_e32 v108, v0
	v_mov_b32_e32 v109, v0
	v_mov_b32_e32 v110, v0
	v_mov_b32_e32 v111, v0
	v_mov_b32_e32 v120, v0
	v_mov_b32_e32 v121, v0
	v_mov_b32_e32 v122, v0
	v_mov_b32_e32 v123, v0
	v_mov_b32_e32 v124, v0
	v_mov_b32_e32 v125, v0
	v_mov_b32_e32 v126, v0
	v_mov_b32_e32 v127, v0
	s_cmp_eq_u64 s[22:23], 0
	s_cbranch_scc0 .Lprio_skip_1
	s_setprio 1
.Lprio_skip_1:
.LBB0_196:
	ds_read_b128 v[142:145], v165
	ds_read_b128 v[146:149], v165 offset:1024
	ds_read_b128 v[150:153], v165 offset:2048
	ds_read_b128 v[170:173], v165 offset:3072
	ds_read_b128 v[174:177], v166
	ds_read_b128 v[178:181], v166 offset:1024
	ds_read_b128 v[182:185], v166 offset:2048
	ds_read_b128 v[186:189], v166 offset:3072
	s_add_u32 s40, s6, 0xfff80080
	s_addc_u32 s41, s7, -1
	s_cmp_eq_u32 s72, 28
	s_cselect_b32 s43, s37, s41
	s_cselect_b32 s42, s36, s40
	s_cselect_b32 s41, s39, s71
	s_cselect_b32 s40, s38, s70
	v_lshl_add_u64 v[222:223], s[6:7], 0, v[136:137]
	s_add_i32 m0, s56, 0xc000
	ds_read_b128 v[190:193], v167
	ds_read_b128 v[194:197], v167 offset:1024
	ds_read_b128 v[198:201], v167 offset:2048
	ds_read_b128 v[202:205], v167 offset:3072
	ds_read_b128 v[206:209], v167 offset:4096
	ds_read_b128 v[210:213], v167 offset:5120
	ds_read_b128 v[214:217], v167 offset:6144
	ds_read_b128 v[218:221], v167 offset:7168
	global_load_lds_dwordx4 v[222:223], off
	v_lshl_add_u64 v[222:223], s[6:7], 0, v[140:141]
	s_add_i32 m0, s56, 0xe000
	s_nop 0
	global_load_lds_dwordx4 v[222:223], off
	s_waitcnt vmcnt(8)
	s_waitcnt lgkmcnt(0)
	s_barrier
	s_waitcnt lgkmcnt(0)
	v_mfma_f32_16x16x32_bf16 v[124:127], v[142:145], v[190:193], v[124:127]
	v_mfma_f32_16x16x32_bf16 v[120:123], v[150:153], v[190:193], v[120:123]
	v_mfma_f32_16x16x32_bf16 v[108:111], v[142:145], v[198:201], v[108:111]
	v_mfma_f32_16x16x32_bf16 v[104:107], v[150:153], v[198:201], v[104:107]
	v_mfma_f32_16x16x32_bf16 v[92:95], v[142:145], v[206:209], v[92:95]
	v_mfma_f32_16x16x32_bf16 v[88:91], v[150:153], v[206:209], v[88:91]
	v_mfma_f32_16x16x32_bf16 v[76:79], v[142:145], v[214:217], v[76:79]
	v_mfma_f32_16x16x32_bf16 v[72:75], v[150:153], v[214:217], v[72:75]
	v_mfma_f32_16x16x32_bf16 v[124:127], v[146:149], v[194:197], v[124:127]
	v_mfma_f32_16x16x32_bf16 v[120:123], v[170:173], v[194:197], v[120:123]
	v_mfma_f32_16x16x32_bf16 v[108:111], v[146:149], v[202:205], v[108:111]
	v_mfma_f32_16x16x32_bf16 v[104:107], v[170:173], v[202:205], v[104:107]
	v_mfma_f32_16x16x32_bf16 v[92:95], v[146:149], v[210:213], v[92:95]
	v_mfma_f32_16x16x32_bf16 v[88:91], v[170:173], v[210:213], v[88:91]
	v_mfma_f32_16x16x32_bf16 v[76:79], v[146:149], v[218:221], v[76:79]
	v_mfma_f32_16x16x32_bf16 v[72:75], v[170:173], v[218:221], v[72:75]
	v_mfma_f32_16x16x32_bf16 v[116:119], v[174:177], v[190:193], v[116:119]
	v_mfma_f32_16x16x32_bf16 v[112:115], v[182:185], v[190:193], v[112:115]
	v_mfma_f32_16x16x32_bf16 v[100:103], v[174:177], v[198:201], v[100:103]
	v_mfma_f32_16x16x32_bf16 v[96:99], v[182:185], v[198:201], v[96:99]
	v_mfma_f32_16x16x32_bf16 v[84:87], v[174:177], v[206:209], v[84:87]
	v_mfma_f32_16x16x32_bf16 v[80:83], v[182:185], v[206:209], v[80:83]
	v_mfma_f32_16x16x32_bf16 v[68:71], v[174:177], v[214:217], v[68:71]
	v_mfma_f32_16x16x32_bf16 v[64:67], v[182:185], v[214:217], v[64:67]
	v_mfma_f32_16x16x32_bf16 v[116:119], v[178:181], v[194:197], v[116:119]
	v_mfma_f32_16x16x32_bf16 v[112:115], v[186:189], v[194:197], v[112:115]
	v_mfma_f32_16x16x32_bf16 v[100:103], v[178:181], v[202:205], v[100:103]
	v_mfma_f32_16x16x32_bf16 v[96:99], v[186:189], v[202:205], v[96:99]
	v_mfma_f32_16x16x32_bf16 v[84:87], v[178:181], v[210:213], v[84:87]
	v_mfma_f32_16x16x32_bf16 v[80:83], v[186:189], v[210:213], v[80:83]
	v_mfma_f32_16x16x32_bf16 v[68:71], v[178:181], v[218:221], v[68:71]
	v_mfma_f32_16x16x32_bf16 v[64:67], v[186:189], v[218:221], v[64:67]
	s_barrier
	s_add_i32 s73, s64, s55
	v_lshl_add_u64 v[222:223], s[40:41], 0, v[130:131]
	s_mov_b32 m0, s73
	ds_read_b128 v[190:193], v167 offset:16384
	ds_read_b128 v[194:197], v167 offset:17408
	ds_read_b128 v[198:201], v167 offset:18432
	ds_read_b128 v[202:205], v167 offset:19456
	ds_read_b128 v[206:209], v167 offset:20480
	ds_read_b128 v[210:213], v167 offset:21504
	ds_read_b128 v[214:217], v167 offset:22528
	ds_read_b128 v[218:221], v167 offset:23552
	global_load_lds_dwordx4 v[222:223], off
	s_add_i32 m0, s73, 0x2000
	s_add_u32 s74, s40, 0x80000
	v_lshl_add_u64 v[224:225], s[40:41], 0, v[134:135]
	s_addc_u32 s75, s41, 0
	s_add_i32 s73, s65, s55
	global_load_lds_dwordx4 v[224:225], off
	v_lshl_add_u64 v[226:227], s[74:75], 0, v[130:131]
	s_mov_b32 m0, s73
	v_lshl_add_u64 v[228:229], s[42:43], 0, v[132:133]
	global_load_lds_dwordx4 v[226:227], off
	v_lshl_add_u64 v[226:227], s[74:75], 0, v[134:135]
	s_add_i32 m0, s73, 0x2000
	s_nop 0
	global_load_lds_dwordx4 v[226:227], off
	v_lshl_add_u64 v[226:227], s[42:43], 0, v[128:129]
	s_mov_b32 m0, s56
	s_nop 0
	global_load_lds_dwordx4 v[226:227], off
	s_mov_b32 m0, s57
	s_nop 0
	global_load_lds_dwordx4 v[228:229], off
	s_waitcnt vmcnt(8)
	s_waitcnt lgkmcnt(0)
	s_barrier
	s_waitcnt lgkmcnt(0)
	v_mfma_f32_16x16x32_bf16 v[60:63], v[142:145], v[190:193], v[60:63]
	v_mfma_f32_16x16x32_bf16 v[56:59], v[150:153], v[190:193], v[56:59]
	v_mfma_f32_16x16x32_bf16 v[44:47], v[142:145], v[198:201], v[44:47]
	v_mfma_f32_16x16x32_bf16 v[40:43], v[150:153], v[198:201], v[40:43]
	v_mfma_f32_16x16x32_bf16 v[28:31], v[142:145], v[206:209], v[28:31]
	v_mfma_f32_16x16x32_bf16 v[24:27], v[150:153], v[206:209], v[24:27]
	v_mfma_f32_16x16x32_bf16 v[12:15], v[142:145], v[214:217], v[12:15]
	v_mfma_f32_16x16x32_bf16 v[8:11], v[150:153], v[214:217], v[8:11]
	v_mfma_f32_16x16x32_bf16 v[60:63], v[146:149], v[194:197], v[60:63]
	v_mfma_f32_16x16x32_bf16 v[56:59], v[170:173], v[194:197], v[56:59]
	v_mfma_f32_16x16x32_bf16 v[44:47], v[146:149], v[202:205], v[44:47]
	v_mfma_f32_16x16x32_bf16 v[40:43], v[170:173], v[202:205], v[40:43]
	v_mfma_f32_16x16x32_bf16 v[28:31], v[146:149], v[210:213], v[28:31]
	v_mfma_f32_16x16x32_bf16 v[24:27], v[170:173], v[210:213], v[24:27]
	v_mfma_f32_16x16x32_bf16 v[12:15], v[146:149], v[218:221], v[12:15]
	v_mfma_f32_16x16x32_bf16 v[8:11], v[170:173], v[218:221], v[8:11]
	v_mfma_f32_16x16x32_bf16 v[52:55], v[174:177], v[190:193], v[52:55]
	v_mfma_f32_16x16x32_bf16 v[48:51], v[182:185], v[190:193], v[48:51]
	v_mfma_f32_16x16x32_bf16 v[36:39], v[174:177], v[198:201], v[36:39]
	v_mfma_f32_16x16x32_bf16 v[32:35], v[182:185], v[198:201], v[32:35]
	v_mfma_f32_16x16x32_bf16 v[20:23], v[174:177], v[206:209], v[20:23]
	v_mfma_f32_16x16x32_bf16 v[16:19], v[182:185], v[206:209], v[16:19]
	v_mfma_f32_16x16x32_bf16 v[4:7], v[174:177], v[214:217], v[4:7]
	v_mfma_f32_16x16x32_bf16 v[0:3], v[182:185], v[214:217], v[0:3]
	v_mfma_f32_16x16x32_bf16 v[52:55], v[178:181], v[194:197], v[52:55]
	v_mfma_f32_16x16x32_bf16 v[48:51], v[186:189], v[194:197], v[48:51]
	v_mfma_f32_16x16x32_bf16 v[36:39], v[178:181], v[202:205], v[36:39]
	v_mfma_f32_16x16x32_bf16 v[32:35], v[186:189], v[202:205], v[32:35]
	v_mfma_f32_16x16x32_bf16 v[20:23], v[178:181], v[210:213], v[20:23]
	v_mfma_f32_16x16x32_bf16 v[16:19], v[186:189], v[210:213], v[16:19]
	v_mfma_f32_16x16x32_bf16 v[4:7], v[178:181], v[218:221], v[4:7]
	v_mfma_f32_16x16x32_bf16 v[0:3], v[186:189], v[218:221], v[0:3]
	s_barrier
	s_add_i32 s73, 0, 0x18000
	v_add_u32_e32 v138, s73, v155
	s_add_i32 s74, 0, 0x1c000
	ds_read_b128 v[142:145], v138
	ds_read_b128 v[146:149], v138 offset:1024
	ds_read_b128 v[150:153], v138 offset:2048
	ds_read_b128 v[170:173], v138 offset:3072
	v_add_u32_e32 v138, s74, v155
	ds_read_b128 v[174:177], v138
	ds_read_b128 v[178:181], v138 offset:1024
	ds_read_b128 v[182:185], v138 offset:2048
	ds_read_b128 v[186:189], v138 offset:3072
	s_add_u32 s42, s42, 0x80000
	s_addc_u32 s43, s43, 0
	s_mov_b32 m0, s58
	v_lshl_add_u64 v[232:233], s[42:43], 0, v[128:129]
	ds_read_b128 v[190:193], v167 offset:32768
	ds_read_b128 v[194:197], v167 offset:33792
	ds_read_b128 v[198:201], v167 offset:34816
	ds_read_b128 v[202:205], v167 offset:35840
	ds_read_b128 v[206:209], v167 offset:36864
	ds_read_b128 v[210:213], v167 offset:37888
	ds_read_b128 v[214:217], v167 offset:38912
	ds_read_b128 v[218:221], v167 offset:39936
	global_load_lds_dwordx4 v[232:233], off
	v_lshl_add_u64 v[232:233], s[42:43], 0, v[132:133]
	s_mov_b32 m0, s59
	s_nop 0
	global_load_lds_dwordx4 v[232:233], off
	s_waitcnt vmcnt(8)
	s_waitcnt lgkmcnt(0)
	s_barrier
	s_waitcnt lgkmcnt(0)
	v_mfma_f32_16x16x32_bf16 v[124:127], v[142:145], v[190:193], v[124:127]
	v_mfma_f32_16x16x32_bf16 v[120:123], v[150:153], v[190:193], v[120:123]
	v_mfma_f32_16x16x32_bf16 v[108:111], v[142:145], v[198:201], v[108:111]
	v_mfma_f32_16x16x32_bf16 v[104:107], v[150:153], v[198:201], v[104:107]
	v_mfma_f32_16x16x32_bf16 v[92:95], v[142:145], v[206:209], v[92:95]
	v_mfma_f32_16x16x32_bf16 v[88:91], v[150:153], v[206:209], v[88:91]
	v_mfma_f32_16x16x32_bf16 v[76:79], v[142:145], v[214:217], v[76:79]
	v_mfma_f32_16x16x32_bf16 v[72:75], v[150:153], v[214:217], v[72:75]
	v_mfma_f32_16x16x32_bf16 v[124:127], v[146:149], v[194:197], v[124:127]
	v_mfma_f32_16x16x32_bf16 v[120:123], v[170:173], v[194:197], v[120:123]
	v_mfma_f32_16x16x32_bf16 v[108:111], v[146:149], v[202:205], v[108:111]
	v_mfma_f32_16x16x32_bf16 v[104:107], v[170:173], v[202:205], v[104:107]
	v_mfma_f32_16x16x32_bf16 v[92:95], v[146:149], v[210:213], v[92:95]
	v_mfma_f32_16x16x32_bf16 v[88:91], v[170:173], v[210:213], v[88:91]
	v_mfma_f32_16x16x32_bf16 v[76:79], v[146:149], v[218:221], v[76:79]
	v_mfma_f32_16x16x32_bf16 v[72:75], v[170:173], v[218:221], v[72:75]
	v_mfma_f32_16x16x32_bf16 v[116:119], v[174:177], v[190:193], v[116:119]
	v_mfma_f32_16x16x32_bf16 v[112:115], v[182:185], v[190:193], v[112:115]
	v_mfma_f32_16x16x32_bf16 v[100:103], v[174:177], v[198:201], v[100:103]
	v_mfma_f32_16x16x32_bf16 v[96:99], v[182:185], v[198:201], v[96:99]
	v_mfma_f32_16x16x32_bf16 v[84:87], v[174:177], v[206:209], v[84:87]
	v_mfma_f32_16x16x32_bf16 v[80:83], v[182:185], v[206:209], v[80:83]
	v_mfma_f32_16x16x32_bf16 v[68:71], v[174:177], v[214:217], v[68:71]
	v_mfma_f32_16x16x32_bf16 v[64:67], v[182:185], v[214:217], v[64:67]
	v_mfma_f32_16x16x32_bf16 v[116:119], v[178:181], v[194:197], v[116:119]
	v_mfma_f32_16x16x32_bf16 v[112:115], v[186:189], v[194:197], v[112:115]
	v_mfma_f32_16x16x32_bf16 v[100:103], v[178:181], v[202:205], v[100:103]
	v_mfma_f32_16x16x32_bf16 v[96:99], v[186:189], v[202:205], v[96:99]
	v_mfma_f32_16x16x32_bf16 v[84:87], v[178:181], v[210:213], v[84:87]
	v_mfma_f32_16x16x32_bf16 v[80:83], v[186:189], v[210:213], v[80:83]
	v_mfma_f32_16x16x32_bf16 v[68:71], v[178:181], v[218:221], v[68:71]
	v_mfma_f32_16x16x32_bf16 v[64:67], v[186:189], v[218:221], v[64:67]
	s_barrier
	s_add_i32 s42, s73, s55
	v_lshl_add_u64 v[222:223], v[222:223], 0, s[20:21]
	s_mov_b32 m0, s42
	ds_read_b128 v[190:193], v167 offset:49152
	ds_read_b128 v[194:197], v167 offset:50176
	ds_read_b128 v[198:201], v167 offset:51200
	ds_read_b128 v[202:205], v167 offset:52224
	ds_read_b128 v[206:209], v167 offset:53248
	ds_read_b128 v[210:213], v167 offset:54272
	ds_read_b128 v[214:217], v167 offset:55296
	ds_read_b128 v[218:221], v167 offset:56320
	global_load_lds_dwordx4 v[222:223], off
	s_add_i32 m0, s42, 0x2000
	s_add_u32 s40, s40, 0x80080
	v_lshl_add_u64 v[222:223], v[224:225], 0, s[20:21]
	s_addc_u32 s41, s41, 0
	s_add_i32 s42, s74, s55
	global_load_lds_dwordx4 v[222:223], off
	v_lshl_add_u64 v[222:223], s[40:41], 0, v[130:131]
	s_mov_b32 m0, s42
	s_nop 0
	global_load_lds_dwordx4 v[222:223], off
	v_lshl_add_u64 v[222:223], s[40:41], 0, v[134:135]
	s_add_i32 m0, s42, 0x2000
	s_nop 0
	global_load_lds_dwordx4 v[222:223], off
	v_lshl_add_u64 v[222:223], v[226:227], 0, s[20:21]
	s_mov_b32 m0, s62
	s_nop 0
	global_load_lds_dwordx4 v[222:223], off
	v_lshl_add_u64 v[222:223], v[228:229], 0, s[20:21]
	s_mov_b32 m0, s63
	s_nop 0
	global_load_lds_dwordx4 v[222:223], off
	s_waitcnt vmcnt(8)
	s_waitcnt lgkmcnt(0)
	s_barrier
	s_waitcnt lgkmcnt(0)
	v_mfma_f32_16x16x32_bf16 v[60:63], v[142:145], v[190:193], v[60:63]
	v_mfma_f32_16x16x32_bf16 v[56:59], v[150:153], v[190:193], v[56:59]
	v_mfma_f32_16x16x32_bf16 v[44:47], v[142:145], v[198:201], v[44:47]
	v_mfma_f32_16x16x32_bf16 v[40:43], v[150:153], v[198:201], v[40:43]
	v_mfma_f32_16x16x32_bf16 v[28:31], v[142:145], v[206:209], v[28:31]
	v_mfma_f32_16x16x32_bf16 v[24:27], v[150:153], v[206:209], v[24:27]
	v_mfma_f32_16x16x32_bf16 v[12:15], v[142:145], v[214:217], v[12:15]
	v_mfma_f32_16x16x32_bf16 v[8:11], v[150:153], v[214:217], v[8:11]
	v_mfma_f32_16x16x32_bf16 v[60:63], v[146:149], v[194:197], v[60:63]
	v_mfma_f32_16x16x32_bf16 v[56:59], v[170:173], v[194:197], v[56:59]
	v_mfma_f32_16x16x32_bf16 v[44:47], v[146:149], v[202:205], v[44:47]
	v_mfma_f32_16x16x32_bf16 v[40:43], v[170:173], v[202:205], v[40:43]
	v_mfma_f32_16x16x32_bf16 v[28:31], v[146:149], v[210:213], v[28:31]
	v_mfma_f32_16x16x32_bf16 v[24:27], v[170:173], v[210:213], v[24:27]
	v_mfma_f32_16x16x32_bf16 v[12:15], v[146:149], v[218:221], v[12:15]
	v_mfma_f32_16x16x32_bf16 v[8:11], v[170:173], v[218:221], v[8:11]
	v_mfma_f32_16x16x32_bf16 v[52:55], v[174:177], v[190:193], v[52:55]
	v_mfma_f32_16x16x32_bf16 v[48:51], v[182:185], v[190:193], v[48:51]
	v_mfma_f32_16x16x32_bf16 v[36:39], v[174:177], v[198:201], v[36:39]
	v_mfma_f32_16x16x32_bf16 v[32:35], v[182:185], v[198:201], v[32:35]
	v_mfma_f32_16x16x32_bf16 v[20:23], v[174:177], v[206:209], v[20:23]
	v_mfma_f32_16x16x32_bf16 v[16:19], v[182:185], v[206:209], v[16:19]
	v_mfma_f32_16x16x32_bf16 v[4:7], v[174:177], v[214:217], v[4:7]
	v_mfma_f32_16x16x32_bf16 v[0:3], v[182:185], v[214:217], v[0:3]
	v_mfma_f32_16x16x32_bf16 v[52:55], v[178:181], v[194:197], v[52:55]
	v_mfma_f32_16x16x32_bf16 v[48:51], v[186:189], v[194:197], v[48:51]
	v_mfma_f32_16x16x32_bf16 v[36:39], v[178:181], v[202:205], v[36:39]
	v_mfma_f32_16x16x32_bf16 v[32:35], v[186:189], v[202:205], v[32:35]
	v_mfma_f32_16x16x32_bf16 v[20:23], v[178:181], v[210:213], v[20:23]
	v_mfma_f32_16x16x32_bf16 v[16:19], v[186:189], v[210:213], v[16:19]
	v_mfma_f32_16x16x32_bf16 v[4:7], v[178:181], v[218:221], v[4:7]
	v_mfma_f32_16x16x32_bf16 v[0:3], v[186:189], v[218:221], v[0:3]
	s_barrier
	s_add_i32 s72, s72, 2
	s_add_u32 s6, s6, 0x100
	s_addc_u32 s7, s7, 0
	s_add_u32 s70, s70, 0x100
	s_addc_u32 s71, s71, 0
	s_cmp_gt_u32 s72, 29
	s_cbranch_scc0 .LBB0_196
	s_and_b64 vcc, exec, s[22:23]
	s_cbranch_vccz .LBB0_199
	s_barrier
.LBB0_199:
	s_setprio 0
	v_add_u32_e32 v152, s66, v154
	v_ashrrev_i32_e32 v142, 8, v152
	v_ashrrev_i32_e32 v143, 31, v142
	v_ashrrev_i32_e32 v153, 31, v152
	v_lshlrev_b64 v[148:149], 20, v[142:143]
	v_add_u32_e32 v142, s68, v156
	s_cmp_gt_i32 s69, 7
	v_lshlrev_b64 v[146:147], 11, v[152:153]
	s_cselect_b64 s[40:41], -1, 0
	v_add_u32_e32 v144, 0xfffff800, v142
	s_mov_b64 s[6:7], -1
	s_and_b64 vcc, exec, s[40:41]
	v_lshl_add_u64 v[148:149], s[18:19], 0, v[148:149]
	v_lshl_add_u64 v[150:151], v[146:147], 2, s[14:15]
	v_ashrrev_i32_e32 v145, 31, v144
	v_lshlrev_b32_sdwa v138, v168, v152 dst_sel:DWORD dst_unused:UNUSED_PAD src0_sel:DWORD src1_sel:BYTE_0
	s_cbranch_vccz .LBB0_201
	v_lshl_add_u64 v[152:153], v[144:145], 2, v[150:151]
	global_store_dwordx4 v[152:153], v[124:127], off
	global_store_dwordx4 v[152:153], v[120:123], off offset:16
	v_lshlrev_b64 v[152:153], 9, v[144:145]
	v_lshl_add_u64 v[152:153], v[148:149], 0, v[152:153]
	v_lshl_add_u64 v[152:153], v[152:153], 0, v[138:139]
	v_cvt_pk_bf16_f32 v143, v124, v124
	global_store_short v[152:153], v143, off
	v_cvt_pk_bf16_f32 v143, v120, v120
	global_store_short v[152:153], v143, off offset:2048
	v_cvt_pk_bf16_f32 v143, v125, v125
	global_store_short v[152:153], v143, off offset:512
	v_cvt_pk_bf16_f32 v143, v121, v121
	global_store_short v[152:153], v143, off offset:2560
	v_cvt_pk_bf16_f32 v143, v126, v126
	global_store_short v[152:153], v143, off offset:1024
	v_cvt_pk_bf16_f32 v143, v122, v122
	global_store_short v[152:153], v143, off offset:3072
	v_cvt_pk_bf16_f32 v143, v127, v127
	global_store_short v[152:153], v143, off offset:1536
	v_cvt_pk_bf16_f32 v143, v123, v123
	global_store_short v[152:153], v143, off offset:3584
	s_mov_b64 s[6:7], 0

.LBB0_334:
	s_add_u32 s22, s22, 0x160080
	s_addc_u32 s23, s23, 0
	s_add_u32 s59, s24, 0x100
	v_mov_b32_e32 v0, 0
	s_addc_u32 s60, s25, 0
	s_mov_b32 s61, -2
	v_mov_b32_e32 v1, v0
	v_mov_b32_e32 v2, v0
	v_mov_b32_e32 v3, v0
	v_mov_b32_e32 v4, v0
	v_mov_b32_e32 v5, v0
	v_mov_b32_e32 v6, v0
	v_mov_b32_e32 v7, v0
	v_mov_b32_e32 v16, v0
	v_mov_b32_e32 v17, v0
	v_mov_b32_e32 v18, v0
	v_mov_b32_e32 v19, v0
	v_mov_b32_e32 v20, v0
	v_mov_b32_e32 v21, v0
	v_mov_b32_e32 v22, v0
	v_mov_b32_e32 v23, v0
	v_mov_b32_e32 v32, v0
	v_mov_b32_e32 v33, v0
	v_mov_b32_e32 v34, v0
	v_mov_b32_e32 v35, v0
	v_mov_b32_e32 v36, v0
	v_mov_b32_e32 v37, v0
	v_mov_b32_e32 v38, v0
	v_mov_b32_e32 v39, v0
	v_mov_b32_e32 v48, v0
	v_mov_b32_e32 v49, v0
	v_mov_b32_e32 v50, v0
	v_mov_b32_e32 v51, v0
	v_mov_b32_e32 v52, v0
	v_mov_b32_e32 v53, v0
	v_mov_b32_e32 v54, v0
	v_mov_b32_e32 v55, v0
	v_mov_b32_e32 v8, v0
	v_mov_b32_e32 v9, v0
	v_mov_b32_e32 v10, v0
	v_mov_b32_e32 v11, v0
	v_mov_b32_e32 v12, v0
	v_mov_b32_e32 v13, v0
	v_mov_b32_e32 v14, v0
	v_mov_b32_e32 v15, v0
	v_mov_b32_e32 v24, v0
	v_mov_b32_e32 v25, v0
	v_mov_b32_e32 v26, v0
	v_mov_b32_e32 v27, v0
	v_mov_b32_e32 v28, v0
	v_mov_b32_e32 v29, v0
	v_mov_b32_e32 v30, v0
	v_mov_b32_e32 v31, v0
	v_mov_b32_e32 v40, v0
	v_mov_b32_e32 v41, v0
	v_mov_b32_e32 v42, v0
	v_mov_b32_e32 v43, v0
	v_mov_b32_e32 v44, v0
	v_mov_b32_e32 v45, v0
	v_mov_b32_e32 v46, v0
	v_mov_b32_e32 v47, v0
	v_mov_b32_e32 v56, v0
	v_mov_b32_e32 v57, v0
	v_mov_b32_e32 v58, v0
	v_mov_b32_e32 v59, v0
	v_mov_b32_e32 v60, v0
	v_mov_b32_e32 v61, v0
	v_mov_b32_e32 v62, v0
	v_mov_b32_e32 v63, v0
	v_mov_b32_e32 v64, v0
	v_mov_b32_e32 v65, v0
	v_mov_b32_e32 v66, v0
	v_mov_b32_e32 v67, v0
	v_mov_b32_e32 v68, v0
	v_mov_b32_e32 v69, v0
	v_mov_b32_e32 v70, v0
	v_mov_b32_e32 v71, v0
	v_mov_b32_e32 v80, v0
	v_mov_b32_e32 v81, v0
	v_mov_b32_e32 v82, v0
	v_mov_b32_e32 v83, v0
	v_mov_b32_e32 v84, v0
	v_mov_b32_e32 v85, v0
	v_mov_b32_e32 v86, v0
	v_mov_b32_e32 v87, v0
	v_mov_b32_e32 v96, v0
	v_mov_b32_e32 v97, v0
	v_mov_b32_e32 v98, v0
	v_mov_b32_e32 v99, v0
	v_mov_b32_e32 v100, v0
	v_mov_b32_e32 v101, v0
	v_mov_b32_e32 v102, v0
	v_mov_b32_e32 v103, v0
	v_mov_b32_e32 v112, v0
	v_mov_b32_e32 v113, v0
	v_mov_b32_e32 v114, v0
	v_mov_b32_e32 v115, v0
	v_mov_b32_e32 v116, v0
	v_mov_b32_e32 v117, v0
	v_mov_b32_e32 v118, v0
	v_mov_b32_e32 v119, v0
	v_mov_b32_e32 v72, v0
	v_mov_b32_e32 v73, v0
	v_mov_b32_e32 v74, v0
	v_mov_b32_e32 v75, v0
	v_mov_b32_e32 v76, v0
	v_mov_b32_e32 v77, v0
	v_mov_b32_e32 v78, v0
	v_mov_b32_e32 v79, v0
	v_mov_b32_e32 v88, v0
	v_mov_b32_e32 v89, v0
	v_mov_b32_e32 v90, v0
	v_mov_b32_e32 v91, v0
	v_mov_b32_e32 v92, v0
	v_mov_b32_e32 v93, v0
	v_mov_b32_e32 v94, v0
	v_mov_b32_e32 v95, v0
	v_mov_b32_e32 v104, v0
	v_mov_b32_e32 v105, v0
	v_mov_b32_e32 v106, v0
	v_mov_b32_e32 v107, v0
	v_mov_b32_e32 v108, v0
	v_mov_b32_e32 v109, v0
	v_mov_b32_e32 v110, v0
	v_mov_b32_e32 v111, v0
	v_mov_b32_e32 v120, v0
	v_mov_b32_e32 v121, v0
	v_mov_b32_e32 v122, v0
	v_mov_b32_e32 v123, v0
	v_mov_b32_e32 v124, v0
	v_mov_b32_e32 v125, v0
	v_mov_b32_e32 v126, v0
	v_mov_b32_e32 v127, v0
	s_cmp_eq_u64 s[14:15], 0
	s_cbranch_scc0 .Lprio_skip_2
	s_setprio 1
.Lprio_skip_2:
.LBB0_335:
	ds_read_b128 v[146:149], v156
	ds_read_b128 v[160:163], v156 offset:1024
	ds_read_b128 v[164:167], v156 offset:2048
	ds_read_b128 v[168:171], v156 offset:3072
	ds_read_b128 v[172:175], v157
	ds_read_b128 v[176:179], v157 offset:1024
	ds_read_b128 v[180:183], v157 offset:2048
	ds_read_b128 v[184:187], v157 offset:3072
	s_add_u32 s24, s22, 0xffea0080
	s_addc_u32 s25, s23, -1
	s_cmpk_eq_i32 s61, 0x54
	s_cselect_b32 s27, s19, s25
	s_cselect_b32 s26, s18, s24
	s_cselect_b32 s25, s21, s60
	s_cselect_b32 s24, s20, s59
	v_lshl_add_u64 v[220:221], s[22:23], 0, v[136:137]
	s_add_i32 m0, s36, 0xc000
	ds_read_b128 v[188:191], v158
	ds_read_b128 v[192:195], v158 offset:1024
	ds_read_b128 v[196:199], v158 offset:2048
	ds_read_b128 v[200:203], v158 offset:3072
	ds_read_b128 v[204:207], v158 offset:4096
	ds_read_b128 v[208:211], v158 offset:5120
	ds_read_b128 v[212:215], v158 offset:6144
	ds_read_b128 v[216:219], v158 offset:7168
	global_load_lds_dwordx4 v[220:221], off
	v_lshl_add_u64 v[220:221], s[22:23], 0, v[140:141]
	s_add_i32 m0, s36, 0xe000
	s_nop 0
	global_load_lds_dwordx4 v[220:221], off
	s_waitcnt vmcnt(8)
	s_waitcnt lgkmcnt(0)
	s_barrier
	s_waitcnt lgkmcnt(0)
	v_mfma_f32_16x16x32_bf16 v[124:127], v[146:149], v[188:191], v[124:127]
	v_mfma_f32_16x16x32_bf16 v[120:123], v[164:167], v[188:191], v[120:123]
	v_mfma_f32_16x16x32_bf16 v[108:111], v[146:149], v[196:199], v[108:111]
	v_mfma_f32_16x16x32_bf16 v[104:107], v[164:167], v[196:199], v[104:107]
	v_mfma_f32_16x16x32_bf16 v[92:95], v[146:149], v[204:207], v[92:95]
	v_mfma_f32_16x16x32_bf16 v[88:91], v[164:167], v[204:207], v[88:91]
	v_mfma_f32_16x16x32_bf16 v[76:79], v[146:149], v[212:215], v[76:79]
	v_mfma_f32_16x16x32_bf16 v[72:75], v[164:167], v[212:215], v[72:75]
	v_mfma_f32_16x16x32_bf16 v[124:127], v[160:163], v[192:195], v[124:127]
	v_mfma_f32_16x16x32_bf16 v[120:123], v[168:171], v[192:195], v[120:123]
	v_mfma_f32_16x16x32_bf16 v[108:111], v[160:163], v[200:203], v[108:111]
	v_mfma_f32_16x16x32_bf16 v[104:107], v[168:171], v[200:203], v[104:107]
	v_mfma_f32_16x16x32_bf16 v[92:95], v[160:163], v[208:211], v[92:95]
	v_mfma_f32_16x16x32_bf16 v[88:91], v[168:171], v[208:211], v[88:91]
	v_mfma_f32_16x16x32_bf16 v[76:79], v[160:163], v[216:219], v[76:79]
	v_mfma_f32_16x16x32_bf16 v[72:75], v[168:171], v[216:219], v[72:75]
	v_mfma_f32_16x16x32_bf16 v[116:119], v[172:175], v[188:191], v[116:119]
	v_mfma_f32_16x16x32_bf16 v[112:115], v[180:183], v[188:191], v[112:115]
	v_mfma_f32_16x16x32_bf16 v[100:103], v[172:175], v[196:199], v[100:103]
	v_mfma_f32_16x16x32_bf16 v[96:99], v[180:183], v[196:199], v[96:99]
	v_mfma_f32_16x16x32_bf16 v[84:87], v[172:175], v[204:207], v[84:87]
	v_mfma_f32_16x16x32_bf16 v[80:83], v[180:183], v[204:207], v[80:83]
	v_mfma_f32_16x16x32_bf16 v[68:71], v[172:175], v[212:215], v[68:71]
	v_mfma_f32_16x16x32_bf16 v[64:67], v[180:183], v[212:215], v[64:67]
	v_mfma_f32_16x16x32_bf16 v[116:119], v[176:179], v[192:195], v[116:119]
	v_mfma_f32_16x16x32_bf16 v[112:115], v[184:187], v[192:195], v[112:115]
	v_mfma_f32_16x16x32_bf16 v[100:103], v[176:179], v[200:203], v[100:103]
	v_mfma_f32_16x16x32_bf16 v[96:99], v[184:187], v[200:203], v[96:99]
	v_mfma_f32_16x16x32_bf16 v[84:87], v[176:179], v[208:211], v[84:87]
	v_mfma_f32_16x16x32_bf16 v[80:83], v[184:187], v[208:211], v[80:83]
	v_mfma_f32_16x16x32_bf16 v[68:71], v[176:179], v[216:219], v[68:71]
	v_mfma_f32_16x16x32_bf16 v[64:67], v[184:187], v[216:219], v[64:67]
	s_barrier
	s_add_i32 s65, s43, s17
	v_lshl_add_u64 v[220:221], s[24:25], 0, v[130:131]
	s_mov_b32 m0, s65
	ds_read_b128 v[188:191], v158 offset:16384
	ds_read_b128 v[192:195], v158 offset:17408
	ds_read_b128 v[196:199], v158 offset:18432
	ds_read_b128 v[200:203], v158 offset:19456
	ds_read_b128 v[204:207], v158 offset:20480
	ds_read_b128 v[208:211], v158 offset:21504
	ds_read_b128 v[212:215], v158 offset:22528
	ds_read_b128 v[216:219], v158 offset:23552
	global_load_lds_dwordx4 v[220:221], off
	s_add_i32 m0, s65, 0x2000
	s_add_u32 s66, s24, 0x160000
	v_lshl_add_u64 v[222:223], s[24:25], 0, v[134:135]
	s_addc_u32 s67, s25, 0
	s_add_i32 s65, s44, s17
	global_load_lds_dwordx4 v[222:223], off
	v_lshl_add_u64 v[224:225], s[66:67], 0, v[130:131]
	s_mov_b32 m0, s65
	v_lshl_add_u64 v[226:227], s[26:27], 0, v[132:133]
	global_load_lds_dwordx4 v[224:225], off
	v_lshl_add_u64 v[224:225], s[66:67], 0, v[134:135]
	s_add_i32 m0, s65, 0x2000
	s_nop 0
	global_load_lds_dwordx4 v[224:225], off
	v_lshl_add_u64 v[224:225], s[26:27], 0, v[128:129]
	s_mov_b32 m0, s36
	s_nop 0
	global_load_lds_dwordx4 v[224:225], off
	s_mov_b32 m0, s37
	s_nop 0
	global_load_lds_dwordx4 v[226:227], off
	s_waitcnt vmcnt(8)
	s_waitcnt lgkmcnt(0)
	s_barrier
	s_waitcnt lgkmcnt(0)
	v_mfma_f32_16x16x32_bf16 v[60:63], v[146:149], v[188:191], v[60:63]
	v_mfma_f32_16x16x32_bf16 v[56:59], v[164:167], v[188:191], v[56:59]
	v_mfma_f32_16x16x32_bf16 v[44:47], v[146:149], v[196:199], v[44:47]
	v_mfma_f32_16x16x32_bf16 v[40:43], v[164:167], v[196:199], v[40:43]
	v_mfma_f32_16x16x32_bf16 v[28:31], v[146:149], v[204:207], v[28:31]
	v_mfma_f32_16x16x32_bf16 v[24:27], v[164:167], v[204:207], v[24:27]
	v_mfma_f32_16x16x32_bf16 v[12:15], v[146:149], v[212:215], v[12:15]
	v_mfma_f32_16x16x32_bf16 v[8:11], v[164:167], v[212:215], v[8:11]
	v_mfma_f32_16x16x32_bf16 v[60:63], v[160:163], v[192:195], v[60:63]
	v_mfma_f32_16x16x32_bf16 v[56:59], v[168:171], v[192:195], v[56:59]
	v_mfma_f32_16x16x32_bf16 v[44:47], v[160:163], v[200:203], v[44:47]
	v_mfma_f32_16x16x32_bf16 v[40:43], v[168:171], v[200:203], v[40:43]
	v_mfma_f32_16x16x32_bf16 v[28:31], v[160:163], v[208:211], v[28:31]
	v_mfma_f32_16x16x32_bf16 v[24:27], v[168:171], v[208:211], v[24:27]
	v_mfma_f32_16x16x32_bf16 v[12:15], v[160:163], v[216:219], v[12:15]
	v_mfma_f32_16x16x32_bf16 v[8:11], v[168:171], v[216:219], v[8:11]
	v_mfma_f32_16x16x32_bf16 v[52:55], v[172:175], v[188:191], v[52:55]
	v_mfma_f32_16x16x32_bf16 v[48:51], v[180:183], v[188:191], v[48:51]
	v_mfma_f32_16x16x32_bf16 v[36:39], v[172:175], v[196:199], v[36:39]
	v_mfma_f32_16x16x32_bf16 v[32:35], v[180:183], v[196:199], v[32:35]
	v_mfma_f32_16x16x32_bf16 v[20:23], v[172:175], v[204:207], v[20:23]
	v_mfma_f32_16x16x32_bf16 v[16:19], v[180:183], v[204:207], v[16:19]
	v_mfma_f32_16x16x32_bf16 v[4:7], v[172:175], v[212:215], v[4:7]
	v_mfma_f32_16x16x32_bf16 v[0:3], v[180:183], v[212:215], v[0:3]
	v_mfma_f32_16x16x32_bf16 v[52:55], v[176:179], v[192:195], v[52:55]
	v_mfma_f32_16x16x32_bf16 v[48:51], v[184:187], v[192:195], v[48:51]
	v_mfma_f32_16x16x32_bf16 v[36:39], v[176:179], v[200:203], v[36:39]
	v_mfma_f32_16x16x32_bf16 v[32:35], v[184:187], v[200:203], v[32:35]
	v_mfma_f32_16x16x32_bf16 v[20:23], v[176:179], v[208:211], v[20:23]
	v_mfma_f32_16x16x32_bf16 v[16:19], v[184:187], v[208:211], v[16:19]
	v_mfma_f32_16x16x32_bf16 v[4:7], v[176:179], v[216:219], v[4:7]
	v_mfma_f32_16x16x32_bf16 v[0:3], v[184:187], v[216:219], v[0:3]
	s_barrier
	s_add_i32 s65, 0, 0x18000
	v_add_u32_e32 v159, s65, v154
	s_add_i32 s66, 0, 0x1c000
	ds_read_b128 v[146:149], v159
	ds_read_b128 v[160:163], v159 offset:1024
	ds_read_b128 v[164:167], v159 offset:2048
	ds_read_b128 v[168:171], v159 offset:3072
	v_add_u32_e32 v159, s66, v154
	ds_read_b128 v[172:175], v159
	ds_read_b128 v[176:179], v159 offset:1024
	ds_read_b128 v[180:183], v159 offset:2048
	ds_read_b128 v[184:187], v159 offset:3072
	s_add_u32 s26, s26, 0x160000
	s_addc_u32 s27, s27, 0
	s_mov_b32 m0, s38
	v_lshl_add_u64 v[228:229], s[26:27], 0, v[128:129]
	ds_read_b128 v[188:191], v158 offset:32768
	ds_read_b128 v[192:195], v158 offset:33792
	ds_read_b128 v[196:199], v158 offset:34816
	ds_read_b128 v[200:203], v158 offset:35840
	ds_read_b128 v[204:207], v158 offset:36864
	ds_read_b128 v[208:211], v158 offset:37888
	ds_read_b128 v[212:215], v158 offset:38912
	ds_read_b128 v[216:219], v158 offset:39936
	global_load_lds_dwordx4 v[228:229], off
	v_lshl_add_u64 v[228:229], s[26:27], 0, v[132:133]
	s_mov_b32 m0, s39
	s_nop 0
	global_load_lds_dwordx4 v[228:229], off
	s_waitcnt vmcnt(8)
	s_waitcnt lgkmcnt(0)
	s_barrier
	s_waitcnt lgkmcnt(0)
	v_mfma_f32_16x16x32_bf16 v[124:127], v[146:149], v[188:191], v[124:127]
	v_mfma_f32_16x16x32_bf16 v[120:123], v[164:167], v[188:191], v[120:123]
	v_mfma_f32_16x16x32_bf16 v[108:111], v[146:149], v[196:199], v[108:111]
	v_mfma_f32_16x16x32_bf16 v[104:107], v[164:167], v[196:199], v[104:107]
	v_mfma_f32_16x16x32_bf16 v[92:95], v[146:149], v[204:207], v[92:95]
	v_mfma_f32_16x16x32_bf16 v[88:91], v[164:167], v[204:207], v[88:91]
	v_mfma_f32_16x16x32_bf16 v[76:79], v[146:149], v[212:215], v[76:79]
	v_mfma_f32_16x16x32_bf16 v[72:75], v[164:167], v[212:215], v[72:75]
	v_mfma_f32_16x16x32_bf16 v[124:127], v[160:163], v[192:195], v[124:127]
	v_mfma_f32_16x16x32_bf16 v[120:123], v[168:171], v[192:195], v[120:123]
	v_mfma_f32_16x16x32_bf16 v[108:111], v[160:163], v[200:203], v[108:111]
	v_mfma_f32_16x16x32_bf16 v[104:107], v[168:171], v[200:203], v[104:107]
	v_mfma_f32_16x16x32_bf16 v[92:95], v[160:163], v[208:211], v[92:95]
	v_mfma_f32_16x16x32_bf16 v[88:91], v[168:171], v[208:211], v[88:91]
	v_mfma_f32_16x16x32_bf16 v[76:79], v[160:163], v[216:219], v[76:79]
	v_mfma_f32_16x16x32_bf16 v[72:75], v[168:171], v[216:219], v[72:75]
	v_mfma_f32_16x16x32_bf16 v[116:119], v[172:175], v[188:191], v[116:119]
	v_mfma_f32_16x16x32_bf16 v[112:115], v[180:183], v[188:191], v[112:115]
	v_mfma_f32_16x16x32_bf16 v[100:103], v[172:175], v[196:199], v[100:103]
	v_mfma_f32_16x16x32_bf16 v[96:99], v[180:183], v[196:199], v[96:99]
	v_mfma_f32_16x16x32_bf16 v[84:87], v[172:175], v[204:207], v[84:87]
	v_mfma_f32_16x16x32_bf16 v[80:83], v[180:183], v[204:207], v[80:83]
	v_mfma_f32_16x16x32_bf16 v[68:71], v[172:175], v[212:215], v[68:71]
	v_mfma_f32_16x16x32_bf16 v[64:67], v[180:183], v[212:215], v[64:67]
	v_mfma_f32_16x16x32_bf16 v[116:119], v[176:179], v[192:195], v[116:119]
	v_mfma_f32_16x16x32_bf16 v[112:115], v[184:187], v[192:195], v[112:115]
	v_mfma_f32_16x16x32_bf16 v[100:103], v[176:179], v[200:203], v[100:103]
	v_mfma_f32_16x16x32_bf16 v[96:99], v[184:187], v[200:203], v[96:99]
	v_mfma_f32_16x16x32_bf16 v[84:87], v[176:179], v[208:211], v[84:87]
	v_mfma_f32_16x16x32_bf16 v[80:83], v[184:187], v[208:211], v[80:83]
	v_mfma_f32_16x16x32_bf16 v[68:71], v[176:179], v[216:219], v[68:71]
	v_mfma_f32_16x16x32_bf16 v[64:67], v[184:187], v[216:219], v[64:67]
	s_barrier
	s_add_i32 s26, s65, s17
	v_lshl_add_u64 v[220:221], v[220:221], 0, s[12:13]
	s_mov_b32 m0, s26
	ds_read_b128 v[188:191], v158 offset:49152
	ds_read_b128 v[192:195], v158 offset:50176
	ds_read_b128 v[196:199], v158 offset:51200
	ds_read_b128 v[200:203], v158 offset:52224
	ds_read_b128 v[204:207], v158 offset:53248
	ds_read_b128 v[208:211], v158 offset:54272
	ds_read_b128 v[212:215], v158 offset:55296
	ds_read_b128 v[216:219], v158 offset:56320
	global_load_lds_dwordx4 v[220:221], off
	s_add_i32 m0, s26, 0x2000
	s_add_u32 s24, s24, 0x160080
	v_lshl_add_u64 v[220:221], v[222:223], 0, s[12:13]
	s_addc_u32 s25, s25, 0
	s_add_i32 s26, s66, s17
	global_load_lds_dwordx4 v[220:221], off
	v_lshl_add_u64 v[220:221], s[24:25], 0, v[130:131]
	s_mov_b32 m0, s26
	s_nop 0
	global_load_lds_dwordx4 v[220:221], off
	v_lshl_add_u64 v[220:221], s[24:25], 0, v[134:135]
	s_add_i32 m0, s26, 0x2000
	s_nop 0
	global_load_lds_dwordx4 v[220:221], off
	v_lshl_add_u64 v[220:221], v[224:225], 0, s[12:13]
	s_mov_b32 m0, s41
	s_nop 0
	global_load_lds_dwordx4 v[220:221], off
	v_lshl_add_u64 v[220:221], v[226:227], 0, s[12:13]
	s_mov_b32 m0, s42
	s_nop 0
	global_load_lds_dwordx4 v[220:221], off
	s_waitcnt vmcnt(8)
	s_waitcnt lgkmcnt(0)
	s_barrier
	s_waitcnt lgkmcnt(0)
	v_mfma_f32_16x16x32_bf16 v[60:63], v[146:149], v[188:191], v[60:63]
	v_mfma_f32_16x16x32_bf16 v[56:59], v[164:167], v[188:191], v[56:59]
	v_mfma_f32_16x16x32_bf16 v[44:47], v[146:149], v[196:199], v[44:47]
	v_mfma_f32_16x16x32_bf16 v[40:43], v[164:167], v[196:199], v[40:43]
	v_mfma_f32_16x16x32_bf16 v[28:31], v[146:149], v[204:207], v[28:31]
	v_mfma_f32_16x16x32_bf16 v[24:27], v[164:167], v[204:207], v[24:27]
	v_mfma_f32_16x16x32_bf16 v[12:15], v[146:149], v[212:215], v[12:15]
	v_mfma_f32_16x16x32_bf16 v[8:11], v[164:167], v[212:215], v[8:11]
	v_mfma_f32_16x16x32_bf16 v[60:63], v[160:163], v[192:195], v[60:63]
	v_mfma_f32_16x16x32_bf16 v[56:59], v[168:171], v[192:195], v[56:59]
	v_mfma_f32_16x16x32_bf16 v[44:47], v[160:163], v[200:203], v[44:47]
	v_mfma_f32_16x16x32_bf16 v[40:43], v[168:171], v[200:203], v[40:43]
	v_mfma_f32_16x16x32_bf16 v[28:31], v[160:163], v[208:211], v[28:31]
	v_mfma_f32_16x16x32_bf16 v[24:27], v[168:171], v[208:211], v[24:27]
	v_mfma_f32_16x16x32_bf16 v[12:15], v[160:163], v[216:219], v[12:15]
	v_mfma_f32_16x16x32_bf16 v[8:11], v[168:171], v[216:219], v[8:11]
	v_mfma_f32_16x16x32_bf16 v[52:55], v[172:175], v[188:191], v[52:55]
	v_mfma_f32_16x16x32_bf16 v[48:51], v[180:183], v[188:191], v[48:51]
	v_mfma_f32_16x16x32_bf16 v[36:39], v[172:175], v[196:199], v[36:39]
	v_mfma_f32_16x16x32_bf16 v[32:35], v[180:183], v[196:199], v[32:35]
	v_mfma_f32_16x16x32_bf16 v[20:23], v[172:175], v[204:207], v[20:23]
	v_mfma_f32_16x16x32_bf16 v[16:19], v[180:183], v[204:207], v[16:19]
	v_mfma_f32_16x16x32_bf16 v[4:7], v[172:175], v[212:215], v[4:7]
	v_mfma_f32_16x16x32_bf16 v[0:3], v[180:183], v[212:215], v[0:3]
	v_mfma_f32_16x16x32_bf16 v[52:55], v[176:179], v[192:195], v[52:55]
	v_mfma_f32_16x16x32_bf16 v[48:51], v[184:187], v[192:195], v[48:51]
	v_mfma_f32_16x16x32_bf16 v[36:39], v[176:179], v[200:203], v[36:39]
	v_mfma_f32_16x16x32_bf16 v[32:35], v[184:187], v[200:203], v[32:35]
	v_mfma_f32_16x16x32_bf16 v[20:23], v[176:179], v[208:211], v[20:23]
	v_mfma_f32_16x16x32_bf16 v[16:19], v[184:187], v[208:211], v[16:19]
	v_mfma_f32_16x16x32_bf16 v[4:7], v[176:179], v[216:219], v[4:7]
	v_mfma_f32_16x16x32_bf16 v[0:3], v[184:187], v[216:219], v[0:3]
	s_barrier
	s_add_i32 s61, s61, 2
	s_add_u32 s22, s22, 0x100
	s_addc_u32 s23, s23, 0
	s_add_u32 s59, s59, 0x100
	s_addc_u32 s60, s60, 0
	s_cmpk_gt_u32 s61, 0x55
	s_cbranch_scc0 .LBB0_335
	s_and_b64 vcc, exec, s[14:15]
	s_cbranch_vccz .LBB0_338
	s_barrier
.LBB0_338:
	s_setprio 0
	v_add_u32_e32 v148, s58, v153
	v_add_u32_e32 v146, s47, v155
	v_ashrrev_i32_e32 v149, 31, v148
	v_ashrrev_i32_e32 v147, 31, v146
	v_lshlrev_b64 v[168:169], 12, v[148:149]
	v_lshl_add_u64 v[160:161], s[50:51], 0, v[168:169]
	v_lshlrev_b64 v[146:147], 1, v[146:147]
	v_lshl_add_u64 v[164:165], v[160:161], 0, v[146:147]
	global_load_dwordx4 v[160:163], v[164:165], off
	s_nop 0
	global_load_dwordx4 v[164:167], v[164:165], off offset:256
	v_add_u32_e32 v170, 16, v148
	v_ashrrev_i32_e32 v171, 31, v170
	v_lshl_add_u64 v[168:169], s[56:57], 0, v[168:169]
	v_lshlrev_b64 v[170:171], 12, v[170:171]
	v_lshl_add_u64 v[168:169], v[168:169], 0, v[146:147]
	v_lshl_add_u64 v[172:173], s[50:51], 0, v[170:171]
	v_lshl_add_u64 v[172:173], v[172:173], 0, v[146:147]
	s_andn2_b64 vcc, exec, s[6:7]
	s_mov_b64 s[6:7], -1
	s_waitcnt vmcnt(0)
	v_lshlrev_b32_e32 v176, 16, v162
	v_and_b32_e32 v177, 0xffff0000, v162
	v_lshlrev_b32_e32 v174, 16, v160
	v_and_b32_e32 v175, 0xffff0000, v160
	v_lshlrev_b32_e32 v160, 16, v161
	v_and_b32_e32 v161, 0xffff0000, v161
	v_lshlrev_b32_e32 v162, 16, v163
	v_and_b32_e32 v163, 0xffff0000, v163
	v_lshlrev_b32_e32 v178, 16, v164
	v_and_b32_e32 v179, 0xffff0000, v164
	v_lshlrev_b32_e32 v164, 16, v165
	v_and_b32_e32 v165, 0xffff0000, v165
	v_lshlrev_b32_e32 v180, 16, v166
	v_and_b32_e32 v181, 0xffff0000, v166
	v_lshlrev_b32_e32 v166, 16, v167
	v_and_b32_e32 v167, 0xffff0000, v167
	v_pk_mul_f32 v[176:177], v[176:177], s[16:17] op_sel_hi:[1,0]
	v_pk_mul_f32 v[174:175], v[174:175], s[16:17] op_sel_hi:[1,0]
	v_pk_mul_f32 v[160:161], v[160:161], s[16:17] op_sel_hi:[1,0]
	v_pk_mul_f32 v[162:163], v[162:163], s[16:17] op_sel_hi:[1,0]
	v_pk_mul_f32 v[178:179], v[178:179], s[16:17] op_sel_hi:[1,0]
	v_pk_mul_f32 v[164:165], v[164:165], s[16:17] op_sel_hi:[1,0]
	v_pk_mul_f32 v[180:181], v[180:181], s[16:17] op_sel_hi:[1,0]
	v_pk_mul_f32 v[166:167], v[166:167], s[16:17] op_sel_hi:[1,0]
	v_pk_fma_f32 v[120:121], v[120:121], 0.5, v[176:177] op_sel_hi:[1,0,1]
	v_pk_fma_f32 v[126:127], v[126:127], 0.5, v[160:161] op_sel_hi:[1,0,1]
	v_pk_fma_f32 v[124:125], v[124:125], 0.5, v[174:175] op_sel_hi:[1,0,1]
	v_pk_fma_f32 v[122:123], v[122:123], 0.5, v[162:163] op_sel_hi:[1,0,1]
	v_pk_fma_f32 v[160:161], v[118:119], 0.5, v[164:165] op_sel_hi:[1,0,1]
	v_pk_fma_f32 v[162:163], v[116:117], 0.5, v[178:179] op_sel_hi:[1,0,1]
	v_cvt_pk_bf16_f32 v116, v124, v125
	v_cvt_pk_bf16_f32 v117, v126, v127
	v_cvt_pk_bf16_f32 v118, v120, v121
	v_cvt_pk_bf16_f32 v119, v122, v123
	global_store_dwordx4 v[168:169], v[116:119], off
	v_pk_fma_f32 v[120:121], v[114:115], 0.5, v[166:167] op_sel_hi:[1,0,1]
	v_pk_fma_f32 v[114:115], v[112:113], 0.5, v[180:181] op_sel_hi:[1,0,1]
	global_load_dwordx4 v[116:119], v[172:173], off
	v_cvt_pk_bf16_f32 v112, v162, v163
	v_cvt_pk_bf16_f32 v113, v160, v161
	v_cvt_pk_bf16_f32 v114, v114, v115
	v_cvt_pk_bf16_f32 v115, v120, v121
	global_store_dwordx4 v[168:169], v[112:115], off offset:256
	global_load_dwordx4 v[112:115], v[172:173], off offset:256
	v_add_u32_e32 v120, 32, v148
	v_ashrrev_i32_e32 v121, 31, v120
	v_lshlrev_b64 v[120:121], 12, v[120:121]
	v_lshl_add_u64 v[122:123], s[56:57], 0, v[170:171]
	v_lshl_add_u64 v[124:125], s[50:51], 0, v[120:121]
	v_lshl_add_u64 v[122:123], v[122:123], 0, v[146:147]
	v_lshl_add_u64 v[124:125], v[124:125], 0, v[146:147]
	s_waitcnt vmcnt(2)
	v_lshlrev_b32_e32 v160, 16, v118
	v_and_b32_e32 v161, 0xffff0000, v118
	v_lshlrev_b32_e32 v126, 16, v116
	v_and_b32_e32 v127, 0xffff0000, v116
	v_lshlrev_b32_e32 v116, 16, v117
	v_and_b32_e32 v117, 0xffff0000, v117
	v_lshlrev_b32_e32 v118, 16, v119
	v_and_b32_e32 v119, 0xffff0000, v119
	s_waitcnt vmcnt(0)
	v_lshlrev_b32_e32 v162, 16, v112
	v_and_b32_e32 v163, 0xffff0000, v112
	v_lshlrev_b32_e32 v112, 16, v113
	v_and_b32_e32 v113, 0xffff0000, v113
	v_lshlrev_b32_e32 v164, 16, v114
	v_and_b32_e32 v165, 0xffff0000, v114
	v_lshlrev_b32_e32 v114, 16, v115
	v_and_b32_e32 v115, 0xffff0000, v115
	v_pk_mul_f32 v[160:161], v[160:161], s[16:17] op_sel_hi:[1,0]
	v_pk_mul_f32 v[126:127], v[126:127], s[16:17] op_sel_hi:[1,0]
	v_pk_mul_f32 v[116:117], v[116:117], s[16:17] op_sel_hi:[1,0]
	v_pk_mul_f32 v[118:119], v[118:119], s[16:17] op_sel_hi:[1,0]
	v_pk_mul_f32 v[162:163], v[162:163], s[16:17] op_sel_hi:[1,0]
	v_pk_mul_f32 v[112:113], v[112:113], s[16:17] op_sel_hi:[1,0]
	v_pk_mul_f32 v[164:165], v[164:165], s[16:17] op_sel_hi:[1,0]
	v_pk_mul_f32 v[114:115], v[114:115], s[16:17] op_sel_hi:[1,0]
	v_pk_fma_f32 v[104:105], v[104:105], 0.5, v[160:161] op_sel_hi:[1,0,1]
	v_pk_fma_f32 v[110:111], v[110:111], 0.5, v[116:117] op_sel_hi:[1,0,1]
	v_pk_fma_f32 v[108:109], v[108:109], 0.5, v[126:127] op_sel_hi:[1,0,1]
	v_pk_fma_f32 v[106:107], v[106:107], 0.5, v[118:119] op_sel_hi:[1,0,1]
	v_pk_fma_f32 v[112:113], v[102:103], 0.5, v[112:113] op_sel_hi:[1,0,1]
	v_pk_fma_f32 v[116:117], v[100:101], 0.5, v[162:163] op_sel_hi:[1,0,1]
	v_cvt_pk_bf16_f32 v100, v108, v109
	v_cvt_pk_bf16_f32 v101, v110, v111
	v_cvt_pk_bf16_f32 v102, v104, v105
	v_cvt_pk_bf16_f32 v103, v106, v107
	global_store_dwordx4 v[122:123], v[100:103], off
	v_pk_fma_f32 v[104:105], v[98:99], 0.5, v[114:115] op_sel_hi:[1,0,1]
	v_pk_fma_f32 v[98:99], v[96:97], 0.5, v[164:165] op_sel_hi:[1,0,1]
	global_load_dwordx4 v[100:103], v[124:125], off
	v_cvt_pk_bf16_f32 v96, v116, v117
	v_cvt_pk_bf16_f32 v97, v112, v113
	v_cvt_pk_bf16_f32 v98, v98, v99
	v_cvt_pk_bf16_f32 v99, v104, v105
	global_store_dwordx4 v[122:123], v[96:99], off offset:256
	global_load_dwordx4 v[96:99], v[124:125], off offset:256
	v_add_u32_e32 v104, 48, v148
	v_ashrrev_i32_e32 v105, 31, v104
	v_lshlrev_b64 v[104:105], 12, v[104:105]
	v_lshl_add_u64 v[106:107], s[56:57], 0, v[120:121]
	v_lshl_add_u64 v[108:109], s[50:51], 0, v[104:105]
	v_lshl_add_u64 v[106:107], v[106:107], 0, v[146:147]
	v_lshl_add_u64 v[108:109], v[108:109], 0, v[146:147]
	s_waitcnt vmcnt(2)
	v_lshlrev_b32_e32 v112, 16, v102
	v_and_b32_e32 v113, 0xffff0000, v102
	v_lshlrev_b32_e32 v110, 16, v100
	v_and_b32_e32 v111, 0xffff0000, v100
	v_lshlrev_b32_e32 v100, 16, v101
	v_and_b32_e32 v101, 0xffff0000, v101
	v_lshlrev_b32_e32 v102, 16, v103
	v_and_b32_e32 v103, 0xffff0000, v103
	s_waitcnt vmcnt(0)
	v_lshlrev_b32_e32 v114, 16, v96
	v_and_b32_e32 v115, 0xffff0000, v96
	v_lshlrev_b32_e32 v96, 16, v97
	v_and_b32_e32 v97, 0xffff0000, v97
	v_lshlrev_b32_e32 v116, 16, v98
	v_and_b32_e32 v117, 0xffff0000, v98
	v_lshlrev_b32_e32 v98, 16, v99
	v_and_b32_e32 v99, 0xffff0000, v99
	v_pk_mul_f32 v[112:113], v[112:113], s[16:17] op_sel_hi:[1,0]
	v_pk_mul_f32 v[110:111], v[110:111], s[16:17] op_sel_hi:[1,0]
	v_pk_mul_f32 v[100:101], v[100:101], s[16:17] op_sel_hi:[1,0]
	v_pk_mul_f32 v[102:103], v[102:103], s[16:17] op_sel_hi:[1,0]
	v_pk_mul_f32 v[114:115], v[114:115], s[16:17] op_sel_hi:[1,0]
	v_pk_mul_f32 v[96:97], v[96:97], s[16:17] op_sel_hi:[1,0]
	v_pk_mul_f32 v[116:117], v[116:117], s[16:17] op_sel_hi:[1,0]
	v_pk_mul_f32 v[98:99], v[98:99], s[16:17] op_sel_hi:[1,0]
	v_pk_fma_f32 v[88:89], v[88:89], 0.5, v[112:113] op_sel_hi:[1,0,1]
	v_pk_fma_f32 v[94:95], v[94:95], 0.5, v[100:101] op_sel_hi:[1,0,1]
	v_pk_fma_f32 v[92:93], v[92:93], 0.5, v[110:111] op_sel_hi:[1,0,1]
	v_pk_fma_f32 v[90:91], v[90:91], 0.5, v[102:103] op_sel_hi:[1,0,1]
	v_pk_fma_f32 v[96:97], v[86:87], 0.5, v[96:97] op_sel_hi:[1,0,1]
	v_pk_fma_f32 v[100:101], v[84:85], 0.5, v[114:115] op_sel_hi:[1,0,1]
	v_cvt_pk_bf16_f32 v84, v92, v93
	v_cvt_pk_bf16_f32 v85, v94, v95
	v_cvt_pk_bf16_f32 v86, v88, v89
	v_cvt_pk_bf16_f32 v87, v90, v91
	global_store_dwordx4 v[106:107], v[84:87], off
	v_pk_fma_f32 v[88:89], v[82:83], 0.5, v[98:99] op_sel_hi:[1,0,1]
	v_pk_fma_f32 v[82:83], v[80:81], 0.5, v[116:117] op_sel_hi:[1,0,1]
	global_load_dwordx4 v[84:87], v[108:109], off
	v_cvt_pk_bf16_f32 v80, v100, v101
	v_cvt_pk_bf16_f32 v81, v96, v97
	v_cvt_pk_bf16_f32 v82, v82, v83
	v_cvt_pk_bf16_f32 v83, v88, v89
	global_store_dwordx4 v[106:107], v[80:83], off offset:256
	global_load_dwordx4 v[80:83], v[108:109], off offset:256
	v_add_u32_e32 v88, 0x80, v148
	v_ashrrev_i32_e32 v89, 31, v88
	v_lshlrev_b64 v[88:89], 12, v[88:89]
	v_lshl_add_u64 v[90:91], s[56:57], 0, v[104:105]
	v_lshl_add_u64 v[92:93], s[50:51], 0, v[88:89]
	v_lshl_add_u64 v[90:91], v[90:91], 0, v[146:147]
	v_lshl_add_u64 v[92:93], v[92:93], 0, v[146:147]
	s_waitcnt vmcnt(2)
	v_lshlrev_b32_e32 v96, 16, v86
	v_and_b32_e32 v97, 0xffff0000, v86
	v_lshlrev_b32_e32 v94, 16, v84
	v_and_b32_e32 v95, 0xffff0000, v84
	v_lshlrev_b32_e32 v84, 16, v85
	v_and_b32_e32 v85, 0xffff0000, v85
	v_lshlrev_b32_e32 v86, 16, v87
	v_and_b32_e32 v87, 0xffff0000, v87
	s_waitcnt vmcnt(0)
	v_lshlrev_b32_e32 v98, 16, v80
	v_and_b32_e32 v99, 0xffff0000, v80
	v_lshlrev_b32_e32 v80, 16, v81
	v_and_b32_e32 v81, 0xffff0000, v81
	v_lshlrev_b32_e32 v100, 16, v82
	v_and_b32_e32 v101, 0xffff0000, v82
	v_lshlrev_b32_e32 v82, 16, v83
	v_and_b32_e32 v83, 0xffff0000, v83
	v_pk_mul_f32 v[96:97], v[96:97], s[16:17] op_sel_hi:[1,0]
	v_pk_mul_f32 v[94:95], v[94:95], s[16:17] op_sel_hi:[1,0]
	v_pk_mul_f32 v[84:85], v[84:85], s[16:17] op_sel_hi:[1,0]
	v_pk_mul_f32 v[86:87], v[86:87], s[16:17] op_sel_hi:[1,0]
	v_pk_mul_f32 v[98:99], v[98:99], s[16:17] op_sel_hi:[1,0]
	v_pk_mul_f32 v[80:81], v[80:81], s[16:17] op_sel_hi:[1,0]
	v_pk_mul_f32 v[100:101], v[100:101], s[16:17] op_sel_hi:[1,0]
	v_pk_mul_f32 v[82:83], v[82:83], s[16:17] op_sel_hi:[1,0]
	v_pk_fma_f32 v[72:73], v[72:73], 0.5, v[96:97] op_sel_hi:[1,0,1]
	v_pk_fma_f32 v[78:79], v[78:79], 0.5, v[84:85] op_sel_hi:[1,0,1]
	v_pk_fma_f32 v[76:77], v[76:77], 0.5, v[94:95] op_sel_hi:[1,0,1]
	v_pk_fma_f32 v[74:75], v[74:75], 0.5, v[86:87] op_sel_hi:[1,0,1]
	v_pk_fma_f32 v[80:81], v[70:71], 0.5, v[80:81] op_sel_hi:[1,0,1]
	v_pk_fma_f32 v[84:85], v[68:69], 0.5, v[98:99] op_sel_hi:[1,0,1]
	v_cvt_pk_bf16_f32 v68, v76, v77
	v_cvt_pk_bf16_f32 v69, v78, v79
	v_cvt_pk_bf16_f32 v70, v72, v73
	v_cvt_pk_bf16_f32 v71, v74, v75
	global_store_dwordx4 v[90:91], v[68:71], off
	v_pk_fma_f32 v[72:73], v[66:67], 0.5, v[82:83] op_sel_hi:[1,0,1]
	v_pk_fma_f32 v[66:67], v[64:65], 0.5, v[100:101] op_sel_hi:[1,0,1]
	global_load_dwordx4 v[68:71], v[92:93], off
	v_cvt_pk_bf16_f32 v64, v84, v85
	v_cvt_pk_bf16_f32 v65, v80, v81
	v_cvt_pk_bf16_f32 v66, v66, v67
	v_cvt_pk_bf16_f32 v67, v72, v73
	global_store_dwordx4 v[90:91], v[64:67], off offset:256
	global_load_dwordx4 v[64:67], v[92:93], off offset:256
	v_add_u32_e32 v72, 0x90, v148
	v_ashrrev_i32_e32 v73, 31, v72
	v_lshlrev_b64 v[72:73], 12, v[72:73]
	v_lshl_add_u64 v[74:75], s[56:57], 0, v[88:89]
	v_lshl_add_u64 v[76:77], s[50:51], 0, v[72:73]
	v_lshl_add_u64 v[74:75], v[74:75], 0, v[146:147]
	v_lshl_add_u64 v[76:77], v[76:77], 0, v[146:147]
	s_waitcnt vmcnt(2)
	v_lshlrev_b32_e32 v80, 16, v70
	v_and_b32_e32 v81, 0xffff0000, v70
	v_lshlrev_b32_e32 v78, 16, v68
	v_and_b32_e32 v79, 0xffff0000, v68
	v_lshlrev_b32_e32 v68, 16, v69
	v_and_b32_e32 v69, 0xffff0000, v69
	v_lshlrev_b32_e32 v70, 16, v71
	v_and_b32_e32 v71, 0xffff0000, v71
	s_waitcnt vmcnt(0)
	v_lshlrev_b32_e32 v82, 16, v64
	v_and_b32_e32 v83, 0xffff0000, v64
	v_lshlrev_b32_e32 v64, 16, v65
	v_and_b32_e32 v65, 0xffff0000, v65
	v_lshlrev_b32_e32 v84, 16, v66
	v_and_b32_e32 v85, 0xffff0000, v66
	v_lshlrev_b32_e32 v66, 16, v67
	v_and_b32_e32 v67, 0xffff0000, v67
	v_pk_mul_f32 v[80:81], v[80:81], s[16:17] op_sel_hi:[1,0]
	v_pk_mul_f32 v[78:79], v[78:79], s[16:17] op_sel_hi:[1,0]
	v_pk_mul_f32 v[68:69], v[68:69], s[16:17] op_sel_hi:[1,0]
	v_pk_mul_f32 v[70:71], v[70:71], s[16:17] op_sel_hi:[1,0]
	v_pk_mul_f32 v[82:83], v[82:83], s[16:17] op_sel_hi:[1,0]
	v_pk_mul_f32 v[64:65], v[64:65], s[16:17] op_sel_hi:[1,0]
	v_pk_mul_f32 v[84:85], v[84:85], s[16:17] op_sel_hi:[1,0]
	v_pk_mul_f32 v[66:67], v[66:67], s[16:17] op_sel_hi:[1,0]
	v_pk_fma_f32 v[56:57], v[56:57], 0.5, v[80:81] op_sel_hi:[1,0,1]
	v_pk_fma_f32 v[62:63], v[62:63], 0.5, v[68:69] op_sel_hi:[1,0,1]
	v_pk_fma_f32 v[60:61], v[60:61], 0.5, v[78:79] op_sel_hi:[1,0,1]
	v_pk_fma_f32 v[58:59], v[58:59], 0.5, v[70:71] op_sel_hi:[1,0,1]
	v_pk_fma_f32 v[64:65], v[54:55], 0.5, v[64:65] op_sel_hi:[1,0,1]
	v_pk_fma_f32 v[68:69], v[52:53], 0.5, v[82:83] op_sel_hi:[1,0,1]
	v_cvt_pk_bf16_f32 v52, v60, v61
	v_cvt_pk_bf16_f32 v53, v62, v63
	v_cvt_pk_bf16_f32 v54, v56, v57
	v_cvt_pk_bf16_f32 v55, v58, v59
	global_store_dwordx4 v[74:75], v[52:55], off
	v_pk_fma_f32 v[56:57], v[50:51], 0.5, v[66:67] op_sel_hi:[1,0,1]
	v_pk_fma_f32 v[50:51], v[48:49], 0.5, v[84:85] op_sel_hi:[1,0,1]
	global_load_dwordx4 v[52:55], v[76:77], off
	v_cvt_pk_bf16_f32 v48, v68, v69
	v_cvt_pk_bf16_f32 v49, v64, v65
	v_cvt_pk_bf16_f32 v50, v50, v51
	v_cvt_pk_bf16_f32 v51, v56, v57
	global_store_dwordx4 v[74:75], v[48:51], off offset:256
	global_load_dwordx4 v[48:51], v[76:77], off offset:256
	v_add_u32_e32 v56, 0xa0, v148
	v_ashrrev_i32_e32 v57, 31, v56
	v_lshlrev_b64 v[56:57], 12, v[56:57]
	v_lshl_add_u64 v[58:59], s[56:57], 0, v[72:73]
	v_lshl_add_u64 v[60:61], s[50:51], 0, v[56:57]
	v_lshl_add_u64 v[58:59], v[58:59], 0, v[146:147]
	v_lshl_add_u64 v[60:61], v[60:61], 0, v[146:147]
	s_waitcnt vmcnt(2)
	v_lshlrev_b32_e32 v64, 16, v54
	v_and_b32_e32 v65, 0xffff0000, v54
	v_lshlrev_b32_e32 v62, 16, v52
	v_and_b32_e32 v63, 0xffff0000, v52
	v_lshlrev_b32_e32 v52, 16, v53
	v_and_b32_e32 v53, 0xffff0000, v53
	v_lshlrev_b32_e32 v54, 16, v55
	v_and_b32_e32 v55, 0xffff0000, v55
	s_waitcnt vmcnt(0)
	v_lshlrev_b32_e32 v66, 16, v48
	v_and_b32_e32 v67, 0xffff0000, v48
	v_lshlrev_b32_e32 v48, 16, v49
	v_and_b32_e32 v49, 0xffff0000, v49
	v_lshlrev_b32_e32 v68, 16, v50
	v_and_b32_e32 v69, 0xffff0000, v50
	v_lshlrev_b32_e32 v50, 16, v51
	v_and_b32_e32 v51, 0xffff0000, v51
	v_pk_mul_f32 v[64:65], v[64:65], s[16:17] op_sel_hi:[1,0]
	v_pk_mul_f32 v[62:63], v[62:63], s[16:17] op_sel_hi:[1,0]
	v_pk_mul_f32 v[52:53], v[52:53], s[16:17] op_sel_hi:[1,0]
	v_pk_mul_f32 v[54:55], v[54:55], s[16:17] op_sel_hi:[1,0]
	v_pk_mul_f32 v[66:67], v[66:67], s[16:17] op_sel_hi:[1,0]
	v_pk_mul_f32 v[48:49], v[48:49], s[16:17] op_sel_hi:[1,0]
	v_pk_mul_f32 v[68:69], v[68:69], s[16:17] op_sel_hi:[1,0]
	v_pk_mul_f32 v[50:51], v[50:51], s[16:17] op_sel_hi:[1,0]
	v_pk_fma_f32 v[40:41], v[40:41], 0.5, v[64:65] op_sel_hi:[1,0,1]
	v_pk_fma_f32 v[46:47], v[46:47], 0.5, v[52:53] op_sel_hi:[1,0,1]
	v_pk_fma_f32 v[44:45], v[44:45], 0.5, v[62:63] op_sel_hi:[1,0,1]
	v_pk_fma_f32 v[42:43], v[42:43], 0.5, v[54:55] op_sel_hi:[1,0,1]
	v_pk_fma_f32 v[48:49], v[38:39], 0.5, v[48:49] op_sel_hi:[1,0,1]
	v_pk_fma_f32 v[52:53], v[36:37], 0.5, v[66:67] op_sel_hi:[1,0,1]
	v_cvt_pk_bf16_f32 v36, v44, v45
	v_cvt_pk_bf16_f32 v37, v46, v47
	v_cvt_pk_bf16_f32 v38, v40, v41
	v_cvt_pk_bf16_f32 v39, v42, v43
	global_store_dwordx4 v[58:59], v[36:39], off
	v_pk_fma_f32 v[40:41], v[34:35], 0.5, v[50:51] op_sel_hi:[1,0,1]
	v_pk_fma_f32 v[34:35], v[32:33], 0.5, v[68:69] op_sel_hi:[1,0,1]
	global_load_dwordx4 v[36:39], v[60:61], off
	v_cvt_pk_bf16_f32 v32, v52, v53
	v_cvt_pk_bf16_f32 v33, v48, v49
	v_cvt_pk_bf16_f32 v34, v34, v35
	v_cvt_pk_bf16_f32 v35, v40, v41
	global_store_dwordx4 v[58:59], v[32:35], off offset:256
	global_load_dwordx4 v[32:35], v[60:61], off offset:256
	v_add_u32_e32 v40, 0xb0, v148
	v_ashrrev_i32_e32 v41, 31, v40
	v_lshlrev_b64 v[40:41], 12, v[40:41]
	v_lshl_add_u64 v[42:43], s[56:57], 0, v[56:57]
	v_lshl_add_u64 v[44:45], s[50:51], 0, v[40:41]
	v_lshl_add_u64 v[42:43], v[42:43], 0, v[146:147]
	v_lshl_add_u64 v[44:45], v[44:45], 0, v[146:147]
	s_waitcnt vmcnt(2)
	v_lshlrev_b32_e32 v48, 16, v38
	v_and_b32_e32 v49, 0xffff0000, v38
	v_pk_mul_f32 v[48:49], v[48:49], s[16:17] op_sel_hi:[1,0]
	v_lshlrev_b32_e32 v46, 16, v36
	v_and_b32_e32 v47, 0xffff0000, v36
	v_lshlrev_b32_e32 v36, 16, v37
	s_waitcnt vmcnt(0)
	v_lshlrev_b32_e32 v50, 16, v32
	v_and_b32_e32 v51, 0xffff0000, v32
	v_lshlrev_b32_e32 v32, 16, v33
	v_and_b32_e32 v33, 0xffff0000, v33
	v_lshlrev_b32_e32 v52, 16, v34
	v_and_b32_e32 v53, 0xffff0000, v34
	v_lshlrev_b32_e32 v34, 16, v35
	v_and_b32_e32 v35, 0xffff0000, v35
	v_and_b32_e32 v37, 0xffff0000, v37
	v_lshlrev_b32_e32 v38, 16, v39
	v_and_b32_e32 v39, 0xffff0000, v39
	v_pk_mul_f32 v[32:33], v[32:33], s[16:17] op_sel_hi:[1,0]
	v_pk_mul_f32 v[52:53], v[52:53], s[16:17] op_sel_hi:[1,0]
	v_pk_mul_f32 v[34:35], v[34:35], s[16:17] op_sel_hi:[1,0]
	v_pk_fma_f32 v[24:25], v[24:25], 0.5, v[48:49] op_sel_hi:[1,0,1]
	v_pk_mul_f32 v[46:47], v[46:47], s[16:17] op_sel_hi:[1,0]
	v_pk_mul_f32 v[36:37], v[36:37], s[16:17] op_sel_hi:[1,0]
	v_pk_mul_f32 v[38:39], v[38:39], s[16:17] op_sel_hi:[1,0]
	v_pk_mul_f32 v[50:51], v[50:51], s[16:17] op_sel_hi:[1,0]
	v_pk_fma_f32 v[32:33], v[22:23], 0.5, v[32:33] op_sel_hi:[1,0,1]
	v_cvt_pk_bf16_f32 v22, v24, v25
	v_pk_fma_f32 v[24:25], v[18:19], 0.5, v[34:35] op_sel_hi:[1,0,1]
	v_pk_fma_f32 v[18:19], v[16:17], 0.5, v[52:53] op_sel_hi:[1,0,1]
	v_pk_fma_f32 v[30:31], v[30:31], 0.5, v[36:37] op_sel_hi:[1,0,1]
	v_pk_fma_f32 v[28:29], v[28:29], 0.5, v[46:47] op_sel_hi:[1,0,1]
	v_pk_fma_f32 v[26:27], v[26:27], 0.5, v[38:39] op_sel_hi:[1,0,1]
	v_pk_fma_f32 v[36:37], v[20:21], 0.5, v[50:51] op_sel_hi:[1,0,1]
	v_cvt_pk_bf16_f32 v20, v28, v29
	v_cvt_pk_bf16_f32 v21, v30, v31
	v_cvt_pk_bf16_f32 v23, v26, v27
	global_store_dwordx4 v[42:43], v[20:23], off
	v_cvt_pk_bf16_f32 v16, v36, v37
	v_cvt_pk_bf16_f32 v17, v32, v33
	v_cvt_pk_bf16_f32 v18, v18, v19
	v_cvt_pk_bf16_f32 v19, v24, v25
	global_store_dwordx4 v[42:43], v[16:19], off offset:256
	global_load_dwordx4 v[20:23], v[44:45], off
	v_lshl_add_u64 v[24:25], s[56:57], 0, v[40:41]
	global_load_dwordx4 v[16:19], v[44:45], off offset:256
	v_lshl_add_u64 v[24:25], v[24:25], 0, v[146:147]
	s_waitcnt vmcnt(1)
	v_lshlrev_b32_e32 v26, 16, v20
	v_and_b32_e32 v27, 0xffff0000, v20
	v_lshlrev_b32_e32 v20, 16, v21
	v_and_b32_e32 v21, 0xffff0000, v21
	v_lshlrev_b32_e32 v28, 16, v22
	v_and_b32_e32 v29, 0xffff0000, v22
	v_lshlrev_b32_e32 v22, 16, v23
	v_and_b32_e32 v23, 0xffff0000, v23
	s_waitcnt vmcnt(0)
	v_lshlrev_b32_e32 v30, 16, v16
	v_and_b32_e32 v31, 0xffff0000, v16
	v_lshlrev_b32_e32 v16, 16, v17
	v_and_b32_e32 v17, 0xffff0000, v17
	v_lshlrev_b32_e32 v32, 16, v18
	v_and_b32_e32 v33, 0xffff0000, v18
	v_lshlrev_b32_e32 v18, 16, v19
	v_and_b32_e32 v19, 0xffff0000, v19
	v_pk_mul_f32 v[26:27], v[26:27], s[16:17] op_sel_hi:[1,0]
	v_pk_mul_f32 v[20:21], v[20:21], s[16:17] op_sel_hi:[1,0]
	v_pk_mul_f32 v[28:29], v[28:29], s[16:17] op_sel_hi:[1,0]
	v_pk_mul_f32 v[22:23], v[22:23], s[16:17] op_sel_hi:[1,0]
	v_pk_mul_f32 v[30:31], v[30:31], s[16:17] op_sel_hi:[1,0]
	v_pk_mul_f32 v[16:17], v[16:17], s[16:17] op_sel_hi:[1,0]
	v_pk_mul_f32 v[32:33], v[32:33], s[16:17] op_sel_hi:[1,0]
	v_pk_mul_f32 v[18:19], v[18:19], s[16:17] op_sel_hi:[1,0]
	v_pk_fma_f32 v[14:15], v[14:15], 0.5, v[20:21] op_sel_hi:[1,0,1]
	v_pk_fma_f32 v[12:13], v[12:13], 0.5, v[26:27] op_sel_hi:[1,0,1]
	v_pk_fma_f32 v[10:11], v[10:11], 0.5, v[22:23] op_sel_hi:[1,0,1]
	v_pk_fma_f32 v[8:9], v[8:9], 0.5, v[28:29] op_sel_hi:[1,0,1]
	v_pk_fma_f32 v[6:7], v[6:7], 0.5, v[16:17] op_sel_hi:[1,0,1]
	v_pk_fma_f32 v[4:5], v[4:5], 0.5, v[30:31] op_sel_hi:[1,0,1]
	v_pk_fma_f32 v[16:17], v[2:3], 0.5, v[18:19] op_sel_hi:[1,0,1]
	v_pk_fma_f32 v[18:19], v[0:1], 0.5, v[32:33] op_sel_hi:[1,0,1]
	v_cvt_pk_bf16_f32 v0, v12, v13
	v_cvt_pk_bf16_f32 v1, v14, v15
	v_cvt_pk_bf16_f32 v2, v8, v9
	v_cvt_pk_bf16_f32 v3, v10, v11
	v_cvt_pk_bf16_f32 v4, v4, v5
	v_cvt_pk_bf16_f32 v5, v6, v7
	s_nop 0
	v_cvt_pk_bf16_f32 v6, v18, v19
	v_cvt_pk_bf16_f32 v7, v16, v17
	global_store_dwordx4 v[24:25], v[0:3], off
	global_store_dwordx4 v[24:25], v[4:7], off offset:256
	s_cbranch_vccnz .LBB0_327
	s_andn2_b64 vcc, exec, s[10:11]
	s_cbranch_vccnz .LBB0_326
	s_barrier
	s_branch .LBB0_326

.LBB0_497:
	s_add_u32 s26, s26, 0x80080
	s_addc_u32 s27, s27, 0
	s_add_u32 s71, s36, 0x100
	v_mov_b32_e32 v0, 0
	s_addc_u32 s72, s37, 0
	s_mov_b32 s73, -2
	v_mov_b32_e32 v1, v0
	v_mov_b32_e32 v2, v0
	v_mov_b32_e32 v3, v0
	v_mov_b32_e32 v4, v0
	v_mov_b32_e32 v5, v0
	v_mov_b32_e32 v6, v0
	v_mov_b32_e32 v7, v0
	v_mov_b32_e32 v16, v0
	v_mov_b32_e32 v17, v0
	v_mov_b32_e32 v18, v0
	v_mov_b32_e32 v19, v0
	v_mov_b32_e32 v20, v0
	v_mov_b32_e32 v21, v0
	v_mov_b32_e32 v22, v0
	v_mov_b32_e32 v23, v0
	v_mov_b32_e32 v32, v0
	v_mov_b32_e32 v33, v0
	v_mov_b32_e32 v34, v0
	v_mov_b32_e32 v35, v0
	v_mov_b32_e32 v36, v0
	v_mov_b32_e32 v37, v0
	v_mov_b32_e32 v38, v0
	v_mov_b32_e32 v39, v0
	v_mov_b32_e32 v48, v0
	v_mov_b32_e32 v49, v0
	v_mov_b32_e32 v50, v0
	v_mov_b32_e32 v51, v0
	v_mov_b32_e32 v52, v0
	v_mov_b32_e32 v53, v0
	v_mov_b32_e32 v54, v0
	v_mov_b32_e32 v55, v0
	v_mov_b32_e32 v8, v0
	v_mov_b32_e32 v9, v0
	v_mov_b32_e32 v10, v0
	v_mov_b32_e32 v11, v0
	v_mov_b32_e32 v12, v0
	v_mov_b32_e32 v13, v0
	v_mov_b32_e32 v14, v0
	v_mov_b32_e32 v15, v0
	v_mov_b32_e32 v24, v0
	v_mov_b32_e32 v25, v0
	v_mov_b32_e32 v26, v0
	v_mov_b32_e32 v27, v0
	v_mov_b32_e32 v28, v0
	v_mov_b32_e32 v29, v0
	v_mov_b32_e32 v30, v0
	v_mov_b32_e32 v31, v0
	v_mov_b32_e32 v40, v0
	v_mov_b32_e32 v41, v0
	v_mov_b32_e32 v42, v0
	v_mov_b32_e32 v43, v0
	v_mov_b32_e32 v44, v0
	v_mov_b32_e32 v45, v0
	v_mov_b32_e32 v46, v0
	v_mov_b32_e32 v47, v0
	v_mov_b32_e32 v56, v0
	v_mov_b32_e32 v57, v0
	v_mov_b32_e32 v58, v0
	v_mov_b32_e32 v59, v0
	v_mov_b32_e32 v60, v0
	v_mov_b32_e32 v61, v0
	v_mov_b32_e32 v62, v0
	v_mov_b32_e32 v63, v0
	v_mov_b32_e32 v64, v0
	v_mov_b32_e32 v65, v0
	v_mov_b32_e32 v66, v0
	v_mov_b32_e32 v67, v0
	v_mov_b32_e32 v68, v0
	v_mov_b32_e32 v69, v0
	v_mov_b32_e32 v70, v0
	v_mov_b32_e32 v71, v0
	v_mov_b32_e32 v80, v0
	v_mov_b32_e32 v81, v0
	v_mov_b32_e32 v82, v0
	v_mov_b32_e32 v83, v0
	v_mov_b32_e32 v84, v0
	v_mov_b32_e32 v85, v0
	v_mov_b32_e32 v86, v0
	v_mov_b32_e32 v87, v0
	v_mov_b32_e32 v96, v0
	v_mov_b32_e32 v97, v0
	v_mov_b32_e32 v98, v0
	v_mov_b32_e32 v99, v0
	v_mov_b32_e32 v100, v0
	v_mov_b32_e32 v101, v0
	v_mov_b32_e32 v102, v0
	v_mov_b32_e32 v103, v0
	v_mov_b32_e32 v112, v0
	v_mov_b32_e32 v113, v0
	v_mov_b32_e32 v114, v0
	v_mov_b32_e32 v115, v0
	v_mov_b32_e32 v116, v0
	v_mov_b32_e32 v117, v0
	v_mov_b32_e32 v118, v0
	v_mov_b32_e32 v119, v0
	v_mov_b32_e32 v72, v0
	v_mov_b32_e32 v73, v0
	v_mov_b32_e32 v74, v0
	v_mov_b32_e32 v75, v0
	v_mov_b32_e32 v76, v0
	v_mov_b32_e32 v77, v0
	v_mov_b32_e32 v78, v0
	v_mov_b32_e32 v79, v0
	v_mov_b32_e32 v88, v0
	v_mov_b32_e32 v89, v0
	v_mov_b32_e32 v90, v0
	v_mov_b32_e32 v91, v0
	v_mov_b32_e32 v92, v0
	v_mov_b32_e32 v93, v0
	v_mov_b32_e32 v94, v0
	v_mov_b32_e32 v95, v0
	v_mov_b32_e32 v104, v0
	v_mov_b32_e32 v105, v0
	v_mov_b32_e32 v106, v0
	v_mov_b32_e32 v107, v0
	v_mov_b32_e32 v108, v0
	v_mov_b32_e32 v109, v0
	v_mov_b32_e32 v110, v0
	v_mov_b32_e32 v111, v0
	v_mov_b32_e32 v120, v0
	v_mov_b32_e32 v121, v0
	v_mov_b32_e32 v122, v0
	v_mov_b32_e32 v123, v0
	v_mov_b32_e32 v124, v0
	v_mov_b32_e32 v125, v0
	v_mov_b32_e32 v126, v0
	v_mov_b32_e32 v127, v0
	s_cmp_eq_u64 s[18:19], 0
	s_cbranch_scc0 .Lprio_skip_3
	s_setprio 1
.Lprio_skip_3:
.LBB0_498:
	ds_read_b128 v[150:153], v165
	ds_read_b128 v[168:171], v165 offset:1024
	ds_read_b128 v[172:175], v165 offset:2048
	ds_read_b128 v[176:179], v165 offset:3072
	ds_read_b128 v[180:183], v166
	ds_read_b128 v[184:187], v166 offset:1024
	ds_read_b128 v[188:191], v166 offset:2048
	ds_read_b128 v[192:195], v166 offset:3072
	s_add_u32 s36, s26, 0xfff80080
	s_addc_u32 s37, s27, -1
	s_cmp_eq_u32 s73, 28
	s_cselect_b32 s39, s23, s37
	s_cselect_b32 s38, s22, s36
	s_cselect_b32 s37, s25, s72
	s_cselect_b32 s36, s24, s71
	v_lshl_add_u64 v[154:155], s[26:27], 0, v[142:143]
	s_add_i32 m0, s43, 0xc000
	ds_read_b128 v[196:199], v167
	ds_read_b128 v[200:203], v167 offset:1024
	ds_read_b128 v[204:207], v167 offset:2048
	ds_read_b128 v[208:211], v167 offset:3072
	ds_read_b128 v[212:215], v167 offset:4096
	ds_read_b128 v[216:219], v167 offset:5120
	ds_read_b128 v[220:223], v167 offset:6144
	ds_read_b128 v[224:227], v167 offset:7168
	global_load_lds_dwordx4 v[154:155], off
	v_lshl_add_u64 v[154:155], s[26:27], 0, v[144:145]
	s_add_i32 m0, s43, 0xe000
	s_nop 0
	global_load_lds_dwordx4 v[154:155], off
	s_waitcnt vmcnt(8)
	s_waitcnt lgkmcnt(0)
	s_barrier
	s_waitcnt lgkmcnt(0)
	v_mfma_f32_16x16x32_bf16 v[124:127], v[150:153], v[196:199], v[124:127]
	v_mfma_f32_16x16x32_bf16 v[120:123], v[172:175], v[196:199], v[120:123]
	v_mfma_f32_16x16x32_bf16 v[108:111], v[150:153], v[204:207], v[108:111]
	v_mfma_f32_16x16x32_bf16 v[104:107], v[172:175], v[204:207], v[104:107]
	v_mfma_f32_16x16x32_bf16 v[92:95], v[150:153], v[212:215], v[92:95]
	v_mfma_f32_16x16x32_bf16 v[88:91], v[172:175], v[212:215], v[88:91]
	v_mfma_f32_16x16x32_bf16 v[76:79], v[150:153], v[220:223], v[76:79]
	v_mfma_f32_16x16x32_bf16 v[72:75], v[172:175], v[220:223], v[72:75]
	v_mfma_f32_16x16x32_bf16 v[124:127], v[168:171], v[200:203], v[124:127]
	v_mfma_f32_16x16x32_bf16 v[120:123], v[176:179], v[200:203], v[120:123]
	v_mfma_f32_16x16x32_bf16 v[108:111], v[168:171], v[208:211], v[108:111]
	v_mfma_f32_16x16x32_bf16 v[104:107], v[176:179], v[208:211], v[104:107]
	v_mfma_f32_16x16x32_bf16 v[92:95], v[168:171], v[216:219], v[92:95]
	v_mfma_f32_16x16x32_bf16 v[88:91], v[176:179], v[216:219], v[88:91]
	v_mfma_f32_16x16x32_bf16 v[76:79], v[168:171], v[224:227], v[76:79]
	v_mfma_f32_16x16x32_bf16 v[72:75], v[176:179], v[224:227], v[72:75]
	v_mfma_f32_16x16x32_bf16 v[116:119], v[180:183], v[196:199], v[116:119]
	v_mfma_f32_16x16x32_bf16 v[112:115], v[188:191], v[196:199], v[112:115]
	v_mfma_f32_16x16x32_bf16 v[100:103], v[180:183], v[204:207], v[100:103]
	v_mfma_f32_16x16x32_bf16 v[96:99], v[188:191], v[204:207], v[96:99]
	v_mfma_f32_16x16x32_bf16 v[84:87], v[180:183], v[212:215], v[84:87]
	v_mfma_f32_16x16x32_bf16 v[80:83], v[188:191], v[212:215], v[80:83]
	v_mfma_f32_16x16x32_bf16 v[68:71], v[180:183], v[220:223], v[68:71]
	v_mfma_f32_16x16x32_bf16 v[64:67], v[188:191], v[220:223], v[64:67]
	v_mfma_f32_16x16x32_bf16 v[116:119], v[184:187], v[200:203], v[116:119]
	v_mfma_f32_16x16x32_bf16 v[112:115], v[192:195], v[200:203], v[112:115]
	v_mfma_f32_16x16x32_bf16 v[100:103], v[184:187], v[208:211], v[100:103]
	v_mfma_f32_16x16x32_bf16 v[96:99], v[192:195], v[208:211], v[96:99]
	v_mfma_f32_16x16x32_bf16 v[84:87], v[184:187], v[216:219], v[84:87]
	v_mfma_f32_16x16x32_bf16 v[80:83], v[192:195], v[216:219], v[80:83]
	v_mfma_f32_16x16x32_bf16 v[68:71], v[184:187], v[224:227], v[68:71]
	v_mfma_f32_16x16x32_bf16 v[64:67], v[192:195], v[224:227], v[64:67]
	s_barrier
	s_add_i32 s74, s64, s42
	v_lshl_add_u64 v[154:155], s[36:37], 0, v[130:131]
	s_mov_b32 m0, s74
	ds_read_b128 v[196:199], v167 offset:16384
	ds_read_b128 v[200:203], v167 offset:17408
	ds_read_b128 v[204:207], v167 offset:18432
	ds_read_b128 v[208:211], v167 offset:19456
	ds_read_b128 v[212:215], v167 offset:20480
	ds_read_b128 v[216:219], v167 offset:21504
	ds_read_b128 v[220:223], v167 offset:22528
	ds_read_b128 v[224:227], v167 offset:23552
	global_load_lds_dwordx4 v[154:155], off
	s_add_i32 m0, s74, 0x2000
	s_add_u32 s74, s36, 0x80000
	v_lshl_add_u64 v[228:229], s[36:37], 0, v[134:135]
	s_addc_u32 s75, s37, 0
	s_add_i32 s76, s65, s42
	global_load_lds_dwordx4 v[228:229], off
	v_lshl_add_u64 v[240:241], s[74:75], 0, v[130:131]
	s_mov_b32 m0, s76
	v_lshl_add_u64 v[242:243], s[38:39], 0, v[132:133]
	global_load_lds_dwordx4 v[240:241], off
	v_lshl_add_u64 v[240:241], s[74:75], 0, v[134:135]
	s_add_i32 m0, s76, 0x2000
	s_nop 0
	global_load_lds_dwordx4 v[240:241], off
	v_lshl_add_u64 v[240:241], s[38:39], 0, v[128:129]
	s_mov_b32 m0, s43
	s_nop 0
	global_load_lds_dwordx4 v[240:241], off
	s_mov_b32 m0, s44
	s_nop 0
	global_load_lds_dwordx4 v[242:243], off
	s_waitcnt vmcnt(8)
	s_waitcnt lgkmcnt(0)
	s_barrier
	s_waitcnt lgkmcnt(0)
	v_mfma_f32_16x16x32_bf16 v[60:63], v[150:153], v[196:199], v[60:63]
	v_mfma_f32_16x16x32_bf16 v[56:59], v[172:175], v[196:199], v[56:59]
	v_mfma_f32_16x16x32_bf16 v[44:47], v[150:153], v[204:207], v[44:47]
	v_mfma_f32_16x16x32_bf16 v[40:43], v[172:175], v[204:207], v[40:43]
	v_mfma_f32_16x16x32_bf16 v[28:31], v[150:153], v[212:215], v[28:31]
	v_mfma_f32_16x16x32_bf16 v[24:27], v[172:175], v[212:215], v[24:27]
	v_mfma_f32_16x16x32_bf16 v[12:15], v[150:153], v[220:223], v[12:15]
	v_mfma_f32_16x16x32_bf16 v[8:11], v[172:175], v[220:223], v[8:11]
	v_mfma_f32_16x16x32_bf16 v[60:63], v[168:171], v[200:203], v[60:63]
	v_mfma_f32_16x16x32_bf16 v[56:59], v[176:179], v[200:203], v[56:59]
	v_mfma_f32_16x16x32_bf16 v[44:47], v[168:171], v[208:211], v[44:47]
	v_mfma_f32_16x16x32_bf16 v[40:43], v[176:179], v[208:211], v[40:43]
	v_mfma_f32_16x16x32_bf16 v[28:31], v[168:171], v[216:219], v[28:31]
	v_mfma_f32_16x16x32_bf16 v[24:27], v[176:179], v[216:219], v[24:27]
	v_mfma_f32_16x16x32_bf16 v[12:15], v[168:171], v[224:227], v[12:15]
	v_mfma_f32_16x16x32_bf16 v[8:11], v[176:179], v[224:227], v[8:11]
	v_mfma_f32_16x16x32_bf16 v[52:55], v[180:183], v[196:199], v[52:55]
	v_mfma_f32_16x16x32_bf16 v[48:51], v[188:191], v[196:199], v[48:51]
	v_mfma_f32_16x16x32_bf16 v[36:39], v[180:183], v[204:207], v[36:39]
	v_mfma_f32_16x16x32_bf16 v[32:35], v[188:191], v[204:207], v[32:35]
	v_mfma_f32_16x16x32_bf16 v[20:23], v[180:183], v[212:215], v[20:23]
	v_mfma_f32_16x16x32_bf16 v[16:19], v[188:191], v[212:215], v[16:19]
	v_mfma_f32_16x16x32_bf16 v[4:7], v[180:183], v[220:223], v[4:7]
	v_mfma_f32_16x16x32_bf16 v[0:3], v[188:191], v[220:223], v[0:3]
	v_mfma_f32_16x16x32_bf16 v[52:55], v[184:187], v[200:203], v[52:55]
	v_mfma_f32_16x16x32_bf16 v[48:51], v[192:195], v[200:203], v[48:51]
	v_mfma_f32_16x16x32_bf16 v[36:39], v[184:187], v[208:211], v[36:39]
	v_mfma_f32_16x16x32_bf16 v[32:35], v[192:195], v[208:211], v[32:35]
	v_mfma_f32_16x16x32_bf16 v[20:23], v[184:187], v[216:219], v[20:23]
	v_mfma_f32_16x16x32_bf16 v[16:19], v[192:195], v[216:219], v[16:19]
	v_mfma_f32_16x16x32_bf16 v[4:7], v[184:187], v[224:227], v[4:7]
	v_mfma_f32_16x16x32_bf16 v[0:3], v[192:195], v[224:227], v[0:3]
	s_barrier
	s_add_i32 s74, 0, 0x18000
	v_add_u32_e32 v140, s74, v156
	s_add_i32 s75, 0, 0x1c000
	ds_read_b128 v[150:153], v140
	ds_read_b128 v[168:171], v140 offset:1024
	ds_read_b128 v[172:175], v140 offset:2048
	ds_read_b128 v[176:179], v140 offset:3072
	v_add_u32_e32 v140, s75, v156
	ds_read_b128 v[180:183], v140
	ds_read_b128 v[184:187], v140 offset:1024
	ds_read_b128 v[188:191], v140 offset:2048
	ds_read_b128 v[192:195], v140 offset:3072
	s_add_u32 s38, s38, 0x80000
	s_addc_u32 s39, s39, 0
	s_mov_b32 m0, s45
	v_lshl_add_u64 v[244:245], s[38:39], 0, v[128:129]
	ds_read_b128 v[196:199], v167 offset:32768
	ds_read_b128 v[200:203], v167 offset:33792
	ds_read_b128 v[204:207], v167 offset:34816
	ds_read_b128 v[208:211], v167 offset:35840
	ds_read_b128 v[212:215], v167 offset:36864
	ds_read_b128 v[216:219], v167 offset:37888
	ds_read_b128 v[220:223], v167 offset:38912
	ds_read_b128 v[224:227], v167 offset:39936
	global_load_lds_dwordx4 v[244:245], off
	v_lshl_add_u64 v[244:245], s[38:39], 0, v[132:133]
	s_mov_b32 m0, s46
	s_nop 0
	global_load_lds_dwordx4 v[244:245], off
	s_waitcnt vmcnt(8)
	s_waitcnt lgkmcnt(0)
	s_barrier
	s_waitcnt lgkmcnt(0)
	v_mfma_f32_16x16x32_bf16 v[124:127], v[150:153], v[196:199], v[124:127]
	v_mfma_f32_16x16x32_bf16 v[120:123], v[172:175], v[196:199], v[120:123]
	v_mfma_f32_16x16x32_bf16 v[108:111], v[150:153], v[204:207], v[108:111]
	v_mfma_f32_16x16x32_bf16 v[104:107], v[172:175], v[204:207], v[104:107]
	v_mfma_f32_16x16x32_bf16 v[92:95], v[150:153], v[212:215], v[92:95]
	v_mfma_f32_16x16x32_bf16 v[88:91], v[172:175], v[212:215], v[88:91]
	v_mfma_f32_16x16x32_bf16 v[76:79], v[150:153], v[220:223], v[76:79]
	v_mfma_f32_16x16x32_bf16 v[72:75], v[172:175], v[220:223], v[72:75]
	v_mfma_f32_16x16x32_bf16 v[124:127], v[168:171], v[200:203], v[124:127]
	v_mfma_f32_16x16x32_bf16 v[120:123], v[176:179], v[200:203], v[120:123]
	v_mfma_f32_16x16x32_bf16 v[108:111], v[168:171], v[208:211], v[108:111]
	v_mfma_f32_16x16x32_bf16 v[104:107], v[176:179], v[208:211], v[104:107]
	v_mfma_f32_16x16x32_bf16 v[92:95], v[168:171], v[216:219], v[92:95]
	v_mfma_f32_16x16x32_bf16 v[88:91], v[176:179], v[216:219], v[88:91]
	v_mfma_f32_16x16x32_bf16 v[76:79], v[168:171], v[224:227], v[76:79]
	v_mfma_f32_16x16x32_bf16 v[72:75], v[176:179], v[224:227], v[72:75]
	v_mfma_f32_16x16x32_bf16 v[116:119], v[180:183], v[196:199], v[116:119]
	v_mfma_f32_16x16x32_bf16 v[112:115], v[188:191], v[196:199], v[112:115]
	v_mfma_f32_16x16x32_bf16 v[100:103], v[180:183], v[204:207], v[100:103]
	v_mfma_f32_16x16x32_bf16 v[96:99], v[188:191], v[204:207], v[96:99]
	v_mfma_f32_16x16x32_bf16 v[84:87], v[180:183], v[212:215], v[84:87]
	v_mfma_f32_16x16x32_bf16 v[80:83], v[188:191], v[212:215], v[80:83]
	v_mfma_f32_16x16x32_bf16 v[68:71], v[180:183], v[220:223], v[68:71]
	v_mfma_f32_16x16x32_bf16 v[64:67], v[188:191], v[220:223], v[64:67]
	v_mfma_f32_16x16x32_bf16 v[116:119], v[184:187], v[200:203], v[116:119]
	v_mfma_f32_16x16x32_bf16 v[112:115], v[192:195], v[200:203], v[112:115]
	v_mfma_f32_16x16x32_bf16 v[100:103], v[184:187], v[208:211], v[100:103]
	v_mfma_f32_16x16x32_bf16 v[96:99], v[192:195], v[208:211], v[96:99]
	v_mfma_f32_16x16x32_bf16 v[84:87], v[184:187], v[216:219], v[84:87]
	v_mfma_f32_16x16x32_bf16 v[80:83], v[192:195], v[216:219], v[80:83]
	v_mfma_f32_16x16x32_bf16 v[68:71], v[184:187], v[224:227], v[68:71]
	v_mfma_f32_16x16x32_bf16 v[64:67], v[192:195], v[224:227], v[64:67]
	s_barrier
	s_add_i32 s38, s74, s42
	v_lshl_add_u64 v[154:155], v[154:155], 0, s[16:17]
	s_mov_b32 m0, s38
	ds_read_b128 v[196:199], v167 offset:49152
	ds_read_b128 v[200:203], v167 offset:50176
	ds_read_b128 v[204:207], v167 offset:51200
	ds_read_b128 v[208:211], v167 offset:52224
	ds_read_b128 v[212:215], v167 offset:53248
	ds_read_b128 v[216:219], v167 offset:54272
	ds_read_b128 v[220:223], v167 offset:55296
	ds_read_b128 v[224:227], v167 offset:56320
	global_load_lds_dwordx4 v[154:155], off
	s_add_i32 m0, s38, 0x2000
	s_add_u32 s36, s36, 0x80080
	v_lshl_add_u64 v[154:155], v[228:229], 0, s[16:17]
	s_addc_u32 s37, s37, 0
	s_add_i32 s38, s75, s42
	global_load_lds_dwordx4 v[154:155], off
	v_lshl_add_u64 v[154:155], s[36:37], 0, v[130:131]
	s_mov_b32 m0, s38
	s_nop 0
	global_load_lds_dwordx4 v[154:155], off
	v_lshl_add_u64 v[154:155], s[36:37], 0, v[134:135]
	s_add_i32 m0, s38, 0x2000
	s_nop 0
	global_load_lds_dwordx4 v[154:155], off
	v_lshl_add_u64 v[154:155], v[240:241], 0, s[16:17]
	s_mov_b32 m0, s61
	s_nop 0
	global_load_lds_dwordx4 v[154:155], off
	v_lshl_add_u64 v[154:155], v[242:243], 0, s[16:17]
	s_mov_b32 m0, s62
	s_nop 0
	global_load_lds_dwordx4 v[154:155], off
	s_waitcnt vmcnt(8)
	s_waitcnt lgkmcnt(0)
	s_barrier
	s_waitcnt lgkmcnt(0)
	v_mfma_f32_16x16x32_bf16 v[60:63], v[150:153], v[196:199], v[60:63]
	v_mfma_f32_16x16x32_bf16 v[56:59], v[172:175], v[196:199], v[56:59]
	v_mfma_f32_16x16x32_bf16 v[44:47], v[150:153], v[204:207], v[44:47]
	v_mfma_f32_16x16x32_bf16 v[40:43], v[172:175], v[204:207], v[40:43]
	v_mfma_f32_16x16x32_bf16 v[28:31], v[150:153], v[212:215], v[28:31]
	v_mfma_f32_16x16x32_bf16 v[24:27], v[172:175], v[212:215], v[24:27]
	v_mfma_f32_16x16x32_bf16 v[12:15], v[150:153], v[220:223], v[12:15]
	v_mfma_f32_16x16x32_bf16 v[8:11], v[172:175], v[220:223], v[8:11]
	v_mfma_f32_16x16x32_bf16 v[60:63], v[168:171], v[200:203], v[60:63]
	v_mfma_f32_16x16x32_bf16 v[56:59], v[176:179], v[200:203], v[56:59]
	v_mfma_f32_16x16x32_bf16 v[44:47], v[168:171], v[208:211], v[44:47]
	v_mfma_f32_16x16x32_bf16 v[40:43], v[176:179], v[208:211], v[40:43]
	v_mfma_f32_16x16x32_bf16 v[28:31], v[168:171], v[216:219], v[28:31]
	v_mfma_f32_16x16x32_bf16 v[24:27], v[176:179], v[216:219], v[24:27]
	v_mfma_f32_16x16x32_bf16 v[12:15], v[168:171], v[224:227], v[12:15]
	v_mfma_f32_16x16x32_bf16 v[8:11], v[176:179], v[224:227], v[8:11]
	v_mfma_f32_16x16x32_bf16 v[52:55], v[180:183], v[196:199], v[52:55]
	v_mfma_f32_16x16x32_bf16 v[48:51], v[188:191], v[196:199], v[48:51]
	v_mfma_f32_16x16x32_bf16 v[36:39], v[180:183], v[204:207], v[36:39]
	v_mfma_f32_16x16x32_bf16 v[32:35], v[188:191], v[204:207], v[32:35]
	v_mfma_f32_16x16x32_bf16 v[20:23], v[180:183], v[212:215], v[20:23]
	v_mfma_f32_16x16x32_bf16 v[16:19], v[188:191], v[212:215], v[16:19]
	v_mfma_f32_16x16x32_bf16 v[4:7], v[180:183], v[220:223], v[4:7]
	v_mfma_f32_16x16x32_bf16 v[0:3], v[188:191], v[220:223], v[0:3]
	v_mfma_f32_16x16x32_bf16 v[52:55], v[184:187], v[200:203], v[52:55]
	v_mfma_f32_16x16x32_bf16 v[48:51], v[192:195], v[200:203], v[48:51]
	v_mfma_f32_16x16x32_bf16 v[36:39], v[184:187], v[208:211], v[36:39]
	v_mfma_f32_16x16x32_bf16 v[32:35], v[192:195], v[208:211], v[32:35]
	v_mfma_f32_16x16x32_bf16 v[20:23], v[184:187], v[216:219], v[20:23]
	v_mfma_f32_16x16x32_bf16 v[16:19], v[192:195], v[216:219], v[16:19]
	v_mfma_f32_16x16x32_bf16 v[4:7], v[184:187], v[224:227], v[4:7]
	v_mfma_f32_16x16x32_bf16 v[0:3], v[192:195], v[224:227], v[0:3]
	s_barrier
	s_add_i32 s73, s73, 2
	s_add_u32 s26, s26, 0x100
	s_addc_u32 s27, s27, 0
	s_add_u32 s71, s71, 0x100
	s_addc_u32 s72, s72, 0
	s_cmp_gt_u32 s73, 29
	s_cbranch_scc0 .LBB0_498
	s_and_b64 vcc, exec, s[18:19]
	s_cbranch_vccz .LBB0_501
	s_barrier
.LBB0_501:
	s_setprio 0
	v_add_u32_e32 v150, s70, v137
	v_cmp_gt_i32_e32 vcc, s66, v150
	s_and_saveexec_b64 s[26:27], vcc
	s_cbranch_execz .LBB0_513
	s_cmp_lt_i32 s58, 14
	v_ashrrev_i32_e32 v151, 31, v150
	s_mov_b64 s[36:37], -1
	s_cbranch_scc1 .LBB0_504
	v_mul_f32_e32 v140, 0xbfb8aa3b, v116
	v_exp_f32_e32 v140, v140
	v_lshlrev_b64 v[168:169], 12, v[150:151]
	v_mul_f32_e32 v151, 0xbfb8aa3b, v117
	v_mul_f32_e32 v152, 0xbfb8aa3b, v118
	v_mul_f32_e32 v153, 0xbfb8aa3b, v119
	v_exp_f32_e32 v151, v151
	v_exp_f32_e32 v152, v152
	v_exp_f32_e32 v153, v153
	v_add_f32_e32 v140, 1.0, v140
	v_rcp_f32_e32 v170, v140
	v_add_f32_e32 v140, 1.0, v151
	v_add_f32_e32 v152, 1.0, v152
	v_add_f32_e32 v153, 1.0, v153
	v_rcp_f32_e32 v171, v140
	v_mul_f32_e32 v140, 0xbfb8aa3b, v112
	v_rcp_f32_e32 v152, v152
	v_rcp_f32_e32 v153, v153
	v_exp_f32_e32 v151, v140
	v_mul_f32_e32 v172, 0xbfb8aa3b, v115
	v_exp_f32_e32 v173, v172
	v_pk_mul_f32 v[154:155], v[126:127], v[152:153]
	v_pk_mul_f32 v[152:153], v[124:125], v[170:171]
	v_add_f32_e32 v151, 1.0, v151
	v_mul_f32_e32 v171, 0xbfb8aa3b, v114
	v_rcp_f32_e32 v170, v151
	v_mul_f32_e32 v151, 0xbfb8aa3b, v113
	v_exp_f32_e32 v171, v171
	v_exp_f32_e32 v151, v151
	v_lshl_add_u32 v140, s58, 7, v158
	v_lshl_add_u64 v[168:169], s[14:15], 0, v[168:169]
	v_add_f32_e32 v171, 1.0, v171
	v_add_f32_e32 v151, 1.0, v151
	v_rcp_f32_e32 v172, v171
	v_add_f32_e32 v171, 1.0, v173
	v_rcp_f32_e32 v173, v171
	v_rcp_f32_e32 v171, v151
	v_lshl_add_u64 v[168:169], v[140:141], 2, v[168:169]
	global_store_dwordx4 v[168:169], v[152:155], off
	s_mov_b64 s[36:37], 0
	s_nop 0
	v_pk_mul_f32 v[154:155], v[122:123], v[172:173]
	v_pk_mul_f32 v[152:153], v[120:121], v[170:171]
	global_store_dwordx4 v[168:169], v[152:155], off offset:16

.LBB0_774:
	s_add_u32 s8, s8, 0x18080
	s_addc_u32 s9, s9, 0
	s_add_u32 s41, s10, 0x100
	v_mov_b32_e32 v0, 0
	s_addc_u32 s42, s11, 0
	s_mov_b32 s43, -2
	v_mov_b32_e32 v1, v0
	v_mov_b32_e32 v2, v0
	v_mov_b32_e32 v3, v0
	v_mov_b32_e32 v4, v0
	v_mov_b32_e32 v5, v0
	v_mov_b32_e32 v6, v0
	v_mov_b32_e32 v7, v0
	v_mov_b32_e32 v16, v0
	v_mov_b32_e32 v17, v0
	v_mov_b32_e32 v18, v0
	v_mov_b32_e32 v19, v0
	v_mov_b32_e32 v20, v0
	v_mov_b32_e32 v21, v0
	v_mov_b32_e32 v22, v0
	v_mov_b32_e32 v23, v0
	v_mov_b32_e32 v32, v0
	v_mov_b32_e32 v33, v0
	v_mov_b32_e32 v34, v0
	v_mov_b32_e32 v35, v0
	v_mov_b32_e32 v36, v0
	v_mov_b32_e32 v37, v0
	v_mov_b32_e32 v38, v0
	v_mov_b32_e32 v39, v0
	v_mov_b32_e32 v48, v0
	v_mov_b32_e32 v49, v0
	v_mov_b32_e32 v50, v0
	v_mov_b32_e32 v51, v0
	v_mov_b32_e32 v52, v0
	v_mov_b32_e32 v53, v0
	v_mov_b32_e32 v54, v0
	v_mov_b32_e32 v55, v0
	v_mov_b32_e32 v8, v0
	v_mov_b32_e32 v9, v0
	v_mov_b32_e32 v10, v0
	v_mov_b32_e32 v11, v0
	v_mov_b32_e32 v12, v0
	v_mov_b32_e32 v13, v0
	v_mov_b32_e32 v14, v0
	v_mov_b32_e32 v15, v0
	v_mov_b32_e32 v24, v0
	v_mov_b32_e32 v25, v0
	v_mov_b32_e32 v26, v0
	v_mov_b32_e32 v27, v0
	v_mov_b32_e32 v28, v0
	v_mov_b32_e32 v29, v0
	v_mov_b32_e32 v30, v0
	v_mov_b32_e32 v31, v0
	v_mov_b32_e32 v40, v0
	v_mov_b32_e32 v41, v0
	v_mov_b32_e32 v42, v0
	v_mov_b32_e32 v43, v0
	v_mov_b32_e32 v44, v0
	v_mov_b32_e32 v45, v0
	v_mov_b32_e32 v46, v0
	v_mov_b32_e32 v47, v0
	v_mov_b32_e32 v56, v0
	v_mov_b32_e32 v57, v0
	v_mov_b32_e32 v58, v0
	v_mov_b32_e32 v59, v0
	v_mov_b32_e32 v60, v0
	v_mov_b32_e32 v61, v0
	v_mov_b32_e32 v62, v0
	v_mov_b32_e32 v63, v0
	v_mov_b32_e32 v64, v0
	v_mov_b32_e32 v65, v0
	v_mov_b32_e32 v66, v0
	v_mov_b32_e32 v67, v0
	v_mov_b32_e32 v68, v0
	v_mov_b32_e32 v69, v0
	v_mov_b32_e32 v70, v0
	v_mov_b32_e32 v71, v0
	v_mov_b32_e32 v80, v0
	v_mov_b32_e32 v81, v0
	v_mov_b32_e32 v82, v0
	v_mov_b32_e32 v83, v0
	v_mov_b32_e32 v84, v0
	v_mov_b32_e32 v85, v0
	v_mov_b32_e32 v86, v0
	v_mov_b32_e32 v87, v0
	v_mov_b32_e32 v96, v0
	v_mov_b32_e32 v97, v0
	v_mov_b32_e32 v98, v0
	v_mov_b32_e32 v99, v0
	v_mov_b32_e32 v100, v0
	v_mov_b32_e32 v101, v0
	v_mov_b32_e32 v102, v0
	v_mov_b32_e32 v103, v0
	v_mov_b32_e32 v112, v0
	v_mov_b32_e32 v113, v0
	v_mov_b32_e32 v114, v0
	v_mov_b32_e32 v115, v0
	v_mov_b32_e32 v116, v0
	v_mov_b32_e32 v117, v0
	v_mov_b32_e32 v118, v0
	v_mov_b32_e32 v119, v0
	v_mov_b32_e32 v72, v0
	v_mov_b32_e32 v73, v0
	v_mov_b32_e32 v74, v0
	v_mov_b32_e32 v75, v0
	v_mov_b32_e32 v76, v0
	v_mov_b32_e32 v77, v0
	v_mov_b32_e32 v78, v0
	v_mov_b32_e32 v79, v0
	v_mov_b32_e32 v88, v0
	v_mov_b32_e32 v89, v0
	v_mov_b32_e32 v90, v0
	v_mov_b32_e32 v91, v0
	v_mov_b32_e32 v92, v0
	v_mov_b32_e32 v93, v0
	v_mov_b32_e32 v94, v0
	v_mov_b32_e32 v95, v0
	v_mov_b32_e32 v104, v0
	v_mov_b32_e32 v105, v0
	v_mov_b32_e32 v106, v0
	v_mov_b32_e32 v107, v0
	v_mov_b32_e32 v108, v0
	v_mov_b32_e32 v109, v0
	v_mov_b32_e32 v110, v0
	v_mov_b32_e32 v111, v0
	v_mov_b32_e32 v120, v0
	v_mov_b32_e32 v121, v0
	v_mov_b32_e32 v122, v0
	v_mov_b32_e32 v123, v0
	v_mov_b32_e32 v124, v0
	v_mov_b32_e32 v125, v0
	v_mov_b32_e32 v126, v0
	v_mov_b32_e32 v127, v0
	s_cmp_eq_u64 s[24:25], 0
	s_cbranch_scc0 .Lprio_skip_4
	s_setprio 1
.Lprio_skip_4:
.LBB0_775:
	ds_read_b128 v[128:131], v172
	ds_read_b128 v[132:135], v172 offset:1024
	ds_read_b128 v[158:161], v172 offset:2048
	ds_read_b128 v[176:179], v172 offset:3072
	ds_read_b128 v[180:183], v173
	ds_read_b128 v[184:187], v173 offset:1024
	ds_read_b128 v[188:191], v173 offset:2048
	ds_read_b128 v[192:195], v173 offset:3072
	s_add_u32 s10, s8, 0xfffe8080
	s_addc_u32 s11, s9, -1
	s_cmp_eq_u32 s43, 2
	s_cselect_b32 s39, s27, s11
	s_cselect_b32 s38, s26, s10
	s_cselect_b32 s11, s37, s42
	s_cselect_b32 s10, s36, s41
	v_lshl_add_u64 v[162:163], s[8:9], 0, v[150:151]
	s_add_i32 m0, s58, 0xc000
	ds_read_b128 v[196:199], v174
	ds_read_b128 v[200:203], v174 offset:1024
	ds_read_b128 v[204:207], v174 offset:2048
	ds_read_b128 v[208:211], v174 offset:3072
	ds_read_b128 v[212:215], v174 offset:4096
	ds_read_b128 v[216:219], v174 offset:5120
	ds_read_b128 v[220:223], v174 offset:6144
	ds_read_b128 v[224:227], v174 offset:7168
	global_load_lds_dwordx4 v[162:163], off
	v_lshl_add_u64 v[162:163], s[8:9], 0, v[152:153]
	s_add_i32 m0, s58, 0xe000
	s_nop 0
	global_load_lds_dwordx4 v[162:163], off
	s_waitcnt vmcnt(8)
	s_waitcnt lgkmcnt(0)
	s_barrier
	s_waitcnt lgkmcnt(0)
	v_mfma_f32_16x16x32_bf16 v[124:127], v[128:131], v[196:199], v[124:127]
	v_mfma_f32_16x16x32_bf16 v[120:123], v[158:161], v[196:199], v[120:123]
	v_mfma_f32_16x16x32_bf16 v[108:111], v[128:131], v[204:207], v[108:111]
	v_mfma_f32_16x16x32_bf16 v[104:107], v[158:161], v[204:207], v[104:107]
	v_mfma_f32_16x16x32_bf16 v[92:95], v[128:131], v[212:215], v[92:95]
	v_mfma_f32_16x16x32_bf16 v[88:91], v[158:161], v[212:215], v[88:91]
	v_mfma_f32_16x16x32_bf16 v[76:79], v[128:131], v[220:223], v[76:79]
	v_mfma_f32_16x16x32_bf16 v[72:75], v[158:161], v[220:223], v[72:75]
	v_mfma_f32_16x16x32_bf16 v[124:127], v[132:135], v[200:203], v[124:127]
	v_mfma_f32_16x16x32_bf16 v[120:123], v[176:179], v[200:203], v[120:123]
	v_mfma_f32_16x16x32_bf16 v[108:111], v[132:135], v[208:211], v[108:111]
	v_mfma_f32_16x16x32_bf16 v[104:107], v[176:179], v[208:211], v[104:107]
	v_mfma_f32_16x16x32_bf16 v[92:95], v[132:135], v[216:219], v[92:95]
	v_mfma_f32_16x16x32_bf16 v[88:91], v[176:179], v[216:219], v[88:91]
	v_mfma_f32_16x16x32_bf16 v[76:79], v[132:135], v[224:227], v[76:79]
	v_mfma_f32_16x16x32_bf16 v[72:75], v[176:179], v[224:227], v[72:75]
	v_mfma_f32_16x16x32_bf16 v[116:119], v[180:183], v[196:199], v[116:119]
	v_mfma_f32_16x16x32_bf16 v[112:115], v[188:191], v[196:199], v[112:115]
	v_mfma_f32_16x16x32_bf16 v[100:103], v[180:183], v[204:207], v[100:103]
	v_mfma_f32_16x16x32_bf16 v[96:99], v[188:191], v[204:207], v[96:99]
	v_mfma_f32_16x16x32_bf16 v[84:87], v[180:183], v[212:215], v[84:87]
	v_mfma_f32_16x16x32_bf16 v[80:83], v[188:191], v[212:215], v[80:83]
	v_mfma_f32_16x16x32_bf16 v[68:71], v[180:183], v[220:223], v[68:71]
	v_mfma_f32_16x16x32_bf16 v[64:67], v[188:191], v[220:223], v[64:67]
	v_mfma_f32_16x16x32_bf16 v[116:119], v[184:187], v[200:203], v[116:119]
	v_mfma_f32_16x16x32_bf16 v[112:115], v[192:195], v[200:203], v[112:115]
	v_mfma_f32_16x16x32_bf16 v[100:103], v[184:187], v[208:211], v[100:103]
	v_mfma_f32_16x16x32_bf16 v[96:99], v[192:195], v[208:211], v[96:99]
	v_mfma_f32_16x16x32_bf16 v[84:87], v[184:187], v[216:219], v[84:87]
	v_mfma_f32_16x16x32_bf16 v[80:83], v[192:195], v[216:219], v[80:83]
	v_mfma_f32_16x16x32_bf16 v[68:71], v[184:187], v[224:227], v[68:71]
	v_mfma_f32_16x16x32_bf16 v[64:67], v[192:195], v[224:227], v[64:67]
	s_barrier
	s_add_i32 s76, s68, s47
	v_lshl_add_u64 v[162:163], s[10:11], 0, v[142:143]
	s_mov_b32 m0, s76
	ds_read_b128 v[196:199], v174 offset:16384
	ds_read_b128 v[200:203], v174 offset:17408
	ds_read_b128 v[204:207], v174 offset:18432
	ds_read_b128 v[208:211], v174 offset:19456
	ds_read_b128 v[212:215], v174 offset:20480
	ds_read_b128 v[216:219], v174 offset:21504
	ds_read_b128 v[220:223], v174 offset:22528
	ds_read_b128 v[224:227], v174 offset:23552
	global_load_lds_dwordx4 v[162:163], off
	s_add_i32 m0, s76, 0x2000
	s_add_u32 s76, s10, 0x18000
	v_lshl_add_u64 v[228:229], s[10:11], 0, v[146:147]
	s_addc_u32 s77, s11, 0
	s_add_i32 s78, s69, s47
	global_load_lds_dwordx4 v[228:229], off
	v_lshl_add_u64 v[240:241], s[76:77], 0, v[142:143]
	s_mov_b32 m0, s78
	v_lshl_add_u64 v[242:243], s[38:39], 0, v[144:145]
	global_load_lds_dwordx4 v[240:241], off
	v_lshl_add_u64 v[240:241], s[76:77], 0, v[146:147]
	s_add_i32 m0, s78, 0x2000
	s_nop 0
	global_load_lds_dwordx4 v[240:241], off
	v_lshl_add_u64 v[240:241], s[38:39], 0, v[140:141]
	s_mov_b32 m0, s58
	s_nop 0
	global_load_lds_dwordx4 v[240:241], off
	s_mov_b32 m0, s59
	s_nop 0
	global_load_lds_dwordx4 v[242:243], off
	s_waitcnt vmcnt(8)
	s_waitcnt lgkmcnt(0)
	s_barrier
	s_waitcnt lgkmcnt(0)
	v_mfma_f32_16x16x32_bf16 v[60:63], v[128:131], v[196:199], v[60:63]
	v_mfma_f32_16x16x32_bf16 v[56:59], v[158:161], v[196:199], v[56:59]
	v_mfma_f32_16x16x32_bf16 v[44:47], v[128:131], v[204:207], v[44:47]
	v_mfma_f32_16x16x32_bf16 v[40:43], v[158:161], v[204:207], v[40:43]
	v_mfma_f32_16x16x32_bf16 v[28:31], v[128:131], v[212:215], v[28:31]
	v_mfma_f32_16x16x32_bf16 v[24:27], v[158:161], v[212:215], v[24:27]
	v_mfma_f32_16x16x32_bf16 v[12:15], v[128:131], v[220:223], v[12:15]
	v_mfma_f32_16x16x32_bf16 v[8:11], v[158:161], v[220:223], v[8:11]
	v_mfma_f32_16x16x32_bf16 v[60:63], v[132:135], v[200:203], v[60:63]
	v_mfma_f32_16x16x32_bf16 v[56:59], v[176:179], v[200:203], v[56:59]
	v_mfma_f32_16x16x32_bf16 v[44:47], v[132:135], v[208:211], v[44:47]
	v_mfma_f32_16x16x32_bf16 v[40:43], v[176:179], v[208:211], v[40:43]
	v_mfma_f32_16x16x32_bf16 v[28:31], v[132:135], v[216:219], v[28:31]
	v_mfma_f32_16x16x32_bf16 v[24:27], v[176:179], v[216:219], v[24:27]
	v_mfma_f32_16x16x32_bf16 v[12:15], v[132:135], v[224:227], v[12:15]
	v_mfma_f32_16x16x32_bf16 v[8:11], v[176:179], v[224:227], v[8:11]
	v_mfma_f32_16x16x32_bf16 v[52:55], v[180:183], v[196:199], v[52:55]
	v_mfma_f32_16x16x32_bf16 v[48:51], v[188:191], v[196:199], v[48:51]
	v_mfma_f32_16x16x32_bf16 v[36:39], v[180:183], v[204:207], v[36:39]
	v_mfma_f32_16x16x32_bf16 v[32:35], v[188:191], v[204:207], v[32:35]
	v_mfma_f32_16x16x32_bf16 v[20:23], v[180:183], v[212:215], v[20:23]
	v_mfma_f32_16x16x32_bf16 v[16:19], v[188:191], v[212:215], v[16:19]
	v_mfma_f32_16x16x32_bf16 v[4:7], v[180:183], v[220:223], v[4:7]
	v_mfma_f32_16x16x32_bf16 v[0:3], v[188:191], v[220:223], v[0:3]
	v_mfma_f32_16x16x32_bf16 v[52:55], v[184:187], v[200:203], v[52:55]
	v_mfma_f32_16x16x32_bf16 v[48:51], v[192:195], v[200:203], v[48:51]
	v_mfma_f32_16x16x32_bf16 v[36:39], v[184:187], v[208:211], v[36:39]
	v_mfma_f32_16x16x32_bf16 v[32:35], v[192:195], v[208:211], v[32:35]
	v_mfma_f32_16x16x32_bf16 v[20:23], v[184:187], v[216:219], v[20:23]
	v_mfma_f32_16x16x32_bf16 v[16:19], v[192:195], v[216:219], v[16:19]
	v_mfma_f32_16x16x32_bf16 v[4:7], v[184:187], v[224:227], v[4:7]
	v_mfma_f32_16x16x32_bf16 v[0:3], v[192:195], v[224:227], v[0:3]
	s_barrier
	s_add_i32 s76, 0, 0x18000
	v_add_u32_e32 v148, s76, v164
	s_add_i32 s77, 0, 0x1c000
	ds_read_b128 v[128:131], v148
	ds_read_b128 v[132:135], v148 offset:1024
	ds_read_b128 v[158:161], v148 offset:2048
	ds_read_b128 v[176:179], v148 offset:3072
	v_add_u32_e32 v148, s77, v164
	ds_read_b128 v[180:183], v148
	ds_read_b128 v[184:187], v148 offset:1024
	ds_read_b128 v[188:191], v148 offset:2048
	ds_read_b128 v[192:195], v148 offset:3072
	s_add_u32 s38, s38, 0x18000
	s_addc_u32 s39, s39, 0
	s_mov_b32 m0, s60
	v_lshl_add_u64 v[244:245], s[38:39], 0, v[140:141]
	ds_read_b128 v[196:199], v174 offset:32768
	ds_read_b128 v[200:203], v174 offset:33792
	ds_read_b128 v[204:207], v174 offset:34816
	ds_read_b128 v[208:211], v174 offset:35840
	ds_read_b128 v[212:215], v174 offset:36864
	ds_read_b128 v[216:219], v174 offset:37888
	ds_read_b128 v[220:223], v174 offset:38912
	ds_read_b128 v[224:227], v174 offset:39936
	global_load_lds_dwordx4 v[244:245], off
	v_lshl_add_u64 v[244:245], s[38:39], 0, v[144:145]
	s_mov_b32 m0, s61
	s_nop 0
	global_load_lds_dwordx4 v[244:245], off
	s_waitcnt vmcnt(8)
	s_waitcnt lgkmcnt(0)
	s_barrier
	s_waitcnt lgkmcnt(0)
	v_mfma_f32_16x16x32_bf16 v[124:127], v[128:131], v[196:199], v[124:127]
	v_mfma_f32_16x16x32_bf16 v[120:123], v[158:161], v[196:199], v[120:123]
	v_mfma_f32_16x16x32_bf16 v[108:111], v[128:131], v[204:207], v[108:111]
	v_mfma_f32_16x16x32_bf16 v[104:107], v[158:161], v[204:207], v[104:107]
	v_mfma_f32_16x16x32_bf16 v[92:95], v[128:131], v[212:215], v[92:95]
	v_mfma_f32_16x16x32_bf16 v[88:91], v[158:161], v[212:215], v[88:91]
	v_mfma_f32_16x16x32_bf16 v[76:79], v[128:131], v[220:223], v[76:79]
	v_mfma_f32_16x16x32_bf16 v[72:75], v[158:161], v[220:223], v[72:75]
	v_mfma_f32_16x16x32_bf16 v[124:127], v[132:135], v[200:203], v[124:127]
	v_mfma_f32_16x16x32_bf16 v[120:123], v[176:179], v[200:203], v[120:123]
	v_mfma_f32_16x16x32_bf16 v[108:111], v[132:135], v[208:211], v[108:111]
	v_mfma_f32_16x16x32_bf16 v[104:107], v[176:179], v[208:211], v[104:107]
	v_mfma_f32_16x16x32_bf16 v[92:95], v[132:135], v[216:219], v[92:95]
	v_mfma_f32_16x16x32_bf16 v[88:91], v[176:179], v[216:219], v[88:91]
	v_mfma_f32_16x16x32_bf16 v[76:79], v[132:135], v[224:227], v[76:79]
	v_mfma_f32_16x16x32_bf16 v[72:75], v[176:179], v[224:227], v[72:75]
	v_mfma_f32_16x16x32_bf16 v[116:119], v[180:183], v[196:199], v[116:119]
	v_mfma_f32_16x16x32_bf16 v[112:115], v[188:191], v[196:199], v[112:115]
	v_mfma_f32_16x16x32_bf16 v[100:103], v[180:183], v[204:207], v[100:103]
	v_mfma_f32_16x16x32_bf16 v[96:99], v[188:191], v[204:207], v[96:99]
	v_mfma_f32_16x16x32_bf16 v[84:87], v[180:183], v[212:215], v[84:87]
	v_mfma_f32_16x16x32_bf16 v[80:83], v[188:191], v[212:215], v[80:83]
	v_mfma_f32_16x16x32_bf16 v[68:71], v[180:183], v[220:223], v[68:71]
	v_mfma_f32_16x16x32_bf16 v[64:67], v[188:191], v[220:223], v[64:67]
	v_mfma_f32_16x16x32_bf16 v[116:119], v[184:187], v[200:203], v[116:119]
	v_mfma_f32_16x16x32_bf16 v[112:115], v[192:195], v[200:203], v[112:115]
	v_mfma_f32_16x16x32_bf16 v[100:103], v[184:187], v[208:211], v[100:103]
	v_mfma_f32_16x16x32_bf16 v[96:99], v[192:195], v[208:211], v[96:99]
	v_mfma_f32_16x16x32_bf16 v[84:87], v[184:187], v[216:219], v[84:87]
	v_mfma_f32_16x16x32_bf16 v[80:83], v[192:195], v[216:219], v[80:83]
	v_mfma_f32_16x16x32_bf16 v[68:71], v[184:187], v[224:227], v[68:71]
	v_mfma_f32_16x16x32_bf16 v[64:67], v[192:195], v[224:227], v[64:67]
	s_barrier
	s_add_i32 s38, s76, s47
	v_lshl_add_u64 v[162:163], v[162:163], 0, s[22:23]
	s_mov_b32 m0, s38
	ds_read_b128 v[196:199], v174 offset:49152
	ds_read_b128 v[200:203], v174 offset:50176
	ds_read_b128 v[204:207], v174 offset:51200
	ds_read_b128 v[208:211], v174 offset:52224
	ds_read_b128 v[212:215], v174 offset:53248
	ds_read_b128 v[216:219], v174 offset:54272
	ds_read_b128 v[220:223], v174 offset:55296
	ds_read_b128 v[224:227], v174 offset:56320
	global_load_lds_dwordx4 v[162:163], off
	s_add_i32 m0, s38, 0x2000
	s_add_u32 s10, s10, 0x18080
	v_lshl_add_u64 v[162:163], v[228:229], 0, s[22:23]
	s_addc_u32 s11, s11, 0
	s_add_i32 s38, s77, s47
	global_load_lds_dwordx4 v[162:163], off
	v_lshl_add_u64 v[162:163], s[10:11], 0, v[142:143]
	s_mov_b32 m0, s38
	s_nop 0
	global_load_lds_dwordx4 v[162:163], off
	v_lshl_add_u64 v[162:163], s[10:11], 0, v[146:147]
	s_add_i32 m0, s38, 0x2000
	s_nop 0
	global_load_lds_dwordx4 v[162:163], off
	v_lshl_add_u64 v[162:163], v[240:241], 0, s[22:23]
	s_mov_b32 m0, s65
	s_nop 0
	global_load_lds_dwordx4 v[162:163], off
	v_lshl_add_u64 v[162:163], v[242:243], 0, s[22:23]
	s_mov_b32 m0, s66
	s_nop 0
	global_load_lds_dwordx4 v[162:163], off
	s_waitcnt vmcnt(8)
	s_waitcnt lgkmcnt(0)
	s_barrier
	s_waitcnt lgkmcnt(0)
	v_mfma_f32_16x16x32_bf16 v[60:63], v[128:131], v[196:199], v[60:63]
	v_mfma_f32_16x16x32_bf16 v[56:59], v[158:161], v[196:199], v[56:59]
	v_mfma_f32_16x16x32_bf16 v[44:47], v[128:131], v[204:207], v[44:47]
	v_mfma_f32_16x16x32_bf16 v[40:43], v[158:161], v[204:207], v[40:43]
	v_mfma_f32_16x16x32_bf16 v[28:31], v[128:131], v[212:215], v[28:31]
	v_mfma_f32_16x16x32_bf16 v[24:27], v[158:161], v[212:215], v[24:27]
	v_mfma_f32_16x16x32_bf16 v[12:15], v[128:131], v[220:223], v[12:15]
	v_mfma_f32_16x16x32_bf16 v[8:11], v[158:161], v[220:223], v[8:11]
	v_mfma_f32_16x16x32_bf16 v[60:63], v[132:135], v[200:203], v[60:63]
	v_mfma_f32_16x16x32_bf16 v[56:59], v[176:179], v[200:203], v[56:59]
	v_mfma_f32_16x16x32_bf16 v[44:47], v[132:135], v[208:211], v[44:47]
	v_mfma_f32_16x16x32_bf16 v[40:43], v[176:179], v[208:211], v[40:43]
	v_mfma_f32_16x16x32_bf16 v[28:31], v[132:135], v[216:219], v[28:31]
	v_mfma_f32_16x16x32_bf16 v[24:27], v[176:179], v[216:219], v[24:27]
	v_mfma_f32_16x16x32_bf16 v[12:15], v[132:135], v[224:227], v[12:15]
	v_mfma_f32_16x16x32_bf16 v[8:11], v[176:179], v[224:227], v[8:11]
	v_mfma_f32_16x16x32_bf16 v[52:55], v[180:183], v[196:199], v[52:55]
	v_mfma_f32_16x16x32_bf16 v[48:51], v[188:191], v[196:199], v[48:51]
	v_mfma_f32_16x16x32_bf16 v[36:39], v[180:183], v[204:207], v[36:39]
	v_mfma_f32_16x16x32_bf16 v[32:35], v[188:191], v[204:207], v[32:35]
	v_mfma_f32_16x16x32_bf16 v[20:23], v[180:183], v[212:215], v[20:23]
	v_mfma_f32_16x16x32_bf16 v[16:19], v[188:191], v[212:215], v[16:19]
	v_mfma_f32_16x16x32_bf16 v[4:7], v[180:183], v[220:223], v[4:7]
	v_mfma_f32_16x16x32_bf16 v[0:3], v[188:191], v[220:223], v[0:3]
	v_mfma_f32_16x16x32_bf16 v[52:55], v[184:187], v[200:203], v[52:55]
	v_mfma_f32_16x16x32_bf16 v[48:51], v[192:195], v[200:203], v[48:51]
	v_mfma_f32_16x16x32_bf16 v[36:39], v[184:187], v[208:211], v[36:39]
	v_mfma_f32_16x16x32_bf16 v[32:35], v[192:195], v[208:211], v[32:35]
	v_mfma_f32_16x16x32_bf16 v[20:23], v[184:187], v[216:219], v[20:23]
	v_mfma_f32_16x16x32_bf16 v[16:19], v[192:195], v[216:219], v[16:19]
	v_mfma_f32_16x16x32_bf16 v[4:7], v[184:187], v[224:227], v[4:7]
	v_mfma_f32_16x16x32_bf16 v[0:3], v[192:195], v[224:227], v[0:3]
	s_barrier
	s_add_i32 s43, s43, 2
	s_add_u32 s8, s8, 0x100
	s_addc_u32 s9, s9, 0
	s_add_u32 s41, s41, 0x100
	s_addc_u32 s42, s42, 0
	s_cmp_gt_u32 s43, 3
	s_cbranch_scc0 .LBB0_775
	s_and_b64 vcc, exec, s[24:25]
	s_cbranch_vccz .LBB0_778
	s_barrier
.LBB0_778:
	s_setprio 0
	s_cmp_gt_u32 s40, 3
	s_cselect_b64 s[38:39], -1, 0
	s_and_b32 s8, s40, -4
	s_cmp_lg_u32 s8, 4
	v_add_u32_e32 v160, s75, v137
	v_add_u32_e32 v158, s71, v165
	s_cselect_b64 s[10:11], -1, 0
	v_cmp_gt_i32_e32 vcc, s70, v160
	v_and_b32_e32 v175, 0x3ff, v158
	s_and_saveexec_b64 s[40:41], vcc
	s_cbranch_execz .LBB0_806
	s_mov_b64 s[8:9], -1
	s_and_b64 vcc, exec, s[38:39]
	s_cbranch_vccz .LBB0_785
	s_andn2_b64 vcc, exec, s[10:11]
	s_cbranch_vccnz .LBB0_782
	v_mov_b64_e32 v[130:131], v[126:127]
	s_mov_b64 s[8:9], 0
	v_mov_b64_e32 v[128:129], v[124:125]

.LBB0_1648:
	s_add_u32 s22, s22, 0x80080
	s_addc_u32 s23, s23, 0
	s_add_u32 s61, s24, 0x100
	v_mov_b32_e32 v0, 0
	s_addc_u32 s65, s25, 0
	s_mov_b32 s66, -2
	v_mov_b32_e32 v1, v0
	v_mov_b32_e32 v2, v0
	v_mov_b32_e32 v3, v0
	v_mov_b32_e32 v4, v0
	v_mov_b32_e32 v5, v0
	v_mov_b32_e32 v6, v0
	v_mov_b32_e32 v7, v0
	v_mov_b32_e32 v16, v0
	v_mov_b32_e32 v17, v0
	v_mov_b32_e32 v18, v0
	v_mov_b32_e32 v19, v0
	v_mov_b32_e32 v20, v0
	v_mov_b32_e32 v21, v0
	v_mov_b32_e32 v22, v0
	v_mov_b32_e32 v23, v0
	v_mov_b32_e32 v32, v0
	v_mov_b32_e32 v33, v0
	v_mov_b32_e32 v34, v0
	v_mov_b32_e32 v35, v0
	v_mov_b32_e32 v36, v0
	v_mov_b32_e32 v37, v0
	v_mov_b32_e32 v38, v0
	v_mov_b32_e32 v39, v0
	v_mov_b32_e32 v48, v0
	v_mov_b32_e32 v49, v0
	v_mov_b32_e32 v50, v0
	v_mov_b32_e32 v51, v0
	v_mov_b32_e32 v52, v0
	v_mov_b32_e32 v53, v0
	v_mov_b32_e32 v54, v0
	v_mov_b32_e32 v55, v0
	v_mov_b32_e32 v8, v0
	v_mov_b32_e32 v9, v0
	v_mov_b32_e32 v10, v0
	v_mov_b32_e32 v11, v0
	v_mov_b32_e32 v12, v0
	v_mov_b32_e32 v13, v0
	v_mov_b32_e32 v14, v0
	v_mov_b32_e32 v15, v0
	v_mov_b32_e32 v24, v0
	v_mov_b32_e32 v25, v0
	v_mov_b32_e32 v26, v0
	v_mov_b32_e32 v27, v0
	v_mov_b32_e32 v28, v0
	v_mov_b32_e32 v29, v0
	v_mov_b32_e32 v30, v0
	v_mov_b32_e32 v31, v0
	v_mov_b32_e32 v40, v0
	v_mov_b32_e32 v41, v0
	v_mov_b32_e32 v42, v0
	v_mov_b32_e32 v43, v0
	v_mov_b32_e32 v44, v0
	v_mov_b32_e32 v45, v0
	v_mov_b32_e32 v46, v0
	v_mov_b32_e32 v47, v0
	v_mov_b32_e32 v56, v0
	v_mov_b32_e32 v57, v0
	v_mov_b32_e32 v58, v0
	v_mov_b32_e32 v59, v0
	v_mov_b32_e32 v60, v0
	v_mov_b32_e32 v61, v0
	v_mov_b32_e32 v62, v0
	v_mov_b32_e32 v63, v0
	v_mov_b32_e32 v64, v0
	v_mov_b32_e32 v65, v0
	v_mov_b32_e32 v66, v0
	v_mov_b32_e32 v67, v0
	v_mov_b32_e32 v68, v0
	v_mov_b32_e32 v69, v0
	v_mov_b32_e32 v70, v0
	v_mov_b32_e32 v71, v0
	v_mov_b32_e32 v80, v0
	v_mov_b32_e32 v81, v0
	v_mov_b32_e32 v82, v0
	v_mov_b32_e32 v83, v0
	v_mov_b32_e32 v84, v0
	v_mov_b32_e32 v85, v0
	v_mov_b32_e32 v86, v0
	v_mov_b32_e32 v87, v0
	v_mov_b32_e32 v96, v0
	v_mov_b32_e32 v97, v0
	v_mov_b32_e32 v98, v0
	v_mov_b32_e32 v99, v0
	v_mov_b32_e32 v100, v0
	v_mov_b32_e32 v101, v0
	v_mov_b32_e32 v102, v0
	v_mov_b32_e32 v103, v0
	v_mov_b32_e32 v112, v0
	v_mov_b32_e32 v113, v0
	v_mov_b32_e32 v114, v0
	v_mov_b32_e32 v115, v0
	v_mov_b32_e32 v116, v0
	v_mov_b32_e32 v117, v0
	v_mov_b32_e32 v118, v0
	v_mov_b32_e32 v119, v0
	v_mov_b32_e32 v72, v0
	v_mov_b32_e32 v73, v0
	v_mov_b32_e32 v74, v0
	v_mov_b32_e32 v75, v0
	v_mov_b32_e32 v76, v0
	v_mov_b32_e32 v77, v0
	v_mov_b32_e32 v78, v0
	v_mov_b32_e32 v79, v0
	v_mov_b32_e32 v88, v0
	v_mov_b32_e32 v89, v0
	v_mov_b32_e32 v90, v0
	v_mov_b32_e32 v91, v0
	v_mov_b32_e32 v92, v0
	v_mov_b32_e32 v93, v0
	v_mov_b32_e32 v94, v0
	v_mov_b32_e32 v95, v0
	v_mov_b32_e32 v104, v0
	v_mov_b32_e32 v105, v0
	v_mov_b32_e32 v106, v0
	v_mov_b32_e32 v107, v0
	v_mov_b32_e32 v108, v0
	v_mov_b32_e32 v109, v0
	v_mov_b32_e32 v110, v0
	v_mov_b32_e32 v111, v0
	v_mov_b32_e32 v120, v0
	v_mov_b32_e32 v121, v0
	v_mov_b32_e32 v122, v0
	v_mov_b32_e32 v123, v0
	v_mov_b32_e32 v124, v0
	v_mov_b32_e32 v125, v0
	v_mov_b32_e32 v126, v0
	v_mov_b32_e32 v127, v0
	s_cmp_eq_u64 s[14:15], 0
	s_cbranch_scc0 .Lprio_skip_5
	s_setprio 1
.Lprio_skip_5:
.LBB0_1649:
	ds_read_b128 v[148:151], v157
	ds_read_b128 v[160:163], v157 offset:1024
	ds_read_b128 v[164:167], v157 offset:2048
	ds_read_b128 v[168:171], v157 offset:3072
	ds_read_b128 v[172:175], v158
	ds_read_b128 v[176:179], v158 offset:1024
	ds_read_b128 v[180:183], v158 offset:2048
	ds_read_b128 v[184:187], v158 offset:3072
	s_add_u32 s24, s22, 0xfff80080
	s_addc_u32 s25, s23, -1
	s_cmp_eq_u32 s66, 28
	s_cselect_b32 s27, s19, s25
	s_cselect_b32 s26, s18, s24
	s_cselect_b32 s25, s21, s65
	s_cselect_b32 s24, s20, s61
	v_lshl_add_u64 v[220:221], s[22:23], 0, v[140:141]
	s_add_i32 m0, s38, 0xc000
	ds_read_b128 v[188:191], v159
	ds_read_b128 v[192:195], v159 offset:1024
	ds_read_b128 v[196:199], v159 offset:2048
	ds_read_b128 v[200:203], v159 offset:3072
	ds_read_b128 v[204:207], v159 offset:4096
	ds_read_b128 v[208:211], v159 offset:5120
	ds_read_b128 v[212:215], v159 offset:6144
	ds_read_b128 v[216:219], v159 offset:7168
	global_load_lds_dwordx4 v[220:221], off
	v_lshl_add_u64 v[220:221], s[22:23], 0, v[142:143]
	s_add_i32 m0, s38, 0xe000
	s_nop 0
	global_load_lds_dwordx4 v[220:221], off
	s_waitcnt vmcnt(8)
	s_waitcnt lgkmcnt(0)
	s_barrier
	s_waitcnt lgkmcnt(0)
	v_mfma_f32_16x16x32_bf16 v[124:127], v[148:151], v[188:191], v[124:127]
	v_mfma_f32_16x16x32_bf16 v[120:123], v[164:167], v[188:191], v[120:123]
	v_mfma_f32_16x16x32_bf16 v[108:111], v[148:151], v[196:199], v[108:111]
	v_mfma_f32_16x16x32_bf16 v[104:107], v[164:167], v[196:199], v[104:107]
	v_mfma_f32_16x16x32_bf16 v[92:95], v[148:151], v[204:207], v[92:95]
	v_mfma_f32_16x16x32_bf16 v[88:91], v[164:167], v[204:207], v[88:91]
	v_mfma_f32_16x16x32_bf16 v[76:79], v[148:151], v[212:215], v[76:79]
	v_mfma_f32_16x16x32_bf16 v[72:75], v[164:167], v[212:215], v[72:75]
	v_mfma_f32_16x16x32_bf16 v[124:127], v[160:163], v[192:195], v[124:127]
	v_mfma_f32_16x16x32_bf16 v[120:123], v[168:171], v[192:195], v[120:123]
	v_mfma_f32_16x16x32_bf16 v[108:111], v[160:163], v[200:203], v[108:111]
	v_mfma_f32_16x16x32_bf16 v[104:107], v[168:171], v[200:203], v[104:107]
	v_mfma_f32_16x16x32_bf16 v[92:95], v[160:163], v[208:211], v[92:95]
	v_mfma_f32_16x16x32_bf16 v[88:91], v[168:171], v[208:211], v[88:91]
	v_mfma_f32_16x16x32_bf16 v[76:79], v[160:163], v[216:219], v[76:79]
	v_mfma_f32_16x16x32_bf16 v[72:75], v[168:171], v[216:219], v[72:75]
	v_mfma_f32_16x16x32_bf16 v[116:119], v[172:175], v[188:191], v[116:119]
	v_mfma_f32_16x16x32_bf16 v[112:115], v[180:183], v[188:191], v[112:115]
	v_mfma_f32_16x16x32_bf16 v[100:103], v[172:175], v[196:199], v[100:103]
	v_mfma_f32_16x16x32_bf16 v[96:99], v[180:183], v[196:199], v[96:99]
	v_mfma_f32_16x16x32_bf16 v[84:87], v[172:175], v[204:207], v[84:87]
	v_mfma_f32_16x16x32_bf16 v[80:83], v[180:183], v[204:207], v[80:83]
	v_mfma_f32_16x16x32_bf16 v[68:71], v[172:175], v[212:215], v[68:71]
	v_mfma_f32_16x16x32_bf16 v[64:67], v[180:183], v[212:215], v[64:67]
	v_mfma_f32_16x16x32_bf16 v[116:119], v[176:179], v[192:195], v[116:119]
	v_mfma_f32_16x16x32_bf16 v[112:115], v[184:187], v[192:195], v[112:115]
	v_mfma_f32_16x16x32_bf16 v[100:103], v[176:179], v[200:203], v[100:103]
	v_mfma_f32_16x16x32_bf16 v[96:99], v[184:187], v[200:203], v[96:99]
	v_mfma_f32_16x16x32_bf16 v[84:87], v[176:179], v[208:211], v[84:87]
	v_mfma_f32_16x16x32_bf16 v[80:83], v[184:187], v[208:211], v[80:83]
	v_mfma_f32_16x16x32_bf16 v[68:71], v[176:179], v[216:219], v[68:71]
	v_mfma_f32_16x16x32_bf16 v[64:67], v[184:187], v[216:219], v[64:67]
	s_barrier
	s_add_i32 s67, s45, s37
	v_lshl_add_u64 v[220:221], s[24:25], 0, v[130:131]
	s_mov_b32 m0, s67
	ds_read_b128 v[188:191], v159 offset:16384
	ds_read_b128 v[192:195], v159 offset:17408
	ds_read_b128 v[196:199], v159 offset:18432
	ds_read_b128 v[200:203], v159 offset:19456
	ds_read_b128 v[204:207], v159 offset:20480
	ds_read_b128 v[208:211], v159 offset:21504
	ds_read_b128 v[212:215], v159 offset:22528
	ds_read_b128 v[216:219], v159 offset:23552
	global_load_lds_dwordx4 v[220:221], off
	s_add_i32 m0, s67, 0x2000
	s_add_u32 s68, s24, 0x80000
	v_lshl_add_u64 v[222:223], s[24:25], 0, v[134:135]
	s_addc_u32 s69, s25, 0
	s_add_i32 s67, s46, s37
	global_load_lds_dwordx4 v[222:223], off
	v_lshl_add_u64 v[224:225], s[68:69], 0, v[130:131]
	s_mov_b32 m0, s67
	v_lshl_add_u64 v[226:227], s[26:27], 0, v[132:133]
	global_load_lds_dwordx4 v[224:225], off
	v_lshl_add_u64 v[224:225], s[68:69], 0, v[134:135]
	s_add_i32 m0, s67, 0x2000
	s_nop 0
	global_load_lds_dwordx4 v[224:225], off
	v_lshl_add_u64 v[224:225], s[26:27], 0, v[128:129]
	s_mov_b32 m0, s38
	s_nop 0
	global_load_lds_dwordx4 v[224:225], off
	s_mov_b32 m0, s39
	s_nop 0
	global_load_lds_dwordx4 v[226:227], off
	s_waitcnt vmcnt(8)
	s_waitcnt lgkmcnt(0)
	s_barrier
	s_waitcnt lgkmcnt(0)
	v_mfma_f32_16x16x32_bf16 v[60:63], v[148:151], v[188:191], v[60:63]
	v_mfma_f32_16x16x32_bf16 v[56:59], v[164:167], v[188:191], v[56:59]
	v_mfma_f32_16x16x32_bf16 v[44:47], v[148:151], v[196:199], v[44:47]
	v_mfma_f32_16x16x32_bf16 v[40:43], v[164:167], v[196:199], v[40:43]
	v_mfma_f32_16x16x32_bf16 v[28:31], v[148:151], v[204:207], v[28:31]
	v_mfma_f32_16x16x32_bf16 v[24:27], v[164:167], v[204:207], v[24:27]
	v_mfma_f32_16x16x32_bf16 v[12:15], v[148:151], v[212:215], v[12:15]
	v_mfma_f32_16x16x32_bf16 v[8:11], v[164:167], v[212:215], v[8:11]
	v_mfma_f32_16x16x32_bf16 v[60:63], v[160:163], v[192:195], v[60:63]
	v_mfma_f32_16x16x32_bf16 v[56:59], v[168:171], v[192:195], v[56:59]
	v_mfma_f32_16x16x32_bf16 v[44:47], v[160:163], v[200:203], v[44:47]
	v_mfma_f32_16x16x32_bf16 v[40:43], v[168:171], v[200:203], v[40:43]
	v_mfma_f32_16x16x32_bf16 v[28:31], v[160:163], v[208:211], v[28:31]
	v_mfma_f32_16x16x32_bf16 v[24:27], v[168:171], v[208:211], v[24:27]
	v_mfma_f32_16x16x32_bf16 v[12:15], v[160:163], v[216:219], v[12:15]
	v_mfma_f32_16x16x32_bf16 v[8:11], v[168:171], v[216:219], v[8:11]
	v_mfma_f32_16x16x32_bf16 v[52:55], v[172:175], v[188:191], v[52:55]
	v_mfma_f32_16x16x32_bf16 v[48:51], v[180:183], v[188:191], v[48:51]
	v_mfma_f32_16x16x32_bf16 v[36:39], v[172:175], v[196:199], v[36:39]
	v_mfma_f32_16x16x32_bf16 v[32:35], v[180:183], v[196:199], v[32:35]
	v_mfma_f32_16x16x32_bf16 v[20:23], v[172:175], v[204:207], v[20:23]
	v_mfma_f32_16x16x32_bf16 v[16:19], v[180:183], v[204:207], v[16:19]
	v_mfma_f32_16x16x32_bf16 v[4:7], v[172:175], v[212:215], v[4:7]
	v_mfma_f32_16x16x32_bf16 v[0:3], v[180:183], v[212:215], v[0:3]
	v_mfma_f32_16x16x32_bf16 v[52:55], v[176:179], v[192:195], v[52:55]
	v_mfma_f32_16x16x32_bf16 v[48:51], v[184:187], v[192:195], v[48:51]
	v_mfma_f32_16x16x32_bf16 v[36:39], v[176:179], v[200:203], v[36:39]
	v_mfma_f32_16x16x32_bf16 v[32:35], v[184:187], v[200:203], v[32:35]
	v_mfma_f32_16x16x32_bf16 v[20:23], v[176:179], v[208:211], v[20:23]
	v_mfma_f32_16x16x32_bf16 v[16:19], v[184:187], v[208:211], v[16:19]
	v_mfma_f32_16x16x32_bf16 v[4:7], v[176:179], v[216:219], v[4:7]
	v_mfma_f32_16x16x32_bf16 v[0:3], v[184:187], v[216:219], v[0:3]
	s_barrier
	s_add_i32 s67, 0, 0x18000
	s_add_i32 s68, 0, 0x1c000
	v_add_u32_e32 v168, s67, v155
	v_add_u32_e32 v184, s68, v155
	ds_read_b128 v[148:151], v168
	ds_read_b128 v[160:163], v168 offset:1024
	ds_read_b128 v[164:167], v168 offset:2048
	ds_read_b128 v[168:171], v168 offset:3072
	ds_read_b128 v[172:175], v184
	ds_read_b128 v[176:179], v184 offset:1024
	ds_read_b128 v[180:183], v184 offset:2048
	ds_read_b128 v[184:187], v184 offset:3072
	s_add_u32 s26, s26, 0x80000
	s_addc_u32 s27, s27, 0
	s_mov_b32 m0, s40
	v_lshl_add_u64 v[228:229], s[26:27], 0, v[128:129]
	ds_read_b128 v[188:191], v159 offset:32768
	ds_read_b128 v[192:195], v159 offset:33792
	ds_read_b128 v[196:199], v159 offset:34816
	ds_read_b128 v[200:203], v159 offset:35840
	ds_read_b128 v[204:207], v159 offset:36864
	ds_read_b128 v[208:211], v159 offset:37888
	ds_read_b128 v[212:215], v159 offset:38912
	ds_read_b128 v[216:219], v159 offset:39936
	global_load_lds_dwordx4 v[228:229], off
	v_lshl_add_u64 v[228:229], s[26:27], 0, v[132:133]
	s_mov_b32 m0, s41
	s_nop 0
	global_load_lds_dwordx4 v[228:229], off
	s_waitcnt vmcnt(8)
	s_waitcnt lgkmcnt(0)
	s_barrier
	s_waitcnt lgkmcnt(0)
	v_mfma_f32_16x16x32_bf16 v[124:127], v[148:151], v[188:191], v[124:127]
	v_mfma_f32_16x16x32_bf16 v[120:123], v[164:167], v[188:191], v[120:123]
	v_mfma_f32_16x16x32_bf16 v[108:111], v[148:151], v[196:199], v[108:111]
	v_mfma_f32_16x16x32_bf16 v[104:107], v[164:167], v[196:199], v[104:107]
	v_mfma_f32_16x16x32_bf16 v[92:95], v[148:151], v[204:207], v[92:95]
	v_mfma_f32_16x16x32_bf16 v[88:91], v[164:167], v[204:207], v[88:91]
	v_mfma_f32_16x16x32_bf16 v[76:79], v[148:151], v[212:215], v[76:79]
	v_mfma_f32_16x16x32_bf16 v[72:75], v[164:167], v[212:215], v[72:75]
	v_mfma_f32_16x16x32_bf16 v[124:127], v[160:163], v[192:195], v[124:127]
	v_mfma_f32_16x16x32_bf16 v[120:123], v[168:171], v[192:195], v[120:123]
	v_mfma_f32_16x16x32_bf16 v[108:111], v[160:163], v[200:203], v[108:111]
	v_mfma_f32_16x16x32_bf16 v[104:107], v[168:171], v[200:203], v[104:107]
	v_mfma_f32_16x16x32_bf16 v[92:95], v[160:163], v[208:211], v[92:95]
	v_mfma_f32_16x16x32_bf16 v[88:91], v[168:171], v[208:211], v[88:91]
	v_mfma_f32_16x16x32_bf16 v[76:79], v[160:163], v[216:219], v[76:79]
	v_mfma_f32_16x16x32_bf16 v[72:75], v[168:171], v[216:219], v[72:75]
	v_mfma_f32_16x16x32_bf16 v[116:119], v[172:175], v[188:191], v[116:119]
	v_mfma_f32_16x16x32_bf16 v[112:115], v[180:183], v[188:191], v[112:115]
	v_mfma_f32_16x16x32_bf16 v[100:103], v[172:175], v[196:199], v[100:103]
	v_mfma_f32_16x16x32_bf16 v[96:99], v[180:183], v[196:199], v[96:99]
	v_mfma_f32_16x16x32_bf16 v[84:87], v[172:175], v[204:207], v[84:87]
	v_mfma_f32_16x16x32_bf16 v[80:83], v[180:183], v[204:207], v[80:83]
	v_mfma_f32_16x16x32_bf16 v[68:71], v[172:175], v[212:215], v[68:71]
	v_mfma_f32_16x16x32_bf16 v[64:67], v[180:183], v[212:215], v[64:67]
	v_mfma_f32_16x16x32_bf16 v[116:119], v[176:179], v[192:195], v[116:119]
	v_mfma_f32_16x16x32_bf16 v[112:115], v[184:187], v[192:195], v[112:115]
	v_mfma_f32_16x16x32_bf16 v[100:103], v[176:179], v[200:203], v[100:103]
	v_mfma_f32_16x16x32_bf16 v[96:99], v[184:187], v[200:203], v[96:99]
	v_mfma_f32_16x16x32_bf16 v[84:87], v[176:179], v[208:211], v[84:87]
	v_mfma_f32_16x16x32_bf16 v[80:83], v[184:187], v[208:211], v[80:83]
	v_mfma_f32_16x16x32_bf16 v[68:71], v[176:179], v[216:219], v[68:71]
	v_mfma_f32_16x16x32_bf16 v[64:67], v[184:187], v[216:219], v[64:67]
	s_barrier
	s_add_i32 s26, s67, s37
	v_lshl_add_u64 v[220:221], v[220:221], 0, s[12:13]
	s_mov_b32 m0, s26
	ds_read_b128 v[188:191], v159 offset:49152
	ds_read_b128 v[192:195], v159 offset:50176
	ds_read_b128 v[196:199], v159 offset:51200
	ds_read_b128 v[200:203], v159 offset:52224
	ds_read_b128 v[204:207], v159 offset:53248
	ds_read_b128 v[208:211], v159 offset:54272
	ds_read_b128 v[212:215], v159 offset:55296
	ds_read_b128 v[216:219], v159 offset:56320
	global_load_lds_dwordx4 v[220:221], off
	s_add_i32 m0, s26, 0x2000
	s_add_u32 s24, s24, 0x80080
	v_lshl_add_u64 v[220:221], v[222:223], 0, s[12:13]
	s_addc_u32 s25, s25, 0
	s_add_i32 s26, s68, s37
	global_load_lds_dwordx4 v[220:221], off
	v_lshl_add_u64 v[220:221], s[24:25], 0, v[130:131]
	s_mov_b32 m0, s26
	s_nop 0
	global_load_lds_dwordx4 v[220:221], off
	v_lshl_add_u64 v[220:221], s[24:25], 0, v[134:135]
	s_add_i32 m0, s26, 0x2000
	s_nop 0
	global_load_lds_dwordx4 v[220:221], off
	v_lshl_add_u64 v[220:221], v[224:225], 0, s[12:13]
	s_mov_b32 m0, s43
	s_nop 0
	global_load_lds_dwordx4 v[220:221], off
	v_lshl_add_u64 v[220:221], v[226:227], 0, s[12:13]
	s_mov_b32 m0, s44
	s_nop 0
	global_load_lds_dwordx4 v[220:221], off
	s_waitcnt vmcnt(8)
	s_waitcnt lgkmcnt(0)
	s_barrier
	s_waitcnt lgkmcnt(0)
	v_mfma_f32_16x16x32_bf16 v[60:63], v[148:151], v[188:191], v[60:63]
	v_mfma_f32_16x16x32_bf16 v[56:59], v[164:167], v[188:191], v[56:59]
	v_mfma_f32_16x16x32_bf16 v[44:47], v[148:151], v[196:199], v[44:47]
	v_mfma_f32_16x16x32_bf16 v[40:43], v[164:167], v[196:199], v[40:43]
	v_mfma_f32_16x16x32_bf16 v[28:31], v[148:151], v[204:207], v[28:31]
	v_mfma_f32_16x16x32_bf16 v[24:27], v[164:167], v[204:207], v[24:27]
	v_mfma_f32_16x16x32_bf16 v[12:15], v[148:151], v[212:215], v[12:15]
	v_mfma_f32_16x16x32_bf16 v[8:11], v[164:167], v[212:215], v[8:11]
	v_mfma_f32_16x16x32_bf16 v[60:63], v[160:163], v[192:195], v[60:63]
	v_mfma_f32_16x16x32_bf16 v[56:59], v[168:171], v[192:195], v[56:59]
	v_mfma_f32_16x16x32_bf16 v[44:47], v[160:163], v[200:203], v[44:47]
	v_mfma_f32_16x16x32_bf16 v[40:43], v[168:171], v[200:203], v[40:43]
	v_mfma_f32_16x16x32_bf16 v[28:31], v[160:163], v[208:211], v[28:31]
	v_mfma_f32_16x16x32_bf16 v[24:27], v[168:171], v[208:211], v[24:27]
	v_mfma_f32_16x16x32_bf16 v[12:15], v[160:163], v[216:219], v[12:15]
	v_mfma_f32_16x16x32_bf16 v[8:11], v[168:171], v[216:219], v[8:11]
	v_mfma_f32_16x16x32_bf16 v[52:55], v[172:175], v[188:191], v[52:55]
	v_mfma_f32_16x16x32_bf16 v[48:51], v[180:183], v[188:191], v[48:51]
	v_mfma_f32_16x16x32_bf16 v[36:39], v[172:175], v[196:199], v[36:39]
	v_mfma_f32_16x16x32_bf16 v[32:35], v[180:183], v[196:199], v[32:35]
	v_mfma_f32_16x16x32_bf16 v[20:23], v[172:175], v[204:207], v[20:23]
	v_mfma_f32_16x16x32_bf16 v[16:19], v[180:183], v[204:207], v[16:19]
	v_mfma_f32_16x16x32_bf16 v[4:7], v[172:175], v[212:215], v[4:7]
	v_mfma_f32_16x16x32_bf16 v[0:3], v[180:183], v[212:215], v[0:3]
	v_mfma_f32_16x16x32_bf16 v[52:55], v[176:179], v[192:195], v[52:55]
	v_mfma_f32_16x16x32_bf16 v[48:51], v[184:187], v[192:195], v[48:51]
	v_mfma_f32_16x16x32_bf16 v[36:39], v[176:179], v[200:203], v[36:39]
	v_mfma_f32_16x16x32_bf16 v[32:35], v[184:187], v[200:203], v[32:35]
	v_mfma_f32_16x16x32_bf16 v[20:23], v[176:179], v[208:211], v[20:23]
	v_mfma_f32_16x16x32_bf16 v[16:19], v[184:187], v[208:211], v[16:19]
	v_mfma_f32_16x16x32_bf16 v[4:7], v[176:179], v[216:219], v[4:7]
	v_mfma_f32_16x16x32_bf16 v[0:3], v[184:187], v[216:219], v[0:3]
	s_barrier
	s_add_i32 s66, s66, 2
	s_add_u32 s22, s22, 0x100
	s_addc_u32 s23, s23, 0
	s_add_u32 s61, s61, 0x100
	s_addc_u32 s65, s65, 0
	s_cmp_gt_u32 s66, 29
	s_cbranch_scc0 .LBB0_1649
	s_and_b64 vcc, exec, s[14:15]
	s_cbranch_vccz .LBB0_1652
	s_barrier
.LBB0_1652:
	s_setprio 0
	v_add_u32_e32 v150, s60, v154
	v_add_u32_e32 v148, s59, v156
	v_ashrrev_i32_e32 v151, 31, v150
	v_ashrrev_i32_e32 v149, 31, v148
	v_lshlrev_b64 v[168:169], 12, v[150:151]
	v_lshl_add_u64 v[160:161], s[50:51], 0, v[168:169]
	v_lshlrev_b64 v[148:149], 1, v[148:149]
	v_lshl_add_u64 v[164:165], v[160:161], 0, v[148:149]
	global_load_dwordx4 v[160:163], v[164:165], off
	s_nop 0
	global_load_dwordx4 v[164:167], v[164:165], off offset:256
	v_add_u32_e32 v170, 16, v150
	v_ashrrev_i32_e32 v171, 31, v170
	v_lshl_add_u64 v[168:169], s[56:57], 0, v[168:169]
	v_lshlrev_b64 v[170:171], 12, v[170:171]
	v_lshl_add_u64 v[168:169], v[168:169], 0, v[148:149]
	v_lshl_add_u64 v[172:173], s[50:51], 0, v[170:171]
	v_lshl_add_u64 v[172:173], v[172:173], 0, v[148:149]
	s_andn2_b64 vcc, exec, s[6:7]
	s_mov_b64 s[6:7], -1
	s_waitcnt vmcnt(0)
	v_lshlrev_b32_e32 v176, 16, v162
	v_and_b32_e32 v177, 0xffff0000, v162
	v_lshlrev_b32_e32 v174, 16, v160
	v_and_b32_e32 v175, 0xffff0000, v160
	v_lshlrev_b32_e32 v160, 16, v161
	v_and_b32_e32 v161, 0xffff0000, v161
	v_lshlrev_b32_e32 v162, 16, v163
	v_and_b32_e32 v163, 0xffff0000, v163
	v_lshlrev_b32_e32 v178, 16, v164
	v_and_b32_e32 v179, 0xffff0000, v164
	v_lshlrev_b32_e32 v164, 16, v165
	v_and_b32_e32 v165, 0xffff0000, v165
	v_lshlrev_b32_e32 v180, 16, v166
	v_and_b32_e32 v181, 0xffff0000, v166
	v_lshlrev_b32_e32 v166, 16, v167
	v_and_b32_e32 v167, 0xffff0000, v167
	v_pk_fma_f32 v[120:121], v[176:177], s[16:17], v[120:121] op_sel_hi:[1,0,1]
	v_pk_fma_f32 v[126:127], v[160:161], s[16:17], v[126:127] op_sel_hi:[1,0,1]
	v_pk_fma_f32 v[124:125], v[174:175], s[16:17], v[124:125] op_sel_hi:[1,0,1]
	v_pk_fma_f32 v[122:123], v[162:163], s[16:17], v[122:123] op_sel_hi:[1,0,1]
	v_pk_fma_f32 v[160:161], v[164:165], s[16:17], v[118:119] op_sel_hi:[1,0,1]
	v_pk_fma_f32 v[162:163], v[178:179], s[16:17], v[116:117] op_sel_hi:[1,0,1]
	v_cvt_pk_bf16_f32 v116, v124, v125
	v_cvt_pk_bf16_f32 v117, v126, v127
	v_cvt_pk_bf16_f32 v118, v120, v121
	v_cvt_pk_bf16_f32 v119, v122, v123
	global_store_dwordx4 v[168:169], v[116:119], off
	v_pk_fma_f32 v[120:121], v[166:167], s[16:17], v[114:115] op_sel_hi:[1,0,1]
	v_pk_fma_f32 v[114:115], v[180:181], s[16:17], v[112:113] op_sel_hi:[1,0,1]
	global_load_dwordx4 v[116:119], v[172:173], off
	v_cvt_pk_bf16_f32 v112, v162, v163
	v_cvt_pk_bf16_f32 v113, v160, v161
	v_cvt_pk_bf16_f32 v114, v114, v115
	v_cvt_pk_bf16_f32 v115, v120, v121
	global_store_dwordx4 v[168:169], v[112:115], off offset:256
	global_load_dwordx4 v[112:115], v[172:173], off offset:256
	v_add_u32_e32 v120, 32, v150
	v_ashrrev_i32_e32 v121, 31, v120
	v_lshlrev_b64 v[120:121], 12, v[120:121]
	v_lshl_add_u64 v[122:123], s[56:57], 0, v[170:171]
	v_lshl_add_u64 v[124:125], s[50:51], 0, v[120:121]
	v_lshl_add_u64 v[122:123], v[122:123], 0, v[148:149]
	v_lshl_add_u64 v[124:125], v[124:125], 0, v[148:149]
	s_waitcnt vmcnt(2)
	v_lshlrev_b32_e32 v160, 16, v118
	v_and_b32_e32 v161, 0xffff0000, v118
	v_lshlrev_b32_e32 v126, 16, v116
	v_and_b32_e32 v127, 0xffff0000, v116
	v_lshlrev_b32_e32 v116, 16, v117
	v_and_b32_e32 v117, 0xffff0000, v117
	v_lshlrev_b32_e32 v118, 16, v119
	v_and_b32_e32 v119, 0xffff0000, v119
	s_waitcnt vmcnt(0)
	v_lshlrev_b32_e32 v162, 16, v112
	v_and_b32_e32 v163, 0xffff0000, v112
	v_lshlrev_b32_e32 v112, 16, v113
	v_and_b32_e32 v113, 0xffff0000, v113
	v_lshlrev_b32_e32 v164, 16, v114
	v_and_b32_e32 v165, 0xffff0000, v114
	v_lshlrev_b32_e32 v114, 16, v115
	v_and_b32_e32 v115, 0xffff0000, v115
	v_pk_fma_f32 v[104:105], v[160:161], s[16:17], v[104:105] op_sel_hi:[1,0,1]
	v_pk_fma_f32 v[110:111], v[116:117], s[16:17], v[110:111] op_sel_hi:[1,0,1]
	v_pk_fma_f32 v[108:109], v[126:127], s[16:17], v[108:109] op_sel_hi:[1,0,1]
	v_pk_fma_f32 v[106:107], v[118:119], s[16:17], v[106:107] op_sel_hi:[1,0,1]
	v_pk_fma_f32 v[112:113], v[112:113], s[16:17], v[102:103] op_sel_hi:[1,0,1]
	v_pk_fma_f32 v[116:117], v[162:163], s[16:17], v[100:101] op_sel_hi:[1,0,1]
	v_cvt_pk_bf16_f32 v100, v108, v109
	v_cvt_pk_bf16_f32 v101, v110, v111
	v_cvt_pk_bf16_f32 v102, v104, v105
	v_cvt_pk_bf16_f32 v103, v106, v107
	global_store_dwordx4 v[122:123], v[100:103], off
	v_pk_fma_f32 v[104:105], v[114:115], s[16:17], v[98:99] op_sel_hi:[1,0,1]
	v_pk_fma_f32 v[98:99], v[164:165], s[16:17], v[96:97] op_sel_hi:[1,0,1]
	global_load_dwordx4 v[100:103], v[124:125], off
	v_cvt_pk_bf16_f32 v96, v116, v117
	v_cvt_pk_bf16_f32 v97, v112, v113
	v_cvt_pk_bf16_f32 v98, v98, v99
	v_cvt_pk_bf16_f32 v99, v104, v105
	global_store_dwordx4 v[122:123], v[96:99], off offset:256
	global_load_dwordx4 v[96:99], v[124:125], off offset:256
	v_add_u32_e32 v104, 48, v150
	v_ashrrev_i32_e32 v105, 31, v104
	v_lshlrev_b64 v[104:105], 12, v[104:105]
	v_lshl_add_u64 v[106:107], s[56:57], 0, v[120:121]
	v_lshl_add_u64 v[108:109], s[50:51], 0, v[104:105]
	v_lshl_add_u64 v[106:107], v[106:107], 0, v[148:149]
	v_lshl_add_u64 v[108:109], v[108:109], 0, v[148:149]
	s_waitcnt vmcnt(2)
	v_lshlrev_b32_e32 v112, 16, v102
	v_and_b32_e32 v113, 0xffff0000, v102
	v_lshlrev_b32_e32 v110, 16, v100
	v_and_b32_e32 v111, 0xffff0000, v100
	v_lshlrev_b32_e32 v100, 16, v101
	v_and_b32_e32 v101, 0xffff0000, v101
	v_lshlrev_b32_e32 v102, 16, v103
	v_and_b32_e32 v103, 0xffff0000, v103
	s_waitcnt vmcnt(0)
	v_lshlrev_b32_e32 v114, 16, v96
	v_and_b32_e32 v115, 0xffff0000, v96
	v_lshlrev_b32_e32 v96, 16, v97
	v_and_b32_e32 v97, 0xffff0000, v97
	v_lshlrev_b32_e32 v116, 16, v98
	v_and_b32_e32 v117, 0xffff0000, v98
	v_lshlrev_b32_e32 v98, 16, v99
	v_and_b32_e32 v99, 0xffff0000, v99
	v_pk_fma_f32 v[88:89], v[112:113], s[16:17], v[88:89] op_sel_hi:[1,0,1]
	v_pk_fma_f32 v[94:95], v[100:101], s[16:17], v[94:95] op_sel_hi:[1,0,1]
	v_pk_fma_f32 v[92:93], v[110:111], s[16:17], v[92:93] op_sel_hi:[1,0,1]
	v_pk_fma_f32 v[90:91], v[102:103], s[16:17], v[90:91] op_sel_hi:[1,0,1]
	v_pk_fma_f32 v[96:97], v[96:97], s[16:17], v[86:87] op_sel_hi:[1,0,1]
	v_pk_fma_f32 v[100:101], v[114:115], s[16:17], v[84:85] op_sel_hi:[1,0,1]
	v_cvt_pk_bf16_f32 v84, v92, v93
	v_cvt_pk_bf16_f32 v85, v94, v95
	v_cvt_pk_bf16_f32 v86, v88, v89
	v_cvt_pk_bf16_f32 v87, v90, v91
	global_store_dwordx4 v[106:107], v[84:87], off
	v_pk_fma_f32 v[88:89], v[98:99], s[16:17], v[82:83] op_sel_hi:[1,0,1]
	v_pk_fma_f32 v[82:83], v[116:117], s[16:17], v[80:81] op_sel_hi:[1,0,1]
	global_load_dwordx4 v[84:87], v[108:109], off
	v_cvt_pk_bf16_f32 v80, v100, v101
	v_cvt_pk_bf16_f32 v81, v96, v97
	v_cvt_pk_bf16_f32 v82, v82, v83
	v_cvt_pk_bf16_f32 v83, v88, v89
	global_store_dwordx4 v[106:107], v[80:83], off offset:256
	global_load_dwordx4 v[80:83], v[108:109], off offset:256
	v_add_u32_e32 v88, 0x80, v150
	v_ashrrev_i32_e32 v89, 31, v88
	v_lshlrev_b64 v[88:89], 12, v[88:89]
	v_lshl_add_u64 v[90:91], s[56:57], 0, v[104:105]
	v_lshl_add_u64 v[92:93], s[50:51], 0, v[88:89]
	v_lshl_add_u64 v[90:91], v[90:91], 0, v[148:149]
	v_lshl_add_u64 v[92:93], v[92:93], 0, v[148:149]
	s_waitcnt vmcnt(2)
	v_lshlrev_b32_e32 v96, 16, v86
	v_and_b32_e32 v97, 0xffff0000, v86
	v_lshlrev_b32_e32 v94, 16, v84
	v_and_b32_e32 v95, 0xffff0000, v84
	v_lshlrev_b32_e32 v84, 16, v85
	v_and_b32_e32 v85, 0xffff0000, v85
	v_lshlrev_b32_e32 v86, 16, v87
	v_and_b32_e32 v87, 0xffff0000, v87
	s_waitcnt vmcnt(0)
	v_lshlrev_b32_e32 v98, 16, v80
	v_and_b32_e32 v99, 0xffff0000, v80
	v_lshlrev_b32_e32 v80, 16, v81
	v_and_b32_e32 v81, 0xffff0000, v81
	v_lshlrev_b32_e32 v100, 16, v82
	v_and_b32_e32 v101, 0xffff0000, v82
	v_lshlrev_b32_e32 v82, 16, v83
	v_and_b32_e32 v83, 0xffff0000, v83
	v_pk_fma_f32 v[72:73], v[96:97], s[16:17], v[72:73] op_sel_hi:[1,0,1]
	v_pk_fma_f32 v[78:79], v[84:85], s[16:17], v[78:79] op_sel_hi:[1,0,1]
	v_pk_fma_f32 v[76:77], v[94:95], s[16:17], v[76:77] op_sel_hi:[1,0,1]
	v_pk_fma_f32 v[74:75], v[86:87], s[16:17], v[74:75] op_sel_hi:[1,0,1]
	v_pk_fma_f32 v[80:81], v[80:81], s[16:17], v[70:71] op_sel_hi:[1,0,1]
	v_pk_fma_f32 v[84:85], v[98:99], s[16:17], v[68:69] op_sel_hi:[1,0,1]
	v_cvt_pk_bf16_f32 v68, v76, v77
	v_cvt_pk_bf16_f32 v69, v78, v79
	v_cvt_pk_bf16_f32 v70, v72, v73
	v_cvt_pk_bf16_f32 v71, v74, v75
	global_store_dwordx4 v[90:91], v[68:71], off
	v_pk_fma_f32 v[72:73], v[82:83], s[16:17], v[66:67] op_sel_hi:[1,0,1]
	v_pk_fma_f32 v[66:67], v[100:101], s[16:17], v[64:65] op_sel_hi:[1,0,1]
	global_load_dwordx4 v[68:71], v[92:93], off
	v_cvt_pk_bf16_f32 v64, v84, v85
	v_cvt_pk_bf16_f32 v65, v80, v81
	v_cvt_pk_bf16_f32 v66, v66, v67
	v_cvt_pk_bf16_f32 v67, v72, v73
	global_store_dwordx4 v[90:91], v[64:67], off offset:256
	global_load_dwordx4 v[64:67], v[92:93], off offset:256
	v_add_u32_e32 v72, 0x90, v150
	v_ashrrev_i32_e32 v73, 31, v72
	v_lshlrev_b64 v[72:73], 12, v[72:73]
	v_lshl_add_u64 v[74:75], s[56:57], 0, v[88:89]
	v_lshl_add_u64 v[76:77], s[50:51], 0, v[72:73]
	v_lshl_add_u64 v[74:75], v[74:75], 0, v[148:149]
	v_lshl_add_u64 v[76:77], v[76:77], 0, v[148:149]
	s_waitcnt vmcnt(2)
	v_lshlrev_b32_e32 v80, 16, v70
	v_and_b32_e32 v81, 0xffff0000, v70
	v_lshlrev_b32_e32 v78, 16, v68
	v_and_b32_e32 v79, 0xffff0000, v68
	v_lshlrev_b32_e32 v68, 16, v69
	v_and_b32_e32 v69, 0xffff0000, v69
	v_lshlrev_b32_e32 v70, 16, v71
	v_and_b32_e32 v71, 0xffff0000, v71
	s_waitcnt vmcnt(0)
	v_lshlrev_b32_e32 v82, 16, v64
	v_and_b32_e32 v83, 0xffff0000, v64
	v_lshlrev_b32_e32 v64, 16, v65
	v_and_b32_e32 v65, 0xffff0000, v65
	v_lshlrev_b32_e32 v84, 16, v66
	v_and_b32_e32 v85, 0xffff0000, v66
	v_lshlrev_b32_e32 v66, 16, v67
	v_and_b32_e32 v67, 0xffff0000, v67
	v_pk_fma_f32 v[56:57], v[80:81], s[16:17], v[56:57] op_sel_hi:[1,0,1]
	v_pk_fma_f32 v[62:63], v[68:69], s[16:17], v[62:63] op_sel_hi:[1,0,1]
	v_pk_fma_f32 v[60:61], v[78:79], s[16:17], v[60:61] op_sel_hi:[1,0,1]
	v_pk_fma_f32 v[58:59], v[70:71], s[16:17], v[58:59] op_sel_hi:[1,0,1]
	v_pk_fma_f32 v[64:65], v[64:65], s[16:17], v[54:55] op_sel_hi:[1,0,1]
	v_pk_fma_f32 v[68:69], v[82:83], s[16:17], v[52:53] op_sel_hi:[1,0,1]
	v_cvt_pk_bf16_f32 v52, v60, v61
	v_cvt_pk_bf16_f32 v53, v62, v63
	v_cvt_pk_bf16_f32 v54, v56, v57
	v_cvt_pk_bf16_f32 v55, v58, v59
	global_store_dwordx4 v[74:75], v[52:55], off
	v_pk_fma_f32 v[56:57], v[66:67], s[16:17], v[50:51] op_sel_hi:[1,0,1]
	v_pk_fma_f32 v[50:51], v[84:85], s[16:17], v[48:49] op_sel_hi:[1,0,1]
	global_load_dwordx4 v[52:55], v[76:77], off
	v_cvt_pk_bf16_f32 v48, v68, v69
	v_cvt_pk_bf16_f32 v49, v64, v65
	v_cvt_pk_bf16_f32 v50, v50, v51
	v_cvt_pk_bf16_f32 v51, v56, v57
	global_store_dwordx4 v[74:75], v[48:51], off offset:256
	global_load_dwordx4 v[48:51], v[76:77], off offset:256
	v_add_u32_e32 v56, 0xa0, v150
	v_ashrrev_i32_e32 v57, 31, v56
	v_lshlrev_b64 v[56:57], 12, v[56:57]
	v_lshl_add_u64 v[58:59], s[56:57], 0, v[72:73]
	v_lshl_add_u64 v[60:61], s[50:51], 0, v[56:57]
	v_lshl_add_u64 v[58:59], v[58:59], 0, v[148:149]
	v_lshl_add_u64 v[60:61], v[60:61], 0, v[148:149]
	s_waitcnt vmcnt(2)
	v_lshlrev_b32_e32 v64, 16, v54
	v_and_b32_e32 v65, 0xffff0000, v54
	v_lshlrev_b32_e32 v62, 16, v52
	v_and_b32_e32 v63, 0xffff0000, v52
	v_lshlrev_b32_e32 v52, 16, v53
	v_and_b32_e32 v53, 0xffff0000, v53
	v_lshlrev_b32_e32 v54, 16, v55
	v_and_b32_e32 v55, 0xffff0000, v55
	s_waitcnt vmcnt(0)
	v_lshlrev_b32_e32 v66, 16, v48
	v_and_b32_e32 v67, 0xffff0000, v48
	v_lshlrev_b32_e32 v48, 16, v49
	v_and_b32_e32 v49, 0xffff0000, v49
	v_lshlrev_b32_e32 v68, 16, v50
	v_and_b32_e32 v69, 0xffff0000, v50
	v_lshlrev_b32_e32 v50, 16, v51
	v_and_b32_e32 v51, 0xffff0000, v51
	v_pk_fma_f32 v[40:41], v[64:65], s[16:17], v[40:41] op_sel_hi:[1,0,1]
	v_pk_fma_f32 v[46:47], v[52:53], s[16:17], v[46:47] op_sel_hi:[1,0,1]
	v_pk_fma_f32 v[44:45], v[62:63], s[16:17], v[44:45] op_sel_hi:[1,0,1]
	v_pk_fma_f32 v[42:43], v[54:55], s[16:17], v[42:43] op_sel_hi:[1,0,1]
	v_pk_fma_f32 v[48:49], v[48:49], s[16:17], v[38:39] op_sel_hi:[1,0,1]
	v_pk_fma_f32 v[52:53], v[66:67], s[16:17], v[36:37] op_sel_hi:[1,0,1]
	v_cvt_pk_bf16_f32 v36, v44, v45
	v_cvt_pk_bf16_f32 v37, v46, v47
	v_cvt_pk_bf16_f32 v38, v40, v41
	v_cvt_pk_bf16_f32 v39, v42, v43
	global_store_dwordx4 v[58:59], v[36:39], off
	v_pk_fma_f32 v[40:41], v[50:51], s[16:17], v[34:35] op_sel_hi:[1,0,1]
	v_pk_fma_f32 v[34:35], v[68:69], s[16:17], v[32:33] op_sel_hi:[1,0,1]
	global_load_dwordx4 v[36:39], v[60:61], off
	v_cvt_pk_bf16_f32 v32, v52, v53
	v_cvt_pk_bf16_f32 v33, v48, v49
	v_cvt_pk_bf16_f32 v34, v34, v35
	v_cvt_pk_bf16_f32 v35, v40, v41
	global_store_dwordx4 v[58:59], v[32:35], off offset:256
	global_load_dwordx4 v[32:35], v[60:61], off offset:256
	v_add_u32_e32 v40, 0xb0, v150
	v_ashrrev_i32_e32 v41, 31, v40
	v_lshlrev_b64 v[40:41], 12, v[40:41]
	v_lshl_add_u64 v[42:43], s[56:57], 0, v[56:57]
	v_lshl_add_u64 v[44:45], s[50:51], 0, v[40:41]
	v_lshl_add_u64 v[42:43], v[42:43], 0, v[148:149]
	v_lshl_add_u64 v[44:45], v[44:45], 0, v[148:149]
	s_waitcnt vmcnt(2)
	v_lshlrev_b32_e32 v48, 16, v38
	v_and_b32_e32 v49, 0xffff0000, v38
	v_pk_fma_f32 v[24:25], v[48:49], s[16:17], v[24:25] op_sel_hi:[1,0,1]
	v_lshlrev_b32_e32 v46, 16, v36
	v_and_b32_e32 v47, 0xffff0000, v36
	v_lshlrev_b32_e32 v36, 16, v37
	s_waitcnt vmcnt(0)
	v_lshlrev_b32_e32 v50, 16, v32
	v_and_b32_e32 v51, 0xffff0000, v32
	v_lshlrev_b32_e32 v32, 16, v33
	v_and_b32_e32 v33, 0xffff0000, v33
	v_lshlrev_b32_e32 v52, 16, v34
	v_and_b32_e32 v53, 0xffff0000, v34
	v_lshlrev_b32_e32 v34, 16, v35
	v_and_b32_e32 v35, 0xffff0000, v35
	v_and_b32_e32 v37, 0xffff0000, v37
	v_lshlrev_b32_e32 v38, 16, v39
	v_and_b32_e32 v39, 0xffff0000, v39
	v_pk_fma_f32 v[32:33], v[32:33], s[16:17], v[22:23] op_sel_hi:[1,0,1]
	v_cvt_pk_bf16_f32 v22, v24, v25
	v_pk_fma_f32 v[24:25], v[34:35], s[16:17], v[18:19] op_sel_hi:[1,0,1]
	v_pk_fma_f32 v[18:19], v[52:53], s[16:17], v[16:17] op_sel_hi:[1,0,1]
	v_pk_fma_f32 v[30:31], v[36:37], s[16:17], v[30:31] op_sel_hi:[1,0,1]
	v_pk_fma_f32 v[28:29], v[46:47], s[16:17], v[28:29] op_sel_hi:[1,0,1]
	v_pk_fma_f32 v[26:27], v[38:39], s[16:17], v[26:27] op_sel_hi:[1,0,1]
	v_pk_fma_f32 v[36:37], v[50:51], s[16:17], v[20:21] op_sel_hi:[1,0,1]
	v_cvt_pk_bf16_f32 v20, v28, v29
	v_cvt_pk_bf16_f32 v21, v30, v31
	v_cvt_pk_bf16_f32 v23, v26, v27
	global_store_dwordx4 v[42:43], v[20:23], off
	v_cvt_pk_bf16_f32 v16, v36, v37
	v_cvt_pk_bf16_f32 v17, v32, v33
	v_cvt_pk_bf16_f32 v18, v18, v19
	v_cvt_pk_bf16_f32 v19, v24, v25
	global_store_dwordx4 v[42:43], v[16:19], off offset:256
	global_load_dwordx4 v[20:23], v[44:45], off
	v_lshl_add_u64 v[24:25], s[56:57], 0, v[40:41]
	global_load_dwordx4 v[16:19], v[44:45], off offset:256
	v_lshl_add_u64 v[24:25], v[24:25], 0, v[148:149]
	s_waitcnt vmcnt(1)
	v_lshlrev_b32_e32 v26, 16, v20
	v_and_b32_e32 v27, 0xffff0000, v20
	v_lshlrev_b32_e32 v20, 16, v21
	v_and_b32_e32 v21, 0xffff0000, v21
	v_lshlrev_b32_e32 v28, 16, v22
	v_and_b32_e32 v29, 0xffff0000, v22
	v_lshlrev_b32_e32 v22, 16, v23
	v_and_b32_e32 v23, 0xffff0000, v23
	s_waitcnt vmcnt(0)
	v_lshlrev_b32_e32 v30, 16, v16
	v_and_b32_e32 v31, 0xffff0000, v16
	v_lshlrev_b32_e32 v16, 16, v17
	v_and_b32_e32 v17, 0xffff0000, v17
	v_lshlrev_b32_e32 v32, 16, v18
	v_and_b32_e32 v33, 0xffff0000, v18
	v_lshlrev_b32_e32 v18, 16, v19
	v_and_b32_e32 v19, 0xffff0000, v19
	v_pk_fma_f32 v[14:15], v[20:21], s[16:17], v[14:15] op_sel_hi:[1,0,1]
	v_pk_fma_f32 v[12:13], v[26:27], s[16:17], v[12:13] op_sel_hi:[1,0,1]
	v_pk_fma_f32 v[10:11], v[22:23], s[16:17], v[10:11] op_sel_hi:[1,0,1]
	v_pk_fma_f32 v[8:9], v[28:29], s[16:17], v[8:9] op_sel_hi:[1,0,1]
	v_pk_fma_f32 v[6:7], v[16:17], s[16:17], v[6:7] op_sel_hi:[1,0,1]
	v_pk_fma_f32 v[4:5], v[30:31], s[16:17], v[4:5] op_sel_hi:[1,0,1]
	v_pk_fma_f32 v[16:17], v[18:19], s[16:17], v[2:3] op_sel_hi:[1,0,1]
	v_pk_fma_f32 v[18:19], v[32:33], s[16:17], v[0:1] op_sel_hi:[1,0,1]
	v_cvt_pk_bf16_f32 v0, v12, v13
	v_cvt_pk_bf16_f32 v1, v14, v15
	v_cvt_pk_bf16_f32 v2, v8, v9
	v_cvt_pk_bf16_f32 v3, v10, v11
	v_cvt_pk_bf16_f32 v4, v4, v5
	v_cvt_pk_bf16_f32 v5, v6, v7
	s_nop 0
	v_cvt_pk_bf16_f32 v6, v18, v19
	v_cvt_pk_bf16_f32 v7, v16, v17
	global_store_dwordx4 v[24:25], v[0:3], off
	global_store_dwordx4 v[24:25], v[4:7], off offset:256
	s_cbranch_vccnz .LBB0_1641
	s_andn2_b64 vcc, exec, s[10:11]
	s_cbranch_vccnz .LBB0_1640
	s_barrier
	s_branch .LBB0_1640

.LBB0_1808:
	s_add_u32 s36, s36, 0x80080
	s_addc_u32 s37, s37, 0
	s_add_u32 s11, s38, 0x100
	v_mov_b32_e32 v0, 0
	s_addc_u32 s14, s39, 0
	s_mov_b32 s69, -2
	v_mov_b32_e32 v1, v0
	v_mov_b32_e32 v2, v0
	v_mov_b32_e32 v3, v0
	v_mov_b32_e32 v4, v0
	v_mov_b32_e32 v5, v0
	v_mov_b32_e32 v6, v0
	v_mov_b32_e32 v7, v0
	v_mov_b32_e32 v16, v0
	v_mov_b32_e32 v17, v0
	v_mov_b32_e32 v18, v0
	v_mov_b32_e32 v19, v0
	v_mov_b32_e32 v20, v0
	v_mov_b32_e32 v21, v0
	v_mov_b32_e32 v22, v0
	v_mov_b32_e32 v23, v0
	v_mov_b32_e32 v32, v0
	v_mov_b32_e32 v33, v0
	v_mov_b32_e32 v34, v0
	v_mov_b32_e32 v35, v0
	v_mov_b32_e32 v36, v0
	v_mov_b32_e32 v37, v0
	v_mov_b32_e32 v38, v0
	v_mov_b32_e32 v39, v0
	v_mov_b32_e32 v48, v0
	v_mov_b32_e32 v49, v0
	v_mov_b32_e32 v50, v0
	v_mov_b32_e32 v51, v0
	v_mov_b32_e32 v52, v0
	v_mov_b32_e32 v53, v0
	v_mov_b32_e32 v54, v0
	v_mov_b32_e32 v55, v0
	v_mov_b32_e32 v8, v0
	v_mov_b32_e32 v9, v0
	v_mov_b32_e32 v10, v0
	v_mov_b32_e32 v11, v0
	v_mov_b32_e32 v12, v0
	v_mov_b32_e32 v13, v0
	v_mov_b32_e32 v14, v0
	v_mov_b32_e32 v15, v0
	v_mov_b32_e32 v24, v0
	v_mov_b32_e32 v25, v0
	v_mov_b32_e32 v26, v0
	v_mov_b32_e32 v27, v0
	v_mov_b32_e32 v28, v0
	v_mov_b32_e32 v29, v0
	v_mov_b32_e32 v30, v0
	v_mov_b32_e32 v31, v0
	v_mov_b32_e32 v40, v0
	v_mov_b32_e32 v41, v0
	v_mov_b32_e32 v42, v0
	v_mov_b32_e32 v43, v0
	v_mov_b32_e32 v44, v0
	v_mov_b32_e32 v45, v0
	v_mov_b32_e32 v46, v0
	v_mov_b32_e32 v47, v0
	v_mov_b32_e32 v56, v0
	v_mov_b32_e32 v57, v0
	v_mov_b32_e32 v58, v0
	v_mov_b32_e32 v59, v0
	v_mov_b32_e32 v60, v0
	v_mov_b32_e32 v61, v0
	v_mov_b32_e32 v62, v0
	v_mov_b32_e32 v63, v0
	v_mov_b32_e32 v64, v0
	v_mov_b32_e32 v65, v0
	v_mov_b32_e32 v66, v0
	v_mov_b32_e32 v67, v0
	v_mov_b32_e32 v68, v0
	v_mov_b32_e32 v69, v0
	v_mov_b32_e32 v70, v0
	v_mov_b32_e32 v71, v0
	v_mov_b32_e32 v80, v0
	v_mov_b32_e32 v81, v0
	v_mov_b32_e32 v82, v0
	v_mov_b32_e32 v83, v0
	v_mov_b32_e32 v84, v0
	v_mov_b32_e32 v85, v0
	v_mov_b32_e32 v86, v0
	v_mov_b32_e32 v87, v0
	v_mov_b32_e32 v96, v0
	v_mov_b32_e32 v97, v0
	v_mov_b32_e32 v98, v0
	v_mov_b32_e32 v99, v0
	v_mov_b32_e32 v100, v0
	v_mov_b32_e32 v101, v0
	v_mov_b32_e32 v102, v0
	v_mov_b32_e32 v103, v0
	v_mov_b32_e32 v112, v0
	v_mov_b32_e32 v113, v0
	v_mov_b32_e32 v114, v0
	v_mov_b32_e32 v115, v0
	v_mov_b32_e32 v116, v0
	v_mov_b32_e32 v117, v0
	v_mov_b32_e32 v118, v0
	v_mov_b32_e32 v119, v0
	v_mov_b32_e32 v72, v0
	v_mov_b32_e32 v73, v0
	v_mov_b32_e32 v74, v0
	v_mov_b32_e32 v75, v0
	v_mov_b32_e32 v76, v0
	v_mov_b32_e32 v77, v0
	v_mov_b32_e32 v78, v0
	v_mov_b32_e32 v79, v0
	v_mov_b32_e32 v88, v0
	v_mov_b32_e32 v89, v0
	v_mov_b32_e32 v90, v0
	v_mov_b32_e32 v91, v0
	v_mov_b32_e32 v92, v0
	v_mov_b32_e32 v93, v0
	v_mov_b32_e32 v94, v0
	v_mov_b32_e32 v95, v0
	v_mov_b32_e32 v104, v0
	v_mov_b32_e32 v105, v0
	v_mov_b32_e32 v106, v0
	v_mov_b32_e32 v107, v0
	v_mov_b32_e32 v108, v0
	v_mov_b32_e32 v109, v0
	v_mov_b32_e32 v110, v0
	v_mov_b32_e32 v111, v0
	v_mov_b32_e32 v120, v0
	v_mov_b32_e32 v121, v0
	v_mov_b32_e32 v122, v0
	v_mov_b32_e32 v123, v0
	v_mov_b32_e32 v124, v0
	v_mov_b32_e32 v125, v0
	v_mov_b32_e32 v126, v0
	v_mov_b32_e32 v127, v0
	s_cmp_eq_u64 s[20:21], 0
	s_cbranch_scc0 .Lprio_skip_6
	s_setprio 1
.Lprio_skip_6:
.LBB0_1809:
	ds_read_b128 v[162:165], v158
	ds_read_b128 v[166:169], v158 offset:1024
	ds_read_b128 v[170:173], v158 offset:2048
	ds_read_b128 v[174:177], v158 offset:3072
	ds_read_b128 v[178:181], v159
	ds_read_b128 v[182:185], v159 offset:1024
	ds_read_b128 v[186:189], v159 offset:2048
	ds_read_b128 v[190:193], v159 offset:3072
	s_add_u32 s38, s36, 0xfff80080
	s_addc_u32 s39, s37, -1
	s_cmp_eq_u32 s69, 28
	s_cselect_b32 s41, s25, s39
	s_cselect_b32 s40, s24, s38
	s_cselect_b32 s39, s27, s14
	s_cselect_b32 s38, s26, s11
	v_lshl_add_u64 v[150:151], s[36:37], 0, v[142:143]
	s_add_i32 m0, s42, 0xc000
	ds_read_b128 v[194:197], v160
	ds_read_b128 v[198:201], v160 offset:1024
	ds_read_b128 v[202:205], v160 offset:2048
	ds_read_b128 v[206:209], v160 offset:3072
	ds_read_b128 v[210:213], v160 offset:4096
	ds_read_b128 v[214:217], v160 offset:5120
	ds_read_b128 v[218:221], v160 offset:6144
	ds_read_b128 v[222:225], v160 offset:7168
	global_load_lds_dwordx4 v[150:151], off
	v_lshl_add_u64 v[150:151], s[36:37], 0, v[144:145]
	s_add_i32 m0, s42, 0xe000
	s_nop 0
	global_load_lds_dwordx4 v[150:151], off
	s_waitcnt vmcnt(8)
	s_waitcnt lgkmcnt(0)
	s_barrier
	s_waitcnt lgkmcnt(0)
	v_mfma_f32_16x16x32_bf16 v[124:127], v[162:165], v[194:197], v[124:127]
	v_mfma_f32_16x16x32_bf16 v[120:123], v[170:173], v[194:197], v[120:123]
	v_mfma_f32_16x16x32_bf16 v[108:111], v[162:165], v[202:205], v[108:111]
	v_mfma_f32_16x16x32_bf16 v[104:107], v[170:173], v[202:205], v[104:107]
	v_mfma_f32_16x16x32_bf16 v[92:95], v[162:165], v[210:213], v[92:95]
	v_mfma_f32_16x16x32_bf16 v[88:91], v[170:173], v[210:213], v[88:91]
	v_mfma_f32_16x16x32_bf16 v[76:79], v[162:165], v[218:221], v[76:79]
	v_mfma_f32_16x16x32_bf16 v[72:75], v[170:173], v[218:221], v[72:75]
	v_mfma_f32_16x16x32_bf16 v[124:127], v[166:169], v[198:201], v[124:127]
	v_mfma_f32_16x16x32_bf16 v[120:123], v[174:177], v[198:201], v[120:123]
	v_mfma_f32_16x16x32_bf16 v[108:111], v[166:169], v[206:209], v[108:111]
	v_mfma_f32_16x16x32_bf16 v[104:107], v[174:177], v[206:209], v[104:107]
	v_mfma_f32_16x16x32_bf16 v[92:95], v[166:169], v[214:217], v[92:95]
	v_mfma_f32_16x16x32_bf16 v[88:91], v[174:177], v[214:217], v[88:91]
	v_mfma_f32_16x16x32_bf16 v[76:79], v[166:169], v[222:225], v[76:79]
	v_mfma_f32_16x16x32_bf16 v[72:75], v[174:177], v[222:225], v[72:75]
	v_mfma_f32_16x16x32_bf16 v[116:119], v[178:181], v[194:197], v[116:119]
	v_mfma_f32_16x16x32_bf16 v[112:115], v[186:189], v[194:197], v[112:115]
	v_mfma_f32_16x16x32_bf16 v[100:103], v[178:181], v[202:205], v[100:103]
	v_mfma_f32_16x16x32_bf16 v[96:99], v[186:189], v[202:205], v[96:99]
	v_mfma_f32_16x16x32_bf16 v[84:87], v[178:181], v[210:213], v[84:87]
	v_mfma_f32_16x16x32_bf16 v[80:83], v[186:189], v[210:213], v[80:83]
	v_mfma_f32_16x16x32_bf16 v[68:71], v[178:181], v[218:221], v[68:71]
	v_mfma_f32_16x16x32_bf16 v[64:67], v[186:189], v[218:221], v[64:67]
	v_mfma_f32_16x16x32_bf16 v[116:119], v[182:185], v[198:201], v[116:119]
	v_mfma_f32_16x16x32_bf16 v[112:115], v[190:193], v[198:201], v[112:115]
	v_mfma_f32_16x16x32_bf16 v[100:103], v[182:185], v[206:209], v[100:103]
	v_mfma_f32_16x16x32_bf16 v[96:99], v[190:193], v[206:209], v[96:99]
	v_mfma_f32_16x16x32_bf16 v[84:87], v[182:185], v[214:217], v[84:87]
	v_mfma_f32_16x16x32_bf16 v[80:83], v[190:193], v[214:217], v[80:83]
	v_mfma_f32_16x16x32_bf16 v[68:71], v[182:185], v[222:225], v[68:71]
	v_mfma_f32_16x16x32_bf16 v[64:67], v[190:193], v[222:225], v[64:67]
	s_barrier
	s_add_i32 s70, s59, s23
	v_lshl_add_u64 v[150:151], s[38:39], 0, v[130:131]
	s_mov_b32 m0, s70
	ds_read_b128 v[194:197], v160 offset:16384
	ds_read_b128 v[198:201], v160 offset:17408
	ds_read_b128 v[202:205], v160 offset:18432
	ds_read_b128 v[206:209], v160 offset:19456
	ds_read_b128 v[210:213], v160 offset:20480
	ds_read_b128 v[214:217], v160 offset:21504
	ds_read_b128 v[218:221], v160 offset:22528
	ds_read_b128 v[222:225], v160 offset:23552
	global_load_lds_dwordx4 v[150:151], off
	s_add_i32 m0, s70, 0x2000
	s_add_u32 s70, s38, 0x80000
	v_lshl_add_u64 v[226:227], s[38:39], 0, v[134:135]
	s_addc_u32 s71, s39, 0
	s_add_i32 s72, s60, s23
	global_load_lds_dwordx4 v[226:227], off
	v_lshl_add_u64 v[228:229], s[70:71], 0, v[130:131]
	s_mov_b32 m0, s72
	v_lshl_add_u64 v[240:241], s[40:41], 0, v[132:133]
	global_load_lds_dwordx4 v[228:229], off
	v_lshl_add_u64 v[228:229], s[70:71], 0, v[134:135]
	s_add_i32 m0, s72, 0x2000
	s_nop 0
	global_load_lds_dwordx4 v[228:229], off
	v_lshl_add_u64 v[228:229], s[40:41], 0, v[128:129]
	s_mov_b32 m0, s42
	s_nop 0
	global_load_lds_dwordx4 v[228:229], off
	s_mov_b32 m0, s43
	s_nop 0
	global_load_lds_dwordx4 v[240:241], off
	s_waitcnt vmcnt(8)
	s_waitcnt lgkmcnt(0)
	s_barrier
	s_waitcnt lgkmcnt(0)
	v_mfma_f32_16x16x32_bf16 v[60:63], v[162:165], v[194:197], v[60:63]
	v_mfma_f32_16x16x32_bf16 v[56:59], v[170:173], v[194:197], v[56:59]
	v_mfma_f32_16x16x32_bf16 v[44:47], v[162:165], v[202:205], v[44:47]
	v_mfma_f32_16x16x32_bf16 v[40:43], v[170:173], v[202:205], v[40:43]
	v_mfma_f32_16x16x32_bf16 v[28:31], v[162:165], v[210:213], v[28:31]
	v_mfma_f32_16x16x32_bf16 v[24:27], v[170:173], v[210:213], v[24:27]
	v_mfma_f32_16x16x32_bf16 v[12:15], v[162:165], v[218:221], v[12:15]
	v_mfma_f32_16x16x32_bf16 v[8:11], v[170:173], v[218:221], v[8:11]
	v_mfma_f32_16x16x32_bf16 v[60:63], v[166:169], v[198:201], v[60:63]
	v_mfma_f32_16x16x32_bf16 v[56:59], v[174:177], v[198:201], v[56:59]
	v_mfma_f32_16x16x32_bf16 v[44:47], v[166:169], v[206:209], v[44:47]
	v_mfma_f32_16x16x32_bf16 v[40:43], v[174:177], v[206:209], v[40:43]
	v_mfma_f32_16x16x32_bf16 v[28:31], v[166:169], v[214:217], v[28:31]
	v_mfma_f32_16x16x32_bf16 v[24:27], v[174:177], v[214:217], v[24:27]
	v_mfma_f32_16x16x32_bf16 v[12:15], v[166:169], v[222:225], v[12:15]
	v_mfma_f32_16x16x32_bf16 v[8:11], v[174:177], v[222:225], v[8:11]
	v_mfma_f32_16x16x32_bf16 v[52:55], v[178:181], v[194:197], v[52:55]
	v_mfma_f32_16x16x32_bf16 v[48:51], v[186:189], v[194:197], v[48:51]
	v_mfma_f32_16x16x32_bf16 v[36:39], v[178:181], v[202:205], v[36:39]
	v_mfma_f32_16x16x32_bf16 v[32:35], v[186:189], v[202:205], v[32:35]
	v_mfma_f32_16x16x32_bf16 v[20:23], v[178:181], v[210:213], v[20:23]
	v_mfma_f32_16x16x32_bf16 v[16:19], v[186:189], v[210:213], v[16:19]
	v_mfma_f32_16x16x32_bf16 v[4:7], v[178:181], v[218:221], v[4:7]
	v_mfma_f32_16x16x32_bf16 v[0:3], v[186:189], v[218:221], v[0:3]
	v_mfma_f32_16x16x32_bf16 v[52:55], v[182:185], v[198:201], v[52:55]
	v_mfma_f32_16x16x32_bf16 v[48:51], v[190:193], v[198:201], v[48:51]
	v_mfma_f32_16x16x32_bf16 v[36:39], v[182:185], v[206:209], v[36:39]
	v_mfma_f32_16x16x32_bf16 v[32:35], v[190:193], v[206:209], v[32:35]
	v_mfma_f32_16x16x32_bf16 v[20:23], v[182:185], v[214:217], v[20:23]
	v_mfma_f32_16x16x32_bf16 v[16:19], v[190:193], v[214:217], v[16:19]
	v_mfma_f32_16x16x32_bf16 v[4:7], v[182:185], v[222:225], v[4:7]
	v_mfma_f32_16x16x32_bf16 v[0:3], v[190:193], v[222:225], v[0:3]
	s_barrier
	s_add_i32 s70, 0, 0x18000
	v_add_u32_e32 v161, s70, v154
	s_add_i32 s71, 0, 0x1c000
	ds_read_b128 v[162:165], v161
	ds_read_b128 v[166:169], v161 offset:1024
	ds_read_b128 v[170:173], v161 offset:2048
	ds_read_b128 v[174:177], v161 offset:3072
	v_add_u32_e32 v161, s71, v154
	ds_read_b128 v[178:181], v161
	ds_read_b128 v[182:185], v161 offset:1024
	ds_read_b128 v[186:189], v161 offset:2048
	ds_read_b128 v[190:193], v161 offset:3072
	s_add_u32 s40, s40, 0x80000
	s_addc_u32 s41, s41, 0
	s_mov_b32 m0, s44
	v_lshl_add_u64 v[242:243], s[40:41], 0, v[128:129]
	ds_read_b128 v[194:197], v160 offset:32768
	ds_read_b128 v[198:201], v160 offset:33792
	ds_read_b128 v[202:205], v160 offset:34816
	ds_read_b128 v[206:209], v160 offset:35840
	ds_read_b128 v[210:213], v160 offset:36864
	ds_read_b128 v[214:217], v160 offset:37888
	ds_read_b128 v[218:221], v160 offset:38912
	ds_read_b128 v[222:225], v160 offset:39936
	global_load_lds_dwordx4 v[242:243], off
	v_lshl_add_u64 v[242:243], s[40:41], 0, v[132:133]
	s_mov_b32 m0, s45
	s_nop 0
	global_load_lds_dwordx4 v[242:243], off
	s_waitcnt vmcnt(8)
	s_waitcnt lgkmcnt(0)
	s_barrier
	s_waitcnt lgkmcnt(0)
	v_mfma_f32_16x16x32_bf16 v[124:127], v[162:165], v[194:197], v[124:127]
	v_mfma_f32_16x16x32_bf16 v[120:123], v[170:173], v[194:197], v[120:123]
	v_mfma_f32_16x16x32_bf16 v[108:111], v[162:165], v[202:205], v[108:111]
	v_mfma_f32_16x16x32_bf16 v[104:107], v[170:173], v[202:205], v[104:107]
	v_mfma_f32_16x16x32_bf16 v[92:95], v[162:165], v[210:213], v[92:95]
	v_mfma_f32_16x16x32_bf16 v[88:91], v[170:173], v[210:213], v[88:91]
	v_mfma_f32_16x16x32_bf16 v[76:79], v[162:165], v[218:221], v[76:79]
	v_mfma_f32_16x16x32_bf16 v[72:75], v[170:173], v[218:221], v[72:75]
	v_mfma_f32_16x16x32_bf16 v[124:127], v[166:169], v[198:201], v[124:127]
	v_mfma_f32_16x16x32_bf16 v[120:123], v[174:177], v[198:201], v[120:123]
	v_mfma_f32_16x16x32_bf16 v[108:111], v[166:169], v[206:209], v[108:111]
	v_mfma_f32_16x16x32_bf16 v[104:107], v[174:177], v[206:209], v[104:107]
	v_mfma_f32_16x16x32_bf16 v[92:95], v[166:169], v[214:217], v[92:95]
	v_mfma_f32_16x16x32_bf16 v[88:91], v[174:177], v[214:217], v[88:91]
	v_mfma_f32_16x16x32_bf16 v[76:79], v[166:169], v[222:225], v[76:79]
	v_mfma_f32_16x16x32_bf16 v[72:75], v[174:177], v[222:225], v[72:75]
	v_mfma_f32_16x16x32_bf16 v[116:119], v[178:181], v[194:197], v[116:119]
	v_mfma_f32_16x16x32_bf16 v[112:115], v[186:189], v[194:197], v[112:115]
	v_mfma_f32_16x16x32_bf16 v[100:103], v[178:181], v[202:205], v[100:103]
	v_mfma_f32_16x16x32_bf16 v[96:99], v[186:189], v[202:205], v[96:99]
	v_mfma_f32_16x16x32_bf16 v[84:87], v[178:181], v[210:213], v[84:87]
	v_mfma_f32_16x16x32_bf16 v[80:83], v[186:189], v[210:213], v[80:83]
	v_mfma_f32_16x16x32_bf16 v[68:71], v[178:181], v[218:221], v[68:71]
	v_mfma_f32_16x16x32_bf16 v[64:67], v[186:189], v[218:221], v[64:67]
	v_mfma_f32_16x16x32_bf16 v[116:119], v[182:185], v[198:201], v[116:119]
	v_mfma_f32_16x16x32_bf16 v[112:115], v[190:193], v[198:201], v[112:115]
	v_mfma_f32_16x16x32_bf16 v[100:103], v[182:185], v[206:209], v[100:103]
	v_mfma_f32_16x16x32_bf16 v[96:99], v[190:193], v[206:209], v[96:99]
	v_mfma_f32_16x16x32_bf16 v[84:87], v[182:185], v[214:217], v[84:87]
	v_mfma_f32_16x16x32_bf16 v[80:83], v[190:193], v[214:217], v[80:83]
	v_mfma_f32_16x16x32_bf16 v[68:71], v[182:185], v[222:225], v[68:71]
	v_mfma_f32_16x16x32_bf16 v[64:67], v[190:193], v[222:225], v[64:67]
	s_barrier
	s_add_i32 s40, s70, s23
	v_lshl_add_u64 v[150:151], v[150:151], 0, s[18:19]
	s_mov_b32 m0, s40
	ds_read_b128 v[194:197], v160 offset:49152
	ds_read_b128 v[198:201], v160 offset:50176
	ds_read_b128 v[202:205], v160 offset:51200
	ds_read_b128 v[206:209], v160 offset:52224
	ds_read_b128 v[210:213], v160 offset:53248
	ds_read_b128 v[214:217], v160 offset:54272
	ds_read_b128 v[218:221], v160 offset:55296
	ds_read_b128 v[222:225], v160 offset:56320
	global_load_lds_dwordx4 v[150:151], off
	s_add_i32 m0, s40, 0x2000
	s_add_u32 s38, s38, 0x80080
	v_lshl_add_u64 v[150:151], v[226:227], 0, s[18:19]
	s_addc_u32 s39, s39, 0
	s_add_i32 s40, s71, s23
	global_load_lds_dwordx4 v[150:151], off
	v_lshl_add_u64 v[150:151], s[38:39], 0, v[130:131]
	s_mov_b32 m0, s40
	s_nop 0
	global_load_lds_dwordx4 v[150:151], off
	v_lshl_add_u64 v[150:151], s[38:39], 0, v[134:135]
	s_add_i32 m0, s40, 0x2000
	s_nop 0
	global_load_lds_dwordx4 v[150:151], off
	v_lshl_add_u64 v[150:151], v[228:229], 0, s[18:19]
	s_mov_b32 m0, s47
	s_nop 0
	global_load_lds_dwordx4 v[150:151], off
	v_lshl_add_u64 v[150:151], v[240:241], 0, s[18:19]
	s_mov_b32 m0, s58
	s_nop 0
	global_load_lds_dwordx4 v[150:151], off
	s_waitcnt vmcnt(8)
	s_waitcnt lgkmcnt(0)
	s_barrier
	s_waitcnt lgkmcnt(0)
	v_mfma_f32_16x16x32_bf16 v[60:63], v[162:165], v[194:197], v[60:63]
	v_mfma_f32_16x16x32_bf16 v[56:59], v[170:173], v[194:197], v[56:59]
	v_mfma_f32_16x16x32_bf16 v[44:47], v[162:165], v[202:205], v[44:47]
	v_mfma_f32_16x16x32_bf16 v[40:43], v[170:173], v[202:205], v[40:43]
	v_mfma_f32_16x16x32_bf16 v[28:31], v[162:165], v[210:213], v[28:31]
	v_mfma_f32_16x16x32_bf16 v[24:27], v[170:173], v[210:213], v[24:27]
	v_mfma_f32_16x16x32_bf16 v[12:15], v[162:165], v[218:221], v[12:15]
	v_mfma_f32_16x16x32_bf16 v[8:11], v[170:173], v[218:221], v[8:11]
	v_mfma_f32_16x16x32_bf16 v[60:63], v[166:169], v[198:201], v[60:63]
	v_mfma_f32_16x16x32_bf16 v[56:59], v[174:177], v[198:201], v[56:59]
	v_mfma_f32_16x16x32_bf16 v[44:47], v[166:169], v[206:209], v[44:47]
	v_mfma_f32_16x16x32_bf16 v[40:43], v[174:177], v[206:209], v[40:43]
	v_mfma_f32_16x16x32_bf16 v[28:31], v[166:169], v[214:217], v[28:31]
	v_mfma_f32_16x16x32_bf16 v[24:27], v[174:177], v[214:217], v[24:27]
	v_mfma_f32_16x16x32_bf16 v[12:15], v[166:169], v[222:225], v[12:15]
	v_mfma_f32_16x16x32_bf16 v[8:11], v[174:177], v[222:225], v[8:11]
	v_mfma_f32_16x16x32_bf16 v[52:55], v[178:181], v[194:197], v[52:55]
	v_mfma_f32_16x16x32_bf16 v[48:51], v[186:189], v[194:197], v[48:51]
	v_mfma_f32_16x16x32_bf16 v[36:39], v[178:181], v[202:205], v[36:39]
	v_mfma_f32_16x16x32_bf16 v[32:35], v[186:189], v[202:205], v[32:35]
	v_mfma_f32_16x16x32_bf16 v[20:23], v[178:181], v[210:213], v[20:23]
	v_mfma_f32_16x16x32_bf16 v[16:19], v[186:189], v[210:213], v[16:19]
	v_mfma_f32_16x16x32_bf16 v[4:7], v[178:181], v[218:221], v[4:7]
	v_mfma_f32_16x16x32_bf16 v[0:3], v[186:189], v[218:221], v[0:3]
	v_mfma_f32_16x16x32_bf16 v[52:55], v[182:185], v[198:201], v[52:55]
	v_mfma_f32_16x16x32_bf16 v[48:51], v[190:193], v[198:201], v[48:51]
	v_mfma_f32_16x16x32_bf16 v[36:39], v[182:185], v[206:209], v[36:39]
	v_mfma_f32_16x16x32_bf16 v[32:35], v[190:193], v[206:209], v[32:35]
	v_mfma_f32_16x16x32_bf16 v[20:23], v[182:185], v[214:217], v[20:23]
	v_mfma_f32_16x16x32_bf16 v[16:19], v[190:193], v[214:217], v[16:19]
	v_mfma_f32_16x16x32_bf16 v[4:7], v[182:185], v[222:225], v[4:7]
	v_mfma_f32_16x16x32_bf16 v[0:3], v[190:193], v[222:225], v[0:3]
	s_barrier
	s_add_i32 s69, s69, 2
	s_add_u32 s36, s36, 0x100
	s_addc_u32 s37, s37, 0
	s_add_u32 s11, s11, 0x100
	s_addc_u32 s14, s14, 0
	s_cmp_gt_u32 s69, 29
	s_cbranch_scc0 .LBB0_1809
	s_and_b64 vcc, exec, s[20:21]
	s_cbranch_vccz .LBB0_1812
	s_barrier
.LBB0_1812:
	s_setprio 0
	v_add_u32_e32 v150, s68, v153
	v_cmp_gt_i32_e32 vcc, s61, v150
	s_and_saveexec_b64 s[36:37], vcc
	s_cbranch_execz .LBB0_1814
	v_ashrrev_i32_e32 v151, 31, v150
	v_pk_mul_f32 v[124:125], v[124:125], s[22:23] op_sel_hi:[1,0]
	v_pk_mul_f32 v[162:163], v[122:123], s[22:23] op_sel_hi:[1,0]
	v_pk_mul_f32 v[122:123], v[120:121], s[22:23] op_sel_hi:[1,0]
	v_cvt_pk_bf16_f32 v120, v124, v125
	v_lshlrev_b64 v[124:125], 12, v[150:151]
	v_lshl_add_u64 v[124:125], s[16:17], 0, v[124:125]
	s_ashr_i32 s11, s10, 31
	v_lshl_add_u64 v[124:125], s[10:11], 1, v[124:125]
	s_lshl_b32 s14, s46, 1
	v_lshl_add_u64 v[124:125], v[124:125], 0, s[14:15]
	v_pk_mul_f32 v[126:127], v[126:127], s[22:23] op_sel_hi:[1,0]
	v_lshl_add_u64 v[124:125], v[124:125], 0, v[140:141]
	v_cvt_pk_bf16_f32 v121, v126, v127
	v_cvt_pk_bf16_f32 v122, v122, v123
	v_cvt_pk_bf16_f32 v123, v162, v163
	global_store_dwordx4 v[124:125], v[120:123], off
	v_pk_mul_f32 v[118:119], v[118:119], s[22:23] op_sel_hi:[1,0]
	v_pk_mul_f32 v[116:117], v[116:117], s[22:23] op_sel_hi:[1,0]
	v_pk_mul_f32 v[120:121], v[114:115], s[22:23] op_sel_hi:[1,0]
	v_pk_mul_f32 v[114:115], v[112:113], s[22:23] op_sel_hi:[1,0]
	v_cvt_pk_bf16_f32 v112, v116, v117
	v_cvt_pk_bf16_f32 v113, v118, v119
	s_nop 0
	v_cvt_pk_bf16_f32 v114, v114, v115
	v_cvt_pk_bf16_f32 v115, v120, v121
	global_store_dwordx4 v[124:125], v[112:115], off offset:256

.LBB0_1909:
	s_add_u32 s70, s38, 0x100
	s_addc_u32 s71, s39, 0
	v_lshl_add_u64 v[150:151], s[36:37], 0, v[142:143]
	v_lshl_add_u64 v[152:153], s[36:37], 0, v[144:145]
	s_mov_b32 s72, -2
	s_mov_b64 s[38:39], 0
	s_cmp_eq_u64 s[20:21], 0
	s_cbranch_scc0 .Lprio_skip_7
	s_setprio 1
.Lprio_skip_7:
.LBB0_1910:
	v_add_u32_e32 v157, s65, v155
	ds_read_b128 v[158:161], v157
	ds_read_b128 v[162:165], v157 offset:1024
	ds_read_b128 v[166:169], v157 offset:2048
	ds_read_b128 v[170:173], v157 offset:3072
	v_add_u32_e32 v157, s66, v155
	s_add_u32 s40, s36, s38
	ds_read_b128 v[174:177], v157
	ds_read_b128 v[178:181], v157 offset:1024
	ds_read_b128 v[182:185], v157 offset:2048
	ds_read_b128 v[186:189], v157 offset:3072
	s_addc_u32 s41, s37, s39
	s_add_u32 s40, s40, 0x100
	s_addc_u32 s41, s41, 0
	s_add_u32 s73, s70, s38
	s_addc_u32 s74, s71, s39
	s_cmpk_eq_i32 s38, 0x300
	s_cselect_b32 s43, s25, s41
	s_cselect_b32 s42, s24, s40
	s_cselect_b32 s41, s27, s74
	s_cselect_b32 s40, s26, s73
	s_mov_b32 m0, s67
	v_lshl_add_u64 v[222:223], v[150:151], 0, s[38:39]
	ds_read_b128 v[190:193], v156
	ds_read_b128 v[194:197], v156 offset:1024
	ds_read_b128 v[198:201], v156 offset:2048
	ds_read_b128 v[202:205], v156 offset:3072
	ds_read_b128 v[206:209], v156 offset:4096
	ds_read_b128 v[210:213], v156 offset:5120
	ds_read_b128 v[214:217], v156 offset:6144
	ds_read_b128 v[218:221], v156 offset:7168
	global_load_lds_dwordx4 v[222:223], off
	v_lshl_add_u64 v[222:223], v[152:153], 0, s[38:39]
	s_add_i32 m0, s58, 0xe000
	s_nop 0
	global_load_lds_dwordx4 v[222:223], off
	s_waitcnt vmcnt(8)
	s_waitcnt lgkmcnt(0)
	s_barrier
	s_waitcnt lgkmcnt(0)
	v_mfma_f32_16x16x32_bf16 v[124:127], v[158:161], v[190:193], v[124:127]
	v_mfma_f32_16x16x32_bf16 v[120:123], v[166:169], v[190:193], v[120:123]
	v_mfma_f32_16x16x32_bf16 v[112:115], v[158:161], v[198:201], v[112:115]
	v_mfma_f32_16x16x32_bf16 v[104:107], v[166:169], v[198:201], v[104:107]
	v_mfma_f32_16x16x32_bf16 v[96:99], v[158:161], v[206:209], v[96:99]
	v_mfma_f32_16x16x32_bf16 v[88:91], v[166:169], v[206:209], v[88:91]
	v_mfma_f32_16x16x32_bf16 v[80:83], v[158:161], v[214:217], v[80:83]
	v_mfma_f32_16x16x32_bf16 v[72:75], v[166:169], v[214:217], v[72:75]
	v_mfma_f32_16x16x32_bf16 v[124:127], v[162:165], v[194:197], v[124:127]
	v_mfma_f32_16x16x32_bf16 v[120:123], v[170:173], v[194:197], v[120:123]
	v_mfma_f32_16x16x32_bf16 v[112:115], v[162:165], v[202:205], v[112:115]
	v_mfma_f32_16x16x32_bf16 v[104:107], v[170:173], v[202:205], v[104:107]
	v_mfma_f32_16x16x32_bf16 v[96:99], v[162:165], v[210:213], v[96:99]
	v_mfma_f32_16x16x32_bf16 v[88:91], v[170:173], v[210:213], v[88:91]
	v_mfma_f32_16x16x32_bf16 v[80:83], v[162:165], v[218:221], v[80:83]
	v_mfma_f32_16x16x32_bf16 v[72:75], v[170:173], v[218:221], v[72:75]
	v_mfma_f32_16x16x32_bf16 v[116:119], v[174:177], v[190:193], v[116:119]
	v_mfma_f32_16x16x32_bf16 v[108:111], v[182:185], v[190:193], v[108:111]
	v_mfma_f32_16x16x32_bf16 v[100:103], v[174:177], v[198:201], v[100:103]
	v_mfma_f32_16x16x32_bf16 v[92:95], v[182:185], v[198:201], v[92:95]
	v_mfma_f32_16x16x32_bf16 v[84:87], v[174:177], v[206:209], v[84:87]
	v_mfma_f32_16x16x32_bf16 v[76:79], v[182:185], v[206:209], v[76:79]
	v_mfma_f32_16x16x32_bf16 v[68:71], v[174:177], v[214:217], v[68:71]
	v_mfma_f32_16x16x32_bf16 v[64:67], v[182:185], v[214:217], v[64:67]
	v_mfma_f32_16x16x32_bf16 v[116:119], v[178:181], v[194:197], v[116:119]
	v_mfma_f32_16x16x32_bf16 v[108:111], v[186:189], v[194:197], v[108:111]
	v_mfma_f32_16x16x32_bf16 v[100:103], v[178:181], v[202:205], v[100:103]
	v_mfma_f32_16x16x32_bf16 v[92:95], v[186:189], v[202:205], v[92:95]
	v_mfma_f32_16x16x32_bf16 v[84:87], v[178:181], v[210:213], v[84:87]
	v_mfma_f32_16x16x32_bf16 v[76:79], v[186:189], v[210:213], v[76:79]
	v_mfma_f32_16x16x32_bf16 v[68:71], v[178:181], v[218:221], v[68:71]
	v_mfma_f32_16x16x32_bf16 v[64:67], v[186:189], v[218:221], v[64:67]
	s_barrier
	s_add_i32 s73, s65, s11
	v_lshl_add_u64 v[222:223], s[40:41], 0, v[134:135]
	s_mov_b32 m0, s73
	ds_read_b128 v[190:193], v156 offset:16384
	ds_read_b128 v[194:197], v156 offset:17408
	ds_read_b128 v[198:201], v156 offset:18432
	ds_read_b128 v[202:205], v156 offset:19456
	ds_read_b128 v[206:209], v156 offset:20480
	ds_read_b128 v[210:213], v156 offset:21504
	ds_read_b128 v[214:217], v156 offset:22528
	ds_read_b128 v[218:221], v156 offset:23552
	global_load_lds_dwordx4 v[222:223], off
	s_add_i32 m0, s73, 0x2000
	s_add_u32 s74, s40, 0x80000
	v_lshl_add_u64 v[224:225], s[40:41], 0, v[130:131]
	s_addc_u32 s75, s41, 0
	s_add_i32 s73, s66, s11
	global_load_lds_dwordx4 v[224:225], off
	v_lshl_add_u64 v[226:227], s[74:75], 0, v[134:135]
	s_mov_b32 m0, s73
	v_lshl_add_u64 v[228:229], s[42:43], 0, v[132:133]
	global_load_lds_dwordx4 v[226:227], off
	v_lshl_add_u64 v[226:227], s[74:75], 0, v[130:131]
	s_add_i32 m0, s73, 0x2000
	s_nop 0
	global_load_lds_dwordx4 v[226:227], off
	v_lshl_add_u64 v[226:227], s[42:43], 0, v[140:141]
	s_mov_b32 m0, s58
	s_nop 0
	global_load_lds_dwordx4 v[226:227], off
	s_mov_b32 m0, s59
	s_nop 0
	global_load_lds_dwordx4 v[228:229], off
	s_waitcnt vmcnt(8)
	s_waitcnt lgkmcnt(0)
	s_barrier
	s_waitcnt lgkmcnt(0)
	v_mfma_f32_16x16x32_bf16 v[60:63], v[158:161], v[190:193], v[60:63]
	v_mfma_f32_16x16x32_bf16 v[56:59], v[166:169], v[190:193], v[56:59]
	v_mfma_f32_16x16x32_bf16 v[48:51], v[158:161], v[198:201], v[48:51]
	v_mfma_f32_16x16x32_bf16 v[40:43], v[166:169], v[198:201], v[40:43]
	v_mfma_f32_16x16x32_bf16 v[32:35], v[158:161], v[206:209], v[32:35]
	v_mfma_f32_16x16x32_bf16 v[24:27], v[166:169], v[206:209], v[24:27]
	v_mfma_f32_16x16x32_bf16 v[16:19], v[158:161], v[214:217], v[16:19]
	v_mfma_f32_16x16x32_bf16 v[8:11], v[166:169], v[214:217], v[8:11]
	v_mfma_f32_16x16x32_bf16 v[60:63], v[162:165], v[194:197], v[60:63]
	v_mfma_f32_16x16x32_bf16 v[56:59], v[170:173], v[194:197], v[56:59]
	v_mfma_f32_16x16x32_bf16 v[48:51], v[162:165], v[202:205], v[48:51]
	v_mfma_f32_16x16x32_bf16 v[40:43], v[170:173], v[202:205], v[40:43]
	v_mfma_f32_16x16x32_bf16 v[32:35], v[162:165], v[210:213], v[32:35]
	v_mfma_f32_16x16x32_bf16 v[24:27], v[170:173], v[210:213], v[24:27]
	v_mfma_f32_16x16x32_bf16 v[16:19], v[162:165], v[218:221], v[16:19]
	v_mfma_f32_16x16x32_bf16 v[8:11], v[170:173], v[218:221], v[8:11]
	v_mfma_f32_16x16x32_bf16 v[52:55], v[174:177], v[190:193], v[52:55]
	v_mfma_f32_16x16x32_bf16 v[44:47], v[182:185], v[190:193], v[44:47]
	v_mfma_f32_16x16x32_bf16 v[36:39], v[174:177], v[198:201], v[36:39]
	v_mfma_f32_16x16x32_bf16 v[28:31], v[182:185], v[198:201], v[28:31]
	v_mfma_f32_16x16x32_bf16 v[20:23], v[174:177], v[206:209], v[20:23]
	v_mfma_f32_16x16x32_bf16 v[12:15], v[182:185], v[206:209], v[12:15]
	v_mfma_f32_16x16x32_bf16 v[4:7], v[174:177], v[214:217], v[4:7]
	v_mfma_f32_16x16x32_bf16 v[0:3], v[182:185], v[214:217], v[0:3]
	v_mfma_f32_16x16x32_bf16 v[52:55], v[178:181], v[194:197], v[52:55]
	v_mfma_f32_16x16x32_bf16 v[44:47], v[186:189], v[194:197], v[44:47]
	v_mfma_f32_16x16x32_bf16 v[36:39], v[178:181], v[202:205], v[36:39]
	v_mfma_f32_16x16x32_bf16 v[28:31], v[186:189], v[202:205], v[28:31]
	v_mfma_f32_16x16x32_bf16 v[20:23], v[178:181], v[210:213], v[20:23]
	v_mfma_f32_16x16x32_bf16 v[12:15], v[186:189], v[210:213], v[12:15]
	v_mfma_f32_16x16x32_bf16 v[4:7], v[178:181], v[218:221], v[4:7]
	v_mfma_f32_16x16x32_bf16 v[0:3], v[186:189], v[218:221], v[0:3]
	s_barrier
	s_add_i32 s73, 0, 0x18000
	v_add_u32_e32 v157, s73, v155
	s_add_i32 s74, 0, 0x1c000
	ds_read_b128 v[158:161], v157
	ds_read_b128 v[162:165], v157 offset:1024
	ds_read_b128 v[166:169], v157 offset:2048
	ds_read_b128 v[170:173], v157 offset:3072
	v_add_u32_e32 v157, s74, v155
	ds_read_b128 v[174:177], v157
	ds_read_b128 v[178:181], v157 offset:1024
	ds_read_b128 v[182:185], v157 offset:2048
	ds_read_b128 v[186:189], v157 offset:3072
	s_add_u32 s42, s42, 0x80000
	s_addc_u32 s43, s43, 0
	s_mov_b32 m0, s60
	v_lshl_add_u64 v[240:241], s[42:43], 0, v[140:141]
	ds_read_b128 v[190:193], v156 offset:32768
	ds_read_b128 v[194:197], v156 offset:33792
	ds_read_b128 v[198:201], v156 offset:34816
	ds_read_b128 v[202:205], v156 offset:35840
	ds_read_b128 v[206:209], v156 offset:36864
	ds_read_b128 v[210:213], v156 offset:37888
	ds_read_b128 v[214:217], v156 offset:38912
	ds_read_b128 v[218:221], v156 offset:39936
	global_load_lds_dwordx4 v[240:241], off
	v_lshl_add_u64 v[240:241], s[42:43], 0, v[132:133]
	s_mov_b32 m0, s61
	s_nop 0
	global_load_lds_dwordx4 v[240:241], off
	s_waitcnt vmcnt(8)
	s_waitcnt lgkmcnt(0)
	s_barrier
	s_waitcnt lgkmcnt(0)
	v_mfma_f32_16x16x32_bf16 v[124:127], v[158:161], v[190:193], v[124:127]
	v_mfma_f32_16x16x32_bf16 v[120:123], v[166:169], v[190:193], v[120:123]
	v_mfma_f32_16x16x32_bf16 v[112:115], v[158:161], v[198:201], v[112:115]
	v_mfma_f32_16x16x32_bf16 v[104:107], v[166:169], v[198:201], v[104:107]
	v_mfma_f32_16x16x32_bf16 v[96:99], v[158:161], v[206:209], v[96:99]
	v_mfma_f32_16x16x32_bf16 v[88:91], v[166:169], v[206:209], v[88:91]
	v_mfma_f32_16x16x32_bf16 v[80:83], v[158:161], v[214:217], v[80:83]
	v_mfma_f32_16x16x32_bf16 v[72:75], v[166:169], v[214:217], v[72:75]
	v_mfma_f32_16x16x32_bf16 v[124:127], v[162:165], v[194:197], v[124:127]
	v_mfma_f32_16x16x32_bf16 v[120:123], v[170:173], v[194:197], v[120:123]
	v_mfma_f32_16x16x32_bf16 v[112:115], v[162:165], v[202:205], v[112:115]
	v_mfma_f32_16x16x32_bf16 v[104:107], v[170:173], v[202:205], v[104:107]
	v_mfma_f32_16x16x32_bf16 v[96:99], v[162:165], v[210:213], v[96:99]
	v_mfma_f32_16x16x32_bf16 v[88:91], v[170:173], v[210:213], v[88:91]
	v_mfma_f32_16x16x32_bf16 v[80:83], v[162:165], v[218:221], v[80:83]
	v_mfma_f32_16x16x32_bf16 v[72:75], v[170:173], v[218:221], v[72:75]
	v_mfma_f32_16x16x32_bf16 v[116:119], v[174:177], v[190:193], v[116:119]
	v_mfma_f32_16x16x32_bf16 v[108:111], v[182:185], v[190:193], v[108:111]
	v_mfma_f32_16x16x32_bf16 v[100:103], v[174:177], v[198:201], v[100:103]
	v_mfma_f32_16x16x32_bf16 v[92:95], v[182:185], v[198:201], v[92:95]
	v_mfma_f32_16x16x32_bf16 v[84:87], v[174:177], v[206:209], v[84:87]
	v_mfma_f32_16x16x32_bf16 v[76:79], v[182:185], v[206:209], v[76:79]
	v_mfma_f32_16x16x32_bf16 v[68:71], v[174:177], v[214:217], v[68:71]
	v_mfma_f32_16x16x32_bf16 v[64:67], v[182:185], v[214:217], v[64:67]
	v_mfma_f32_16x16x32_bf16 v[116:119], v[178:181], v[194:197], v[116:119]
	v_mfma_f32_16x16x32_bf16 v[108:111], v[186:189], v[194:197], v[108:111]
	v_mfma_f32_16x16x32_bf16 v[100:103], v[178:181], v[202:205], v[100:103]
	v_mfma_f32_16x16x32_bf16 v[92:95], v[186:189], v[202:205], v[92:95]
	v_mfma_f32_16x16x32_bf16 v[84:87], v[178:181], v[210:213], v[84:87]
	v_mfma_f32_16x16x32_bf16 v[76:79], v[186:189], v[210:213], v[76:79]
	v_mfma_f32_16x16x32_bf16 v[68:71], v[178:181], v[218:221], v[68:71]
	v_mfma_f32_16x16x32_bf16 v[64:67], v[186:189], v[218:221], v[64:67]
	s_barrier
	s_add_i32 s42, s73, s11
	v_lshl_add_u64 v[222:223], v[222:223], 0, s[18:19]
	s_mov_b32 m0, s42
	ds_read_b128 v[190:193], v156 offset:49152
	ds_read_b128 v[194:197], v156 offset:50176
	ds_read_b128 v[198:201], v156 offset:51200
	ds_read_b128 v[202:205], v156 offset:52224
	ds_read_b128 v[206:209], v156 offset:53248
	ds_read_b128 v[210:213], v156 offset:54272
	ds_read_b128 v[214:217], v156 offset:55296
	ds_read_b128 v[218:221], v156 offset:56320
	global_load_lds_dwordx4 v[222:223], off
	s_add_i32 m0, s42, 0x2000
	s_add_u32 s40, s40, 0x80080
	v_lshl_add_u64 v[222:223], v[224:225], 0, s[18:19]
	s_addc_u32 s41, s41, 0
	s_add_i32 s42, s74, s11
	global_load_lds_dwordx4 v[222:223], off
	v_lshl_add_u64 v[222:223], s[40:41], 0, v[134:135]
	s_mov_b32 m0, s42
	s_nop 0
	global_load_lds_dwordx4 v[222:223], off
	v_lshl_add_u64 v[222:223], s[40:41], 0, v[130:131]
	s_add_i32 m0, s42, 0x2000
	s_nop 0
	global_load_lds_dwordx4 v[222:223], off
	v_lshl_add_u64 v[222:223], v[226:227], 0, s[18:19]
	s_mov_b32 m0, s63
	s_nop 0
	global_load_lds_dwordx4 v[222:223], off
	v_lshl_add_u64 v[222:223], v[228:229], 0, s[18:19]
	s_mov_b32 m0, s64
	s_nop 0
	global_load_lds_dwordx4 v[222:223], off
	s_waitcnt vmcnt(8)
	s_waitcnt lgkmcnt(0)
	s_barrier
	s_waitcnt lgkmcnt(0)
	v_mfma_f32_16x16x32_bf16 v[60:63], v[158:161], v[190:193], v[60:63]
	v_mfma_f32_16x16x32_bf16 v[56:59], v[166:169], v[190:193], v[56:59]
	v_mfma_f32_16x16x32_bf16 v[48:51], v[158:161], v[198:201], v[48:51]
	v_mfma_f32_16x16x32_bf16 v[40:43], v[166:169], v[198:201], v[40:43]
	v_mfma_f32_16x16x32_bf16 v[32:35], v[158:161], v[206:209], v[32:35]
	v_mfma_f32_16x16x32_bf16 v[24:27], v[166:169], v[206:209], v[24:27]
	v_mfma_f32_16x16x32_bf16 v[16:19], v[158:161], v[214:217], v[16:19]
	v_mfma_f32_16x16x32_bf16 v[8:11], v[166:169], v[214:217], v[8:11]
	v_mfma_f32_16x16x32_bf16 v[60:63], v[162:165], v[194:197], v[60:63]
	v_mfma_f32_16x16x32_bf16 v[56:59], v[170:173], v[194:197], v[56:59]
	v_mfma_f32_16x16x32_bf16 v[48:51], v[162:165], v[202:205], v[48:51]
	v_mfma_f32_16x16x32_bf16 v[40:43], v[170:173], v[202:205], v[40:43]
	v_mfma_f32_16x16x32_bf16 v[32:35], v[162:165], v[210:213], v[32:35]
	v_mfma_f32_16x16x32_bf16 v[24:27], v[170:173], v[210:213], v[24:27]
	v_mfma_f32_16x16x32_bf16 v[16:19], v[162:165], v[218:221], v[16:19]
	v_mfma_f32_16x16x32_bf16 v[8:11], v[170:173], v[218:221], v[8:11]
	v_mfma_f32_16x16x32_bf16 v[52:55], v[174:177], v[190:193], v[52:55]
	v_mfma_f32_16x16x32_bf16 v[44:47], v[182:185], v[190:193], v[44:47]
	v_mfma_f32_16x16x32_bf16 v[36:39], v[174:177], v[198:201], v[36:39]
	v_mfma_f32_16x16x32_bf16 v[28:31], v[182:185], v[198:201], v[28:31]
	v_mfma_f32_16x16x32_bf16 v[20:23], v[174:177], v[206:209], v[20:23]
	v_mfma_f32_16x16x32_bf16 v[12:15], v[182:185], v[206:209], v[12:15]
	v_mfma_f32_16x16x32_bf16 v[4:7], v[174:177], v[214:217], v[4:7]
	v_mfma_f32_16x16x32_bf16 v[0:3], v[182:185], v[214:217], v[0:3]
	v_mfma_f32_16x16x32_bf16 v[52:55], v[178:181], v[194:197], v[52:55]
	v_mfma_f32_16x16x32_bf16 v[44:47], v[186:189], v[194:197], v[44:47]
	v_mfma_f32_16x16x32_bf16 v[36:39], v[178:181], v[202:205], v[36:39]
	v_mfma_f32_16x16x32_bf16 v[28:31], v[186:189], v[202:205], v[28:31]
	v_mfma_f32_16x16x32_bf16 v[20:23], v[178:181], v[210:213], v[20:23]
	v_mfma_f32_16x16x32_bf16 v[12:15], v[186:189], v[210:213], v[12:15]
	v_mfma_f32_16x16x32_bf16 v[4:7], v[178:181], v[218:221], v[4:7]
	v_mfma_f32_16x16x32_bf16 v[0:3], v[186:189], v[218:221], v[0:3]
	s_barrier
	s_add_i32 s72, s72, 2
	s_add_u32 s38, s38, 0x100
	s_addc_u32 s39, s39, 0
	s_cmp_gt_u32 s72, 5
	s_cbranch_scc0 .LBB0_1910
	s_and_b64 vcc, exec, s[20:21]
	s_cbranch_vccz .LBB0_1913
	s_barrier
.LBB0_1913:
	s_setprio 0
	s_add_u32 s38, s70, 0xffffff00
	s_addc_u32 s39, s71, -1
	s_andn2_b64 vcc, exec, s[8:9]
	s_cbranch_vccnz .LBB0_1917
	s_andn2_b64 vcc, exec, s[16:17]
	s_cbranch_vccnz .LBB0_1916
	s_barrier

.LBB0_2284:
	s_add_u32 s24, s24, 0x80080
	s_addc_u32 s25, s25, 0
	s_add_u32 s66, s26, 0x100
	v_mov_b32_e32 v0, 0
	s_addc_u32 s67, s27, 0
	s_mov_b32 s68, -2
	v_mov_b32_e32 v1, v0
	v_mov_b32_e32 v2, v0
	v_mov_b32_e32 v3, v0
	v_mov_b32_e32 v4, v0
	v_mov_b32_e32 v5, v0
	v_mov_b32_e32 v6, v0
	v_mov_b32_e32 v7, v0
	v_mov_b32_e32 v16, v0
	v_mov_b32_e32 v17, v0
	v_mov_b32_e32 v18, v0
	v_mov_b32_e32 v19, v0
	v_mov_b32_e32 v20, v0
	v_mov_b32_e32 v21, v0
	v_mov_b32_e32 v22, v0
	v_mov_b32_e32 v23, v0
	v_mov_b32_e32 v32, v0
	v_mov_b32_e32 v33, v0
	v_mov_b32_e32 v34, v0
	v_mov_b32_e32 v35, v0
	v_mov_b32_e32 v36, v0
	v_mov_b32_e32 v37, v0
	v_mov_b32_e32 v38, v0
	v_mov_b32_e32 v39, v0
	v_mov_b32_e32 v48, v0
	v_mov_b32_e32 v49, v0
	v_mov_b32_e32 v50, v0
	v_mov_b32_e32 v51, v0
	v_mov_b32_e32 v52, v0
	v_mov_b32_e32 v53, v0
	v_mov_b32_e32 v54, v0
	v_mov_b32_e32 v55, v0
	v_mov_b32_e32 v8, v0
	v_mov_b32_e32 v9, v0
	v_mov_b32_e32 v10, v0
	v_mov_b32_e32 v11, v0
	v_mov_b32_e32 v12, v0
	v_mov_b32_e32 v13, v0
	v_mov_b32_e32 v14, v0
	v_mov_b32_e32 v15, v0
	v_mov_b32_e32 v24, v0
	v_mov_b32_e32 v25, v0
	v_mov_b32_e32 v26, v0
	v_mov_b32_e32 v27, v0
	v_mov_b32_e32 v28, v0
	v_mov_b32_e32 v29, v0
	v_mov_b32_e32 v30, v0
	v_mov_b32_e32 v31, v0
	v_mov_b32_e32 v40, v0
	v_mov_b32_e32 v41, v0
	v_mov_b32_e32 v42, v0
	v_mov_b32_e32 v43, v0
	v_mov_b32_e32 v44, v0
	v_mov_b32_e32 v45, v0
	v_mov_b32_e32 v46, v0
	v_mov_b32_e32 v47, v0
	v_mov_b32_e32 v56, v0
	v_mov_b32_e32 v57, v0
	v_mov_b32_e32 v58, v0
	v_mov_b32_e32 v59, v0
	v_mov_b32_e32 v60, v0
	v_mov_b32_e32 v61, v0
	v_mov_b32_e32 v62, v0
	v_mov_b32_e32 v63, v0
	v_mov_b32_e32 v64, v0
	v_mov_b32_e32 v65, v0
	v_mov_b32_e32 v66, v0
	v_mov_b32_e32 v67, v0
	v_mov_b32_e32 v68, v0
	v_mov_b32_e32 v69, v0
	v_mov_b32_e32 v70, v0
	v_mov_b32_e32 v71, v0
	v_mov_b32_e32 v80, v0
	v_mov_b32_e32 v81, v0
	v_mov_b32_e32 v82, v0
	v_mov_b32_e32 v83, v0
	v_mov_b32_e32 v84, v0
	v_mov_b32_e32 v85, v0
	v_mov_b32_e32 v86, v0
	v_mov_b32_e32 v87, v0
	v_mov_b32_e32 v96, v0
	v_mov_b32_e32 v97, v0
	v_mov_b32_e32 v98, v0
	v_mov_b32_e32 v99, v0
	v_mov_b32_e32 v100, v0
	v_mov_b32_e32 v101, v0
	v_mov_b32_e32 v102, v0
	v_mov_b32_e32 v103, v0
	v_mov_b32_e32 v112, v0
	v_mov_b32_e32 v113, v0
	v_mov_b32_e32 v114, v0
	v_mov_b32_e32 v115, v0
	v_mov_b32_e32 v116, v0
	v_mov_b32_e32 v117, v0
	v_mov_b32_e32 v118, v0
	v_mov_b32_e32 v119, v0
	v_mov_b32_e32 v72, v0
	v_mov_b32_e32 v73, v0
	v_mov_b32_e32 v74, v0
	v_mov_b32_e32 v75, v0
	v_mov_b32_e32 v76, v0
	v_mov_b32_e32 v77, v0
	v_mov_b32_e32 v78, v0
	v_mov_b32_e32 v79, v0
	v_mov_b32_e32 v88, v0
	v_mov_b32_e32 v89, v0
	v_mov_b32_e32 v90, v0
	v_mov_b32_e32 v91, v0
	v_mov_b32_e32 v92, v0
	v_mov_b32_e32 v93, v0
	v_mov_b32_e32 v94, v0
	v_mov_b32_e32 v95, v0
	v_mov_b32_e32 v104, v0
	v_mov_b32_e32 v105, v0
	v_mov_b32_e32 v106, v0
	v_mov_b32_e32 v107, v0
	v_mov_b32_e32 v108, v0
	v_mov_b32_e32 v109, v0
	v_mov_b32_e32 v110, v0
	v_mov_b32_e32 v111, v0
	v_mov_b32_e32 v120, v0
	v_mov_b32_e32 v121, v0
	v_mov_b32_e32 v122, v0
	v_mov_b32_e32 v123, v0
	v_mov_b32_e32 v124, v0
	v_mov_b32_e32 v125, v0
	v_mov_b32_e32 v126, v0
	v_mov_b32_e32 v127, v0
	s_cmp_eq_u64 s[16:17], 0
	s_cbranch_scc0 .Lprio_skip_9
	s_setprio 1
.Lprio_skip_9:
.LBB0_2285:
	ds_read_b128 v[156:159], v152
	ds_read_b128 v[160:163], v152 offset:1024
	ds_read_b128 v[164:167], v152 offset:2048
	ds_read_b128 v[168:171], v152 offset:3072
	ds_read_b128 v[172:175], v153
	ds_read_b128 v[176:179], v153 offset:1024
	ds_read_b128 v[180:183], v153 offset:2048
	ds_read_b128 v[184:187], v153 offset:3072
	s_add_u32 s26, s24, 0xfff80080
	s_addc_u32 s27, s25, -1
	s_cmp_eq_u32 s68, 28
	s_cselect_b32 s37, s21, s27
	s_cselect_b32 s36, s20, s26
	s_cselect_b32 s27, s23, s67
	s_cselect_b32 s26, s22, s66
	v_lshl_add_u64 v[220:221], s[24:25], 0, v[144:145]
	s_add_i32 m0, s40, 0xc000
	ds_read_b128 v[188:191], v154
	ds_read_b128 v[192:195], v154 offset:1024
	ds_read_b128 v[196:199], v154 offset:2048
	ds_read_b128 v[200:203], v154 offset:3072
	ds_read_b128 v[204:207], v154 offset:4096
	ds_read_b128 v[208:211], v154 offset:5120
	ds_read_b128 v[212:215], v154 offset:6144
	ds_read_b128 v[216:219], v154 offset:7168
	global_load_lds_dwordx4 v[220:221], off
	v_lshl_add_u64 v[220:221], s[24:25], 0, v[146:147]
	s_add_i32 m0, s40, 0xe000
	s_nop 0
	global_load_lds_dwordx4 v[220:221], off
	s_waitcnt vmcnt(8)
	s_waitcnt lgkmcnt(0)
	s_barrier
	s_waitcnt lgkmcnt(0)
	v_mfma_f32_16x16x32_bf16 v[124:127], v[156:159], v[188:191], v[124:127]
	v_mfma_f32_16x16x32_bf16 v[120:123], v[164:167], v[188:191], v[120:123]
	v_mfma_f32_16x16x32_bf16 v[108:111], v[156:159], v[196:199], v[108:111]
	v_mfma_f32_16x16x32_bf16 v[104:107], v[164:167], v[196:199], v[104:107]
	v_mfma_f32_16x16x32_bf16 v[92:95], v[156:159], v[204:207], v[92:95]
	v_mfma_f32_16x16x32_bf16 v[88:91], v[164:167], v[204:207], v[88:91]
	v_mfma_f32_16x16x32_bf16 v[76:79], v[156:159], v[212:215], v[76:79]
	v_mfma_f32_16x16x32_bf16 v[72:75], v[164:167], v[212:215], v[72:75]
	v_mfma_f32_16x16x32_bf16 v[124:127], v[160:163], v[192:195], v[124:127]
	v_mfma_f32_16x16x32_bf16 v[120:123], v[168:171], v[192:195], v[120:123]
	v_mfma_f32_16x16x32_bf16 v[108:111], v[160:163], v[200:203], v[108:111]
	v_mfma_f32_16x16x32_bf16 v[104:107], v[168:171], v[200:203], v[104:107]
	v_mfma_f32_16x16x32_bf16 v[92:95], v[160:163], v[208:211], v[92:95]
	v_mfma_f32_16x16x32_bf16 v[88:91], v[168:171], v[208:211], v[88:91]
	v_mfma_f32_16x16x32_bf16 v[76:79], v[160:163], v[216:219], v[76:79]
	v_mfma_f32_16x16x32_bf16 v[72:75], v[168:171], v[216:219], v[72:75]
	v_mfma_f32_16x16x32_bf16 v[116:119], v[172:175], v[188:191], v[116:119]
	v_mfma_f32_16x16x32_bf16 v[112:115], v[180:183], v[188:191], v[112:115]
	v_mfma_f32_16x16x32_bf16 v[100:103], v[172:175], v[196:199], v[100:103]
	v_mfma_f32_16x16x32_bf16 v[96:99], v[180:183], v[196:199], v[96:99]
	v_mfma_f32_16x16x32_bf16 v[84:87], v[172:175], v[204:207], v[84:87]
	v_mfma_f32_16x16x32_bf16 v[80:83], v[180:183], v[204:207], v[80:83]
	v_mfma_f32_16x16x32_bf16 v[68:71], v[172:175], v[212:215], v[68:71]
	v_mfma_f32_16x16x32_bf16 v[64:67], v[180:183], v[212:215], v[64:67]
	v_mfma_f32_16x16x32_bf16 v[116:119], v[176:179], v[192:195], v[116:119]
	v_mfma_f32_16x16x32_bf16 v[112:115], v[184:187], v[192:195], v[112:115]
	v_mfma_f32_16x16x32_bf16 v[100:103], v[176:179], v[200:203], v[100:103]
	v_mfma_f32_16x16x32_bf16 v[96:99], v[184:187], v[200:203], v[96:99]
	v_mfma_f32_16x16x32_bf16 v[84:87], v[176:179], v[208:211], v[84:87]
	v_mfma_f32_16x16x32_bf16 v[80:83], v[184:187], v[208:211], v[80:83]
	v_mfma_f32_16x16x32_bf16 v[68:71], v[176:179], v[216:219], v[68:71]
	v_mfma_f32_16x16x32_bf16 v[64:67], v[184:187], v[216:219], v[64:67]
	s_barrier
	s_add_i32 s69, s60, s39
	v_lshl_add_u64 v[220:221], s[26:27], 0, v[132:133]
	s_mov_b32 m0, s69
	ds_read_b128 v[188:191], v154 offset:16384
	ds_read_b128 v[192:195], v154 offset:17408
	ds_read_b128 v[196:199], v154 offset:18432
	ds_read_b128 v[200:203], v154 offset:19456
	ds_read_b128 v[204:207], v154 offset:20480
	ds_read_b128 v[208:211], v154 offset:21504
	ds_read_b128 v[212:215], v154 offset:22528
	ds_read_b128 v[216:219], v154 offset:23552
	global_load_lds_dwordx4 v[220:221], off
	s_add_i32 m0, s69, 0x2000
	s_add_u32 s70, s26, 0x80000
	v_lshl_add_u64 v[222:223], s[26:27], 0, v[140:141]
	s_addc_u32 s71, s27, 0
	s_add_i32 s69, s61, s39
	global_load_lds_dwordx4 v[222:223], off
	v_lshl_add_u64 v[224:225], s[70:71], 0, v[132:133]
	s_mov_b32 m0, s69
	v_lshl_add_u64 v[226:227], s[36:37], 0, v[134:135]
	global_load_lds_dwordx4 v[224:225], off
	v_lshl_add_u64 v[224:225], s[70:71], 0, v[140:141]
	s_add_i32 m0, s69, 0x2000
	s_nop 0
	global_load_lds_dwordx4 v[224:225], off
	v_lshl_add_u64 v[224:225], s[36:37], 0, v[130:131]
	s_mov_b32 m0, s40
	s_nop 0
	global_load_lds_dwordx4 v[224:225], off
	s_mov_b32 m0, s41
	s_nop 0
	global_load_lds_dwordx4 v[226:227], off
	s_waitcnt vmcnt(8)
	s_waitcnt lgkmcnt(0)
	s_barrier
	s_waitcnt lgkmcnt(0)
	v_mfma_f32_16x16x32_bf16 v[60:63], v[156:159], v[188:191], v[60:63]
	v_mfma_f32_16x16x32_bf16 v[56:59], v[164:167], v[188:191], v[56:59]
	v_mfma_f32_16x16x32_bf16 v[44:47], v[156:159], v[196:199], v[44:47]
	v_mfma_f32_16x16x32_bf16 v[40:43], v[164:167], v[196:199], v[40:43]
	v_mfma_f32_16x16x32_bf16 v[28:31], v[156:159], v[204:207], v[28:31]
	v_mfma_f32_16x16x32_bf16 v[24:27], v[164:167], v[204:207], v[24:27]
	v_mfma_f32_16x16x32_bf16 v[12:15], v[156:159], v[212:215], v[12:15]
	v_mfma_f32_16x16x32_bf16 v[8:11], v[164:167], v[212:215], v[8:11]
	v_mfma_f32_16x16x32_bf16 v[60:63], v[160:163], v[192:195], v[60:63]
	v_mfma_f32_16x16x32_bf16 v[56:59], v[168:171], v[192:195], v[56:59]
	v_mfma_f32_16x16x32_bf16 v[44:47], v[160:163], v[200:203], v[44:47]
	v_mfma_f32_16x16x32_bf16 v[40:43], v[168:171], v[200:203], v[40:43]
	v_mfma_f32_16x16x32_bf16 v[28:31], v[160:163], v[208:211], v[28:31]
	v_mfma_f32_16x16x32_bf16 v[24:27], v[168:171], v[208:211], v[24:27]
	v_mfma_f32_16x16x32_bf16 v[12:15], v[160:163], v[216:219], v[12:15]
	v_mfma_f32_16x16x32_bf16 v[8:11], v[168:171], v[216:219], v[8:11]
	v_mfma_f32_16x16x32_bf16 v[52:55], v[172:175], v[188:191], v[52:55]
	v_mfma_f32_16x16x32_bf16 v[48:51], v[180:183], v[188:191], v[48:51]
	v_mfma_f32_16x16x32_bf16 v[36:39], v[172:175], v[196:199], v[36:39]
	v_mfma_f32_16x16x32_bf16 v[32:35], v[180:183], v[196:199], v[32:35]
	v_mfma_f32_16x16x32_bf16 v[20:23], v[172:175], v[204:207], v[20:23]
	v_mfma_f32_16x16x32_bf16 v[16:19], v[180:183], v[204:207], v[16:19]
	v_mfma_f32_16x16x32_bf16 v[4:7], v[172:175], v[212:215], v[4:7]
	v_mfma_f32_16x16x32_bf16 v[0:3], v[180:183], v[212:215], v[0:3]
	v_mfma_f32_16x16x32_bf16 v[52:55], v[176:179], v[192:195], v[52:55]
	v_mfma_f32_16x16x32_bf16 v[48:51], v[184:187], v[192:195], v[48:51]
	v_mfma_f32_16x16x32_bf16 v[36:39], v[176:179], v[200:203], v[36:39]
	v_mfma_f32_16x16x32_bf16 v[32:35], v[184:187], v[200:203], v[32:35]
	v_mfma_f32_16x16x32_bf16 v[20:23], v[176:179], v[208:211], v[20:23]
	v_mfma_f32_16x16x32_bf16 v[16:19], v[184:187], v[208:211], v[16:19]
	v_mfma_f32_16x16x32_bf16 v[4:7], v[176:179], v[216:219], v[4:7]
	v_mfma_f32_16x16x32_bf16 v[0:3], v[184:187], v[216:219], v[0:3]
	s_barrier
	s_add_i32 s69, 0, 0x18000
	v_add_u32_e32 v142, s69, v137
	s_add_i32 s70, 0, 0x1c000
	ds_read_b128 v[156:159], v142
	ds_read_b128 v[160:163], v142 offset:1024
	ds_read_b128 v[164:167], v142 offset:2048
	ds_read_b128 v[168:171], v142 offset:3072
	v_add_u32_e32 v142, s70, v137
	ds_read_b128 v[172:175], v142
	ds_read_b128 v[176:179], v142 offset:1024
	ds_read_b128 v[180:183], v142 offset:2048
	ds_read_b128 v[184:187], v142 offset:3072
	s_add_u32 s36, s36, 0x80000
	s_addc_u32 s37, s37, 0
	s_mov_b32 m0, s42
	v_lshl_add_u64 v[228:229], s[36:37], 0, v[130:131]
	ds_read_b128 v[188:191], v154 offset:32768
	ds_read_b128 v[192:195], v154 offset:33792
	ds_read_b128 v[196:199], v154 offset:34816
	ds_read_b128 v[200:203], v154 offset:35840
	ds_read_b128 v[204:207], v154 offset:36864
	ds_read_b128 v[208:211], v154 offset:37888
	ds_read_b128 v[212:215], v154 offset:38912
	ds_read_b128 v[216:219], v154 offset:39936
	global_load_lds_dwordx4 v[228:229], off
	v_lshl_add_u64 v[228:229], s[36:37], 0, v[134:135]
	s_mov_b32 m0, s43
	s_nop 0
	global_load_lds_dwordx4 v[228:229], off
	s_waitcnt vmcnt(8)
	s_waitcnt lgkmcnt(0)
	s_barrier
	s_waitcnt lgkmcnt(0)
	v_mfma_f32_16x16x32_bf16 v[124:127], v[156:159], v[188:191], v[124:127]
	v_mfma_f32_16x16x32_bf16 v[120:123], v[164:167], v[188:191], v[120:123]
	v_mfma_f32_16x16x32_bf16 v[108:111], v[156:159], v[196:199], v[108:111]
	v_mfma_f32_16x16x32_bf16 v[104:107], v[164:167], v[196:199], v[104:107]
	v_mfma_f32_16x16x32_bf16 v[92:95], v[156:159], v[204:207], v[92:95]
	v_mfma_f32_16x16x32_bf16 v[88:91], v[164:167], v[204:207], v[88:91]
	v_mfma_f32_16x16x32_bf16 v[76:79], v[156:159], v[212:215], v[76:79]
	v_mfma_f32_16x16x32_bf16 v[72:75], v[164:167], v[212:215], v[72:75]
	v_mfma_f32_16x16x32_bf16 v[124:127], v[160:163], v[192:195], v[124:127]
	v_mfma_f32_16x16x32_bf16 v[120:123], v[168:171], v[192:195], v[120:123]
	v_mfma_f32_16x16x32_bf16 v[108:111], v[160:163], v[200:203], v[108:111]
	v_mfma_f32_16x16x32_bf16 v[104:107], v[168:171], v[200:203], v[104:107]
	v_mfma_f32_16x16x32_bf16 v[92:95], v[160:163], v[208:211], v[92:95]
	v_mfma_f32_16x16x32_bf16 v[88:91], v[168:171], v[208:211], v[88:91]
	v_mfma_f32_16x16x32_bf16 v[76:79], v[160:163], v[216:219], v[76:79]
	v_mfma_f32_16x16x32_bf16 v[72:75], v[168:171], v[216:219], v[72:75]
	v_mfma_f32_16x16x32_bf16 v[116:119], v[172:175], v[188:191], v[116:119]
	v_mfma_f32_16x16x32_bf16 v[112:115], v[180:183], v[188:191], v[112:115]
	v_mfma_f32_16x16x32_bf16 v[100:103], v[172:175], v[196:199], v[100:103]
	v_mfma_f32_16x16x32_bf16 v[96:99], v[180:183], v[196:199], v[96:99]
	v_mfma_f32_16x16x32_bf16 v[84:87], v[172:175], v[204:207], v[84:87]
	v_mfma_f32_16x16x32_bf16 v[80:83], v[180:183], v[204:207], v[80:83]
	v_mfma_f32_16x16x32_bf16 v[68:71], v[172:175], v[212:215], v[68:71]
	v_mfma_f32_16x16x32_bf16 v[64:67], v[180:183], v[212:215], v[64:67]
	v_mfma_f32_16x16x32_bf16 v[116:119], v[176:179], v[192:195], v[116:119]
	v_mfma_f32_16x16x32_bf16 v[112:115], v[184:187], v[192:195], v[112:115]
	v_mfma_f32_16x16x32_bf16 v[100:103], v[176:179], v[200:203], v[100:103]
	v_mfma_f32_16x16x32_bf16 v[96:99], v[184:187], v[200:203], v[96:99]
	v_mfma_f32_16x16x32_bf16 v[84:87], v[176:179], v[208:211], v[84:87]
	v_mfma_f32_16x16x32_bf16 v[80:83], v[184:187], v[208:211], v[80:83]
	v_mfma_f32_16x16x32_bf16 v[68:71], v[176:179], v[216:219], v[68:71]
	v_mfma_f32_16x16x32_bf16 v[64:67], v[184:187], v[216:219], v[64:67]
	s_barrier
	s_add_i32 s36, s69, s39
	v_lshl_add_u64 v[220:221], v[220:221], 0, s[14:15]
	s_mov_b32 m0, s36
	ds_read_b128 v[188:191], v154 offset:49152
	ds_read_b128 v[192:195], v154 offset:50176
	ds_read_b128 v[196:199], v154 offset:51200
	ds_read_b128 v[200:203], v154 offset:52224
	ds_read_b128 v[204:207], v154 offset:53248
	ds_read_b128 v[208:211], v154 offset:54272
	ds_read_b128 v[212:215], v154 offset:55296
	ds_read_b128 v[216:219], v154 offset:56320
	global_load_lds_dwordx4 v[220:221], off
	s_add_i32 m0, s36, 0x2000
	s_add_u32 s26, s26, 0x80080
	v_lshl_add_u64 v[220:221], v[222:223], 0, s[14:15]
	s_addc_u32 s27, s27, 0
	s_add_i32 s36, s70, s39
	global_load_lds_dwordx4 v[220:221], off
	v_lshl_add_u64 v[220:221], s[26:27], 0, v[132:133]
	s_mov_b32 m0, s36
	s_nop 0
	global_load_lds_dwordx4 v[220:221], off
	v_lshl_add_u64 v[220:221], s[26:27], 0, v[140:141]
	s_add_i32 m0, s36, 0x2000
	s_nop 0
	global_load_lds_dwordx4 v[220:221], off
	v_lshl_add_u64 v[220:221], v[224:225], 0, s[14:15]
	s_mov_b32 m0, s47
	s_nop 0
	global_load_lds_dwordx4 v[220:221], off
	v_lshl_add_u64 v[220:221], v[226:227], 0, s[14:15]
	s_mov_b32 m0, s58
	s_nop 0
	global_load_lds_dwordx4 v[220:221], off
	s_waitcnt vmcnt(8)
	s_waitcnt lgkmcnt(0)
	s_barrier
	s_waitcnt lgkmcnt(0)
	v_mfma_f32_16x16x32_bf16 v[60:63], v[156:159], v[188:191], v[60:63]
	v_mfma_f32_16x16x32_bf16 v[56:59], v[164:167], v[188:191], v[56:59]
	v_mfma_f32_16x16x32_bf16 v[44:47], v[156:159], v[196:199], v[44:47]
	v_mfma_f32_16x16x32_bf16 v[40:43], v[164:167], v[196:199], v[40:43]
	v_mfma_f32_16x16x32_bf16 v[28:31], v[156:159], v[204:207], v[28:31]
	v_mfma_f32_16x16x32_bf16 v[24:27], v[164:167], v[204:207], v[24:27]
	v_mfma_f32_16x16x32_bf16 v[12:15], v[156:159], v[212:215], v[12:15]
	v_mfma_f32_16x16x32_bf16 v[8:11], v[164:167], v[212:215], v[8:11]
	v_mfma_f32_16x16x32_bf16 v[60:63], v[160:163], v[192:195], v[60:63]
	v_mfma_f32_16x16x32_bf16 v[56:59], v[168:171], v[192:195], v[56:59]
	v_mfma_f32_16x16x32_bf16 v[44:47], v[160:163], v[200:203], v[44:47]
	v_mfma_f32_16x16x32_bf16 v[40:43], v[168:171], v[200:203], v[40:43]
	v_mfma_f32_16x16x32_bf16 v[28:31], v[160:163], v[208:211], v[28:31]
	v_mfma_f32_16x16x32_bf16 v[24:27], v[168:171], v[208:211], v[24:27]
	v_mfma_f32_16x16x32_bf16 v[12:15], v[160:163], v[216:219], v[12:15]
	v_mfma_f32_16x16x32_bf16 v[8:11], v[168:171], v[216:219], v[8:11]
	v_mfma_f32_16x16x32_bf16 v[52:55], v[172:175], v[188:191], v[52:55]
	v_mfma_f32_16x16x32_bf16 v[48:51], v[180:183], v[188:191], v[48:51]
	v_mfma_f32_16x16x32_bf16 v[36:39], v[172:175], v[196:199], v[36:39]
	v_mfma_f32_16x16x32_bf16 v[32:35], v[180:183], v[196:199], v[32:35]
	v_mfma_f32_16x16x32_bf16 v[20:23], v[172:175], v[204:207], v[20:23]
	v_mfma_f32_16x16x32_bf16 v[16:19], v[180:183], v[204:207], v[16:19]
	v_mfma_f32_16x16x32_bf16 v[4:7], v[172:175], v[212:215], v[4:7]
	v_mfma_f32_16x16x32_bf16 v[0:3], v[180:183], v[212:215], v[0:3]
	v_mfma_f32_16x16x32_bf16 v[52:55], v[176:179], v[192:195], v[52:55]
	v_mfma_f32_16x16x32_bf16 v[48:51], v[184:187], v[192:195], v[48:51]
	v_mfma_f32_16x16x32_bf16 v[36:39], v[176:179], v[200:203], v[36:39]
	v_mfma_f32_16x16x32_bf16 v[32:35], v[184:187], v[200:203], v[32:35]
	v_mfma_f32_16x16x32_bf16 v[20:23], v[176:179], v[208:211], v[20:23]
	v_mfma_f32_16x16x32_bf16 v[16:19], v[184:187], v[208:211], v[16:19]
	v_mfma_f32_16x16x32_bf16 v[4:7], v[176:179], v[216:219], v[4:7]
	v_mfma_f32_16x16x32_bf16 v[0:3], v[184:187], v[216:219], v[0:3]
	s_barrier
	s_add_i32 s68, s68, 2
	s_add_u32 s24, s24, 0x100
	s_addc_u32 s25, s25, 0
	s_add_u32 s66, s66, 0x100
	s_addc_u32 s67, s67, 0
	s_cmp_gt_u32 s68, 29
	s_cbranch_scc0 .LBB0_2285
	s_and_b64 vcc, exec, s[16:17]
	s_cbranch_vccz .LBB0_2288
	s_barrier
.LBB0_2288:
	s_setprio 0
	v_add_u32_e32 v155, s65, v129
	s_lshl_b32 s24, s10, 7
	s_ashr_i32 s25, s24, 31
	v_cmp_gt_i32_e32 vcc, s62, v155
	v_lshlrev_b32_e32 v142, 1, v128
	s_and_saveexec_b64 s[26:27], vcc
	s_cbranch_execz .LBB0_2290
	v_mul_f32_e32 v156, 0xbfb8aa3b, v124
	v_exp_f32_e32 v156, v156
	v_mul_f32_e32 v157, 0xbfb8aa3b, v125
	v_exp_f32_e32 v157, v157
	v_mul_f32_e32 v158, 0xbfb8aa3b, v126
	v_add_f32_e32 v156, 1.0, v156
	v_rcp_f32_e32 v156, v156
	v_add_f32_e32 v157, 1.0, v157
	v_rcp_f32_e32 v157, v157
	s_lshl_b32 s10, s46, 1
	v_mul_f32_e32 v124, v124, v156
	v_mul_f32_e32 v116, v124, v116
	v_exp_f32_e32 v124, v158
	v_mul_f32_e32 v156, 0xbfb8aa3b, v127
	v_exp_f32_e32 v156, v156
	v_mul_f32_e32 v125, v125, v157
	v_add_f32_e32 v124, 1.0, v124
	v_mul_f32_e32 v117, v125, v117
	v_rcp_f32_e32 v124, v124
	v_add_f32_e32 v125, 1.0, v156
	v_mul_f32_e32 v156, 0xbfb8aa3b, v120
	v_rcp_f32_e32 v125, v125
	v_exp_f32_e32 v156, v156
	v_mul_f32_e32 v124, v126, v124
	v_mul_f32_e32 v118, v124, v118
	v_mul_f32_e32 v124, v127, v125
	v_add_f32_e32 v125, 1.0, v156
	v_rcp_f32_e32 v125, v125
	v_mul_f32_e32 v126, 0xbfb8aa3b, v121
	v_exp_f32_e32 v126, v126
	v_mul_f32_e32 v119, v124, v119
	v_mul_f32_e32 v120, v120, v125
	v_mul_f32_e32 v120, v120, v112
	v_add_f32_e32 v112, 1.0, v126
	v_mul_f32_e32 v124, 0xbfb8aa3b, v122
	v_rcp_f32_e32 v112, v112
	v_exp_f32_e32 v124, v124
	v_mul_f32_e32 v125, 0xbfb8aa3b, v123
	v_exp_f32_e32 v125, v125
	v_mul_f32_e32 v112, v121, v112
	v_add_f32_e32 v121, 1.0, v124
	v_rcp_f32_e32 v121, v121
	v_add_f32_e32 v124, 1.0, v125
	v_rcp_f32_e32 v124, v124
	v_mul_f32_e32 v125, v112, v113
	v_mul_f32_e32 v112, v122, v121
	v_mul_f32_e32 v121, v112, v114
	v_mul_f32_e32 v112, v123, v124
	v_mul_f32_e32 v115, v112, v115
	v_cvt_pk_bf16_f32 v112, v116, v117
	v_mov_b64_e32 v[116:117], s[52:53]
	v_mad_i64_i32 v[116:117], s[36:37], v155, s63, v[116:117]
	v_lshl_add_u64 v[116:117], s[24:25], 1, v[116:117]
	v_lshl_add_u64 v[116:117], v[116:117], 0, s[10:11]
	v_lshl_add_u64 v[116:117], v[116:117], 0, v[142:143]
	v_cvt_pk_bf16_f32 v113, v118, v119
	v_cvt_pk_bf16_f32 v114, v120, v125
	v_cvt_pk_bf16_f32 v115, v121, v115
	global_store_dwordx4 v[116:117], v[112:115], off

.LBB0_2375:
	s_add_u32 s22, s22, 0x160080
	s_addc_u32 s23, s23, 0
	s_add_u32 s62, s24, 0x100
	v_mov_b32_e32 v0, 0
	s_addc_u32 s63, s25, 0
	s_mov_b32 s64, -2
	v_mov_b32_e32 v1, v0
	v_mov_b32_e32 v2, v0
	v_mov_b32_e32 v3, v0
	v_mov_b32_e32 v4, v0
	v_mov_b32_e32 v5, v0
	v_mov_b32_e32 v6, v0
	v_mov_b32_e32 v7, v0
	v_mov_b32_e32 v16, v0
	v_mov_b32_e32 v17, v0
	v_mov_b32_e32 v18, v0
	v_mov_b32_e32 v19, v0
	v_mov_b32_e32 v20, v0
	v_mov_b32_e32 v21, v0
	v_mov_b32_e32 v22, v0
	v_mov_b32_e32 v23, v0
	v_mov_b32_e32 v32, v0
	v_mov_b32_e32 v33, v0
	v_mov_b32_e32 v34, v0
	v_mov_b32_e32 v35, v0
	v_mov_b32_e32 v36, v0
	v_mov_b32_e32 v37, v0
	v_mov_b32_e32 v38, v0
	v_mov_b32_e32 v39, v0
	v_mov_b32_e32 v48, v0
	v_mov_b32_e32 v49, v0
	v_mov_b32_e32 v50, v0
	v_mov_b32_e32 v51, v0
	v_mov_b32_e32 v52, v0
	v_mov_b32_e32 v53, v0
	v_mov_b32_e32 v54, v0
	v_mov_b32_e32 v55, v0
	v_mov_b32_e32 v8, v0
	v_mov_b32_e32 v9, v0
	v_mov_b32_e32 v10, v0
	v_mov_b32_e32 v11, v0
	v_mov_b32_e32 v12, v0
	v_mov_b32_e32 v13, v0
	v_mov_b32_e32 v14, v0
	v_mov_b32_e32 v15, v0
	v_mov_b32_e32 v24, v0
	v_mov_b32_e32 v25, v0
	v_mov_b32_e32 v26, v0
	v_mov_b32_e32 v27, v0
	v_mov_b32_e32 v28, v0
	v_mov_b32_e32 v29, v0
	v_mov_b32_e32 v30, v0
	v_mov_b32_e32 v31, v0
	v_mov_b32_e32 v40, v0
	v_mov_b32_e32 v41, v0
	v_mov_b32_e32 v42, v0
	v_mov_b32_e32 v43, v0
	v_mov_b32_e32 v44, v0
	v_mov_b32_e32 v45, v0
	v_mov_b32_e32 v46, v0
	v_mov_b32_e32 v47, v0
	v_mov_b32_e32 v56, v0
	v_mov_b32_e32 v57, v0
	v_mov_b32_e32 v58, v0
	v_mov_b32_e32 v59, v0
	v_mov_b32_e32 v60, v0
	v_mov_b32_e32 v61, v0
	v_mov_b32_e32 v62, v0
	v_mov_b32_e32 v63, v0
	v_mov_b32_e32 v64, v0
	v_mov_b32_e32 v65, v0
	v_mov_b32_e32 v66, v0
	v_mov_b32_e32 v67, v0
	v_mov_b32_e32 v68, v0
	v_mov_b32_e32 v69, v0
	v_mov_b32_e32 v70, v0
	v_mov_b32_e32 v71, v0
	v_mov_b32_e32 v80, v0
	v_mov_b32_e32 v81, v0
	v_mov_b32_e32 v82, v0
	v_mov_b32_e32 v83, v0
	v_mov_b32_e32 v84, v0
	v_mov_b32_e32 v85, v0
	v_mov_b32_e32 v86, v0
	v_mov_b32_e32 v87, v0
	v_mov_b32_e32 v96, v0
	v_mov_b32_e32 v97, v0
	v_mov_b32_e32 v98, v0
	v_mov_b32_e32 v99, v0
	v_mov_b32_e32 v100, v0
	v_mov_b32_e32 v101, v0
	v_mov_b32_e32 v102, v0
	v_mov_b32_e32 v103, v0
	v_mov_b32_e32 v112, v0
	v_mov_b32_e32 v113, v0
	v_mov_b32_e32 v114, v0
	v_mov_b32_e32 v115, v0
	v_mov_b32_e32 v116, v0
	v_mov_b32_e32 v117, v0
	v_mov_b32_e32 v118, v0
	v_mov_b32_e32 v119, v0
	v_mov_b32_e32 v72, v0
	v_mov_b32_e32 v73, v0
	v_mov_b32_e32 v74, v0
	v_mov_b32_e32 v75, v0
	v_mov_b32_e32 v76, v0
	v_mov_b32_e32 v77, v0
	v_mov_b32_e32 v78, v0
	v_mov_b32_e32 v79, v0
	v_mov_b32_e32 v88, v0
	v_mov_b32_e32 v89, v0
	v_mov_b32_e32 v90, v0
	v_mov_b32_e32 v91, v0
	v_mov_b32_e32 v92, v0
	v_mov_b32_e32 v93, v0
	v_mov_b32_e32 v94, v0
	v_mov_b32_e32 v95, v0
	v_mov_b32_e32 v104, v0
	v_mov_b32_e32 v105, v0
	v_mov_b32_e32 v106, v0
	v_mov_b32_e32 v107, v0
	v_mov_b32_e32 v108, v0
	v_mov_b32_e32 v109, v0
	v_mov_b32_e32 v110, v0
	v_mov_b32_e32 v111, v0
	v_mov_b32_e32 v120, v0
	v_mov_b32_e32 v121, v0
	v_mov_b32_e32 v122, v0
	v_mov_b32_e32 v123, v0
	v_mov_b32_e32 v124, v0
	v_mov_b32_e32 v125, v0
	v_mov_b32_e32 v126, v0
	v_mov_b32_e32 v127, v0
	s_cmp_eq_u64 s[14:15], 0
	s_cbranch_scc0 .Lprio_skip_10
	s_setprio 1
.Lprio_skip_10:
.LBB0_2376:
	ds_read_b128 v[146:149], v155
	ds_read_b128 v[158:161], v155 offset:1024
	ds_read_b128 v[162:165], v155 offset:2048
	ds_read_b128 v[166:169], v155 offset:3072
	ds_read_b128 v[170:173], v156
	ds_read_b128 v[174:177], v156 offset:1024
	ds_read_b128 v[178:181], v156 offset:2048
	ds_read_b128 v[182:185], v156 offset:3072
	s_add_u32 s24, s22, 0xffea0080
	s_addc_u32 s25, s23, -1
	s_cmpk_eq_i32 s64, 0x54
	s_cselect_b32 s27, s19, s25
	s_cselect_b32 s26, s18, s24
	s_cselect_b32 s25, s21, s63
	s_cselect_b32 s24, s20, s62
	v_lshl_add_u64 v[218:219], s[22:23], 0, v[138:139]
	s_add_i32 m0, s36, 0xc000
	ds_read_b128 v[186:189], v157
	ds_read_b128 v[190:193], v157 offset:1024
	ds_read_b128 v[194:197], v157 offset:2048
	ds_read_b128 v[198:201], v157 offset:3072
	ds_read_b128 v[202:205], v157 offset:4096
	ds_read_b128 v[206:209], v157 offset:5120
	ds_read_b128 v[210:213], v157 offset:6144
	ds_read_b128 v[214:217], v157 offset:7168
	global_load_lds_dwordx4 v[218:219], off
	v_lshl_add_u64 v[218:219], s[22:23], 0, v[140:141]
	s_add_i32 m0, s36, 0xe000
	s_nop 0
	global_load_lds_dwordx4 v[218:219], off
	s_waitcnt vmcnt(8)
	s_waitcnt lgkmcnt(0)
	s_barrier
	s_waitcnt lgkmcnt(0)
	v_mfma_f32_16x16x32_bf16 v[124:127], v[146:149], v[186:189], v[124:127]
	v_mfma_f32_16x16x32_bf16 v[120:123], v[162:165], v[186:189], v[120:123]
	v_mfma_f32_16x16x32_bf16 v[108:111], v[146:149], v[194:197], v[108:111]
	v_mfma_f32_16x16x32_bf16 v[104:107], v[162:165], v[194:197], v[104:107]
	v_mfma_f32_16x16x32_bf16 v[92:95], v[146:149], v[202:205], v[92:95]
	v_mfma_f32_16x16x32_bf16 v[88:91], v[162:165], v[202:205], v[88:91]
	v_mfma_f32_16x16x32_bf16 v[76:79], v[146:149], v[210:213], v[76:79]
	v_mfma_f32_16x16x32_bf16 v[72:75], v[162:165], v[210:213], v[72:75]
	v_mfma_f32_16x16x32_bf16 v[124:127], v[158:161], v[190:193], v[124:127]
	v_mfma_f32_16x16x32_bf16 v[120:123], v[166:169], v[190:193], v[120:123]
	v_mfma_f32_16x16x32_bf16 v[108:111], v[158:161], v[198:201], v[108:111]
	v_mfma_f32_16x16x32_bf16 v[104:107], v[166:169], v[198:201], v[104:107]
	v_mfma_f32_16x16x32_bf16 v[92:95], v[158:161], v[206:209], v[92:95]
	v_mfma_f32_16x16x32_bf16 v[88:91], v[166:169], v[206:209], v[88:91]
	v_mfma_f32_16x16x32_bf16 v[76:79], v[158:161], v[214:217], v[76:79]
	v_mfma_f32_16x16x32_bf16 v[72:75], v[166:169], v[214:217], v[72:75]
	v_mfma_f32_16x16x32_bf16 v[116:119], v[170:173], v[186:189], v[116:119]
	v_mfma_f32_16x16x32_bf16 v[112:115], v[178:181], v[186:189], v[112:115]
	v_mfma_f32_16x16x32_bf16 v[100:103], v[170:173], v[194:197], v[100:103]
	v_mfma_f32_16x16x32_bf16 v[96:99], v[178:181], v[194:197], v[96:99]
	v_mfma_f32_16x16x32_bf16 v[84:87], v[170:173], v[202:205], v[84:87]
	v_mfma_f32_16x16x32_bf16 v[80:83], v[178:181], v[202:205], v[80:83]
	v_mfma_f32_16x16x32_bf16 v[68:71], v[170:173], v[210:213], v[68:71]
	v_mfma_f32_16x16x32_bf16 v[64:67], v[178:181], v[210:213], v[64:67]
	v_mfma_f32_16x16x32_bf16 v[116:119], v[174:177], v[190:193], v[116:119]
	v_mfma_f32_16x16x32_bf16 v[112:115], v[182:185], v[190:193], v[112:115]
	v_mfma_f32_16x16x32_bf16 v[100:103], v[174:177], v[198:201], v[100:103]
	v_mfma_f32_16x16x32_bf16 v[96:99], v[182:185], v[198:201], v[96:99]
	v_mfma_f32_16x16x32_bf16 v[84:87], v[174:177], v[206:209], v[84:87]
	v_mfma_f32_16x16x32_bf16 v[80:83], v[182:185], v[206:209], v[80:83]
	v_mfma_f32_16x16x32_bf16 v[68:71], v[174:177], v[214:217], v[68:71]
	v_mfma_f32_16x16x32_bf16 v[64:67], v[182:185], v[214:217], v[64:67]
	s_barrier
	s_add_i32 s65, s43, s17
	v_lshl_add_u64 v[218:219], s[24:25], 0, v[130:131]
	s_mov_b32 m0, s65
	ds_read_b128 v[186:189], v157 offset:16384
	ds_read_b128 v[190:193], v157 offset:17408
	ds_read_b128 v[194:197], v157 offset:18432
	ds_read_b128 v[198:201], v157 offset:19456
	ds_read_b128 v[202:205], v157 offset:20480
	ds_read_b128 v[206:209], v157 offset:21504
	ds_read_b128 v[210:213], v157 offset:22528
	ds_read_b128 v[214:217], v157 offset:23552
	global_load_lds_dwordx4 v[218:219], off
	s_add_i32 m0, s65, 0x2000
	s_add_u32 s66, s24, 0x160000
	v_lshl_add_u64 v[220:221], s[24:25], 0, v[134:135]
	s_addc_u32 s67, s25, 0
	s_add_i32 s65, s44, s17
	global_load_lds_dwordx4 v[220:221], off
	v_lshl_add_u64 v[222:223], s[66:67], 0, v[130:131]
	s_mov_b32 m0, s65
	v_lshl_add_u64 v[224:225], s[26:27], 0, v[132:133]
	global_load_lds_dwordx4 v[222:223], off
	v_lshl_add_u64 v[222:223], s[66:67], 0, v[134:135]
	s_add_i32 m0, s65, 0x2000
	s_nop 0
	global_load_lds_dwordx4 v[222:223], off
	v_lshl_add_u64 v[222:223], s[26:27], 0, v[128:129]
	s_mov_b32 m0, s36
	s_nop 0
	global_load_lds_dwordx4 v[222:223], off
	s_mov_b32 m0, s37
	s_nop 0
	global_load_lds_dwordx4 v[224:225], off
	s_waitcnt vmcnt(8)
	s_waitcnt lgkmcnt(0)
	s_barrier
	s_waitcnt lgkmcnt(0)
	v_mfma_f32_16x16x32_bf16 v[60:63], v[146:149], v[186:189], v[60:63]
	v_mfma_f32_16x16x32_bf16 v[56:59], v[162:165], v[186:189], v[56:59]
	v_mfma_f32_16x16x32_bf16 v[44:47], v[146:149], v[194:197], v[44:47]
	v_mfma_f32_16x16x32_bf16 v[40:43], v[162:165], v[194:197], v[40:43]
	v_mfma_f32_16x16x32_bf16 v[28:31], v[146:149], v[202:205], v[28:31]
	v_mfma_f32_16x16x32_bf16 v[24:27], v[162:165], v[202:205], v[24:27]
	v_mfma_f32_16x16x32_bf16 v[12:15], v[146:149], v[210:213], v[12:15]
	v_mfma_f32_16x16x32_bf16 v[8:11], v[162:165], v[210:213], v[8:11]
	v_mfma_f32_16x16x32_bf16 v[60:63], v[158:161], v[190:193], v[60:63]
	v_mfma_f32_16x16x32_bf16 v[56:59], v[166:169], v[190:193], v[56:59]
	v_mfma_f32_16x16x32_bf16 v[44:47], v[158:161], v[198:201], v[44:47]
	v_mfma_f32_16x16x32_bf16 v[40:43], v[166:169], v[198:201], v[40:43]
	v_mfma_f32_16x16x32_bf16 v[28:31], v[158:161], v[206:209], v[28:31]
	v_mfma_f32_16x16x32_bf16 v[24:27], v[166:169], v[206:209], v[24:27]
	v_mfma_f32_16x16x32_bf16 v[12:15], v[158:161], v[214:217], v[12:15]
	v_mfma_f32_16x16x32_bf16 v[8:11], v[166:169], v[214:217], v[8:11]
	v_mfma_f32_16x16x32_bf16 v[52:55], v[170:173], v[186:189], v[52:55]
	v_mfma_f32_16x16x32_bf16 v[48:51], v[178:181], v[186:189], v[48:51]
	v_mfma_f32_16x16x32_bf16 v[36:39], v[170:173], v[194:197], v[36:39]
	v_mfma_f32_16x16x32_bf16 v[32:35], v[178:181], v[194:197], v[32:35]
	v_mfma_f32_16x16x32_bf16 v[20:23], v[170:173], v[202:205], v[20:23]
	v_mfma_f32_16x16x32_bf16 v[16:19], v[178:181], v[202:205], v[16:19]
	v_mfma_f32_16x16x32_bf16 v[4:7], v[170:173], v[210:213], v[4:7]
	v_mfma_f32_16x16x32_bf16 v[0:3], v[178:181], v[210:213], v[0:3]
	v_mfma_f32_16x16x32_bf16 v[52:55], v[174:177], v[190:193], v[52:55]
	v_mfma_f32_16x16x32_bf16 v[48:51], v[182:185], v[190:193], v[48:51]
	v_mfma_f32_16x16x32_bf16 v[36:39], v[174:177], v[198:201], v[36:39]
	v_mfma_f32_16x16x32_bf16 v[32:35], v[182:185], v[198:201], v[32:35]
	v_mfma_f32_16x16x32_bf16 v[20:23], v[174:177], v[206:209], v[20:23]
	v_mfma_f32_16x16x32_bf16 v[16:19], v[182:185], v[206:209], v[16:19]
	v_mfma_f32_16x16x32_bf16 v[4:7], v[174:177], v[214:217], v[4:7]
	v_mfma_f32_16x16x32_bf16 v[0:3], v[182:185], v[214:217], v[0:3]
	s_barrier
	s_add_i32 s65, 0, 0x18000
	s_add_i32 s66, 0, 0x1c000
	v_add_u32_e32 v166, s65, v153
	v_add_u32_e32 v182, s66, v153
	ds_read_b128 v[146:149], v166
	ds_read_b128 v[158:161], v166 offset:1024
	ds_read_b128 v[162:165], v166 offset:2048
	ds_read_b128 v[166:169], v166 offset:3072
	ds_read_b128 v[170:173], v182
	ds_read_b128 v[174:177], v182 offset:1024
	ds_read_b128 v[178:181], v182 offset:2048
	ds_read_b128 v[182:185], v182 offset:3072
	s_add_u32 s26, s26, 0x160000
	s_addc_u32 s27, s27, 0
	s_mov_b32 m0, s38
	v_lshl_add_u64 v[226:227], s[26:27], 0, v[128:129]
	ds_read_b128 v[186:189], v157 offset:32768
	ds_read_b128 v[190:193], v157 offset:33792
	ds_read_b128 v[194:197], v157 offset:34816
	ds_read_b128 v[198:201], v157 offset:35840
	ds_read_b128 v[202:205], v157 offset:36864
	ds_read_b128 v[206:209], v157 offset:37888
	ds_read_b128 v[210:213], v157 offset:38912
	ds_read_b128 v[214:217], v157 offset:39936
	global_load_lds_dwordx4 v[226:227], off
	v_lshl_add_u64 v[226:227], s[26:27], 0, v[132:133]
	s_mov_b32 m0, s39
	s_nop 0
	global_load_lds_dwordx4 v[226:227], off
	s_waitcnt vmcnt(8)
	s_waitcnt lgkmcnt(0)
	s_barrier
	s_waitcnt lgkmcnt(0)
	v_mfma_f32_16x16x32_bf16 v[124:127], v[146:149], v[186:189], v[124:127]
	v_mfma_f32_16x16x32_bf16 v[120:123], v[162:165], v[186:189], v[120:123]
	v_mfma_f32_16x16x32_bf16 v[108:111], v[146:149], v[194:197], v[108:111]
	v_mfma_f32_16x16x32_bf16 v[104:107], v[162:165], v[194:197], v[104:107]
	v_mfma_f32_16x16x32_bf16 v[92:95], v[146:149], v[202:205], v[92:95]
	v_mfma_f32_16x16x32_bf16 v[88:91], v[162:165], v[202:205], v[88:91]
	v_mfma_f32_16x16x32_bf16 v[76:79], v[146:149], v[210:213], v[76:79]
	v_mfma_f32_16x16x32_bf16 v[72:75], v[162:165], v[210:213], v[72:75]
	v_mfma_f32_16x16x32_bf16 v[124:127], v[158:161], v[190:193], v[124:127]
	v_mfma_f32_16x16x32_bf16 v[120:123], v[166:169], v[190:193], v[120:123]
	v_mfma_f32_16x16x32_bf16 v[108:111], v[158:161], v[198:201], v[108:111]
	v_mfma_f32_16x16x32_bf16 v[104:107], v[166:169], v[198:201], v[104:107]
	v_mfma_f32_16x16x32_bf16 v[92:95], v[158:161], v[206:209], v[92:95]
	v_mfma_f32_16x16x32_bf16 v[88:91], v[166:169], v[206:209], v[88:91]
	v_mfma_f32_16x16x32_bf16 v[76:79], v[158:161], v[214:217], v[76:79]
	v_mfma_f32_16x16x32_bf16 v[72:75], v[166:169], v[214:217], v[72:75]
	v_mfma_f32_16x16x32_bf16 v[116:119], v[170:173], v[186:189], v[116:119]
	v_mfma_f32_16x16x32_bf16 v[112:115], v[178:181], v[186:189], v[112:115]
	v_mfma_f32_16x16x32_bf16 v[100:103], v[170:173], v[194:197], v[100:103]
	v_mfma_f32_16x16x32_bf16 v[96:99], v[178:181], v[194:197], v[96:99]
	v_mfma_f32_16x16x32_bf16 v[84:87], v[170:173], v[202:205], v[84:87]
	v_mfma_f32_16x16x32_bf16 v[80:83], v[178:181], v[202:205], v[80:83]
	v_mfma_f32_16x16x32_bf16 v[68:71], v[170:173], v[210:213], v[68:71]
	v_mfma_f32_16x16x32_bf16 v[64:67], v[178:181], v[210:213], v[64:67]
	v_mfma_f32_16x16x32_bf16 v[116:119], v[174:177], v[190:193], v[116:119]
	v_mfma_f32_16x16x32_bf16 v[112:115], v[182:185], v[190:193], v[112:115]
	v_mfma_f32_16x16x32_bf16 v[100:103], v[174:177], v[198:201], v[100:103]
	v_mfma_f32_16x16x32_bf16 v[96:99], v[182:185], v[198:201], v[96:99]
	v_mfma_f32_16x16x32_bf16 v[84:87], v[174:177], v[206:209], v[84:87]
	v_mfma_f32_16x16x32_bf16 v[80:83], v[182:185], v[206:209], v[80:83]
	v_mfma_f32_16x16x32_bf16 v[68:71], v[174:177], v[214:217], v[68:71]
	v_mfma_f32_16x16x32_bf16 v[64:67], v[182:185], v[214:217], v[64:67]
	s_barrier
	s_add_i32 s26, s65, s17
	v_lshl_add_u64 v[218:219], v[218:219], 0, s[12:13]
	s_mov_b32 m0, s26
	ds_read_b128 v[186:189], v157 offset:49152
	ds_read_b128 v[190:193], v157 offset:50176
	ds_read_b128 v[194:197], v157 offset:51200
	ds_read_b128 v[198:201], v157 offset:52224
	ds_read_b128 v[202:205], v157 offset:53248
	ds_read_b128 v[206:209], v157 offset:54272
	ds_read_b128 v[210:213], v157 offset:55296
	ds_read_b128 v[214:217], v157 offset:56320
	global_load_lds_dwordx4 v[218:219], off
	s_add_i32 m0, s26, 0x2000
	s_add_u32 s24, s24, 0x160080
	v_lshl_add_u64 v[218:219], v[220:221], 0, s[12:13]
	s_addc_u32 s25, s25, 0
	s_add_i32 s26, s66, s17
	global_load_lds_dwordx4 v[218:219], off
	v_lshl_add_u64 v[218:219], s[24:25], 0, v[130:131]
	s_mov_b32 m0, s26
	s_nop 0
	global_load_lds_dwordx4 v[218:219], off
	v_lshl_add_u64 v[218:219], s[24:25], 0, v[134:135]
	s_add_i32 m0, s26, 0x2000
	s_nop 0
	global_load_lds_dwordx4 v[218:219], off
	v_lshl_add_u64 v[218:219], v[222:223], 0, s[12:13]
	s_mov_b32 m0, s41
	s_nop 0
	global_load_lds_dwordx4 v[218:219], off
	v_lshl_add_u64 v[218:219], v[224:225], 0, s[12:13]
	s_mov_b32 m0, s42
	s_nop 0
	global_load_lds_dwordx4 v[218:219], off
	s_waitcnt vmcnt(8)
	s_waitcnt lgkmcnt(0)
	s_barrier
	s_waitcnt lgkmcnt(0)
	v_mfma_f32_16x16x32_bf16 v[60:63], v[146:149], v[186:189], v[60:63]
	v_mfma_f32_16x16x32_bf16 v[56:59], v[162:165], v[186:189], v[56:59]
	v_mfma_f32_16x16x32_bf16 v[44:47], v[146:149], v[194:197], v[44:47]
	v_mfma_f32_16x16x32_bf16 v[40:43], v[162:165], v[194:197], v[40:43]
	v_mfma_f32_16x16x32_bf16 v[28:31], v[146:149], v[202:205], v[28:31]
	v_mfma_f32_16x16x32_bf16 v[24:27], v[162:165], v[202:205], v[24:27]
	v_mfma_f32_16x16x32_bf16 v[12:15], v[146:149], v[210:213], v[12:15]
	v_mfma_f32_16x16x32_bf16 v[8:11], v[162:165], v[210:213], v[8:11]
	v_mfma_f32_16x16x32_bf16 v[60:63], v[158:161], v[190:193], v[60:63]
	v_mfma_f32_16x16x32_bf16 v[56:59], v[166:169], v[190:193], v[56:59]
	v_mfma_f32_16x16x32_bf16 v[44:47], v[158:161], v[198:201], v[44:47]
	v_mfma_f32_16x16x32_bf16 v[40:43], v[166:169], v[198:201], v[40:43]
	v_mfma_f32_16x16x32_bf16 v[28:31], v[158:161], v[206:209], v[28:31]
	v_mfma_f32_16x16x32_bf16 v[24:27], v[166:169], v[206:209], v[24:27]
	v_mfma_f32_16x16x32_bf16 v[12:15], v[158:161], v[214:217], v[12:15]
	v_mfma_f32_16x16x32_bf16 v[8:11], v[166:169], v[214:217], v[8:11]
	v_mfma_f32_16x16x32_bf16 v[52:55], v[170:173], v[186:189], v[52:55]
	v_mfma_f32_16x16x32_bf16 v[48:51], v[178:181], v[186:189], v[48:51]
	v_mfma_f32_16x16x32_bf16 v[36:39], v[170:173], v[194:197], v[36:39]
	v_mfma_f32_16x16x32_bf16 v[32:35], v[178:181], v[194:197], v[32:35]
	v_mfma_f32_16x16x32_bf16 v[20:23], v[170:173], v[202:205], v[20:23]
	v_mfma_f32_16x16x32_bf16 v[16:19], v[178:181], v[202:205], v[16:19]
	v_mfma_f32_16x16x32_bf16 v[4:7], v[170:173], v[210:213], v[4:7]
	v_mfma_f32_16x16x32_bf16 v[0:3], v[178:181], v[210:213], v[0:3]
	v_mfma_f32_16x16x32_bf16 v[52:55], v[174:177], v[190:193], v[52:55]
	v_mfma_f32_16x16x32_bf16 v[48:51], v[182:185], v[190:193], v[48:51]
	v_mfma_f32_16x16x32_bf16 v[36:39], v[174:177], v[198:201], v[36:39]
	v_mfma_f32_16x16x32_bf16 v[32:35], v[182:185], v[198:201], v[32:35]
	v_mfma_f32_16x16x32_bf16 v[20:23], v[174:177], v[206:209], v[20:23]
	v_mfma_f32_16x16x32_bf16 v[16:19], v[182:185], v[206:209], v[16:19]
	v_mfma_f32_16x16x32_bf16 v[4:7], v[174:177], v[214:217], v[4:7]
	v_mfma_f32_16x16x32_bf16 v[0:3], v[182:185], v[214:217], v[0:3]
	s_barrier
	s_add_i32 s64, s64, 2
	s_add_u32 s22, s22, 0x100
	s_addc_u32 s23, s23, 0
	s_add_u32 s62, s62, 0x100
	s_addc_u32 s63, s63, 0
	s_cmpk_gt_u32 s64, 0x55
	s_cbranch_scc0 .LBB0_2376
	s_and_b64 vcc, exec, s[14:15]
	s_cbranch_vccz .LBB0_2379
	s_barrier
.LBB0_2379:
	s_setprio 0
	v_add_u32_e32 v148, s61, v152
	v_add_u32_e32 v146, s47, v154
	v_ashrrev_i32_e32 v149, 31, v148
	v_ashrrev_i32_e32 v147, 31, v146
	v_lshlrev_b64 v[166:167], 12, v[148:149]
	v_lshl_add_u64 v[158:159], s[50:51], 0, v[166:167]
	v_lshlrev_b64 v[146:147], 1, v[146:147]
	v_lshl_add_u64 v[162:163], v[158:159], 0, v[146:147]
	global_load_dwordx4 v[158:161], v[162:163], off
	s_nop 0
	global_load_dwordx4 v[162:165], v[162:163], off offset:256
	v_add_u32_e32 v168, 16, v148
	v_ashrrev_i32_e32 v169, 31, v168
	v_lshl_add_u64 v[166:167], s[56:57], 0, v[166:167]
	v_lshlrev_b64 v[168:169], 12, v[168:169]
	v_lshl_add_u64 v[166:167], v[166:167], 0, v[146:147]
	v_lshl_add_u64 v[170:171], s[50:51], 0, v[168:169]
	v_lshl_add_u64 v[170:171], v[170:171], 0, v[146:147]
	s_andn2_b64 vcc, exec, s[6:7]
	s_mov_b64 s[6:7], -1
	s_waitcnt vmcnt(0)
	v_lshlrev_b32_e32 v174, 16, v160
	v_and_b32_e32 v175, 0xffff0000, v160
	v_lshlrev_b32_e32 v172, 16, v158
	v_and_b32_e32 v173, 0xffff0000, v158
	v_lshlrev_b32_e32 v158, 16, v159
	v_and_b32_e32 v159, 0xffff0000, v159
	v_lshlrev_b32_e32 v160, 16, v161
	v_and_b32_e32 v161, 0xffff0000, v161
	v_lshlrev_b32_e32 v176, 16, v162
	v_and_b32_e32 v177, 0xffff0000, v162
	v_lshlrev_b32_e32 v162, 16, v163
	v_and_b32_e32 v163, 0xffff0000, v163
	v_lshlrev_b32_e32 v178, 16, v164
	v_and_b32_e32 v179, 0xffff0000, v164
	v_lshlrev_b32_e32 v164, 16, v165
	v_and_b32_e32 v165, 0xffff0000, v165
	v_pk_mul_f32 v[174:175], v[174:175], s[16:17] op_sel_hi:[1,0]
	v_pk_mul_f32 v[172:173], v[172:173], s[16:17] op_sel_hi:[1,0]
	v_pk_mul_f32 v[158:159], v[158:159], s[16:17] op_sel_hi:[1,0]
	v_pk_mul_f32 v[160:161], v[160:161], s[16:17] op_sel_hi:[1,0]
	v_pk_mul_f32 v[176:177], v[176:177], s[16:17] op_sel_hi:[1,0]
	v_pk_mul_f32 v[162:163], v[162:163], s[16:17] op_sel_hi:[1,0]
	v_pk_mul_f32 v[178:179], v[178:179], s[16:17] op_sel_hi:[1,0]
	v_pk_mul_f32 v[164:165], v[164:165], s[16:17] op_sel_hi:[1,0]
	v_pk_fma_f32 v[120:121], v[120:121], 0.5, v[174:175] op_sel_hi:[1,0,1]
	v_pk_fma_f32 v[126:127], v[126:127], 0.5, v[158:159] op_sel_hi:[1,0,1]
	v_pk_fma_f32 v[124:125], v[124:125], 0.5, v[172:173] op_sel_hi:[1,0,1]
	v_pk_fma_f32 v[122:123], v[122:123], 0.5, v[160:161] op_sel_hi:[1,0,1]
	v_pk_fma_f32 v[158:159], v[118:119], 0.5, v[162:163] op_sel_hi:[1,0,1]
	v_pk_fma_f32 v[160:161], v[116:117], 0.5, v[176:177] op_sel_hi:[1,0,1]
	v_cvt_pk_bf16_f32 v116, v124, v125
	v_cvt_pk_bf16_f32 v117, v126, v127
	v_cvt_pk_bf16_f32 v118, v120, v121
	v_cvt_pk_bf16_f32 v119, v122, v123
	global_store_dwordx4 v[166:167], v[116:119], off
	v_pk_fma_f32 v[120:121], v[114:115], 0.5, v[164:165] op_sel_hi:[1,0,1]
	v_pk_fma_f32 v[114:115], v[112:113], 0.5, v[178:179] op_sel_hi:[1,0,1]
	global_load_dwordx4 v[116:119], v[170:171], off
	v_cvt_pk_bf16_f32 v112, v160, v161
	v_cvt_pk_bf16_f32 v113, v158, v159
	v_cvt_pk_bf16_f32 v114, v114, v115
	v_cvt_pk_bf16_f32 v115, v120, v121
	global_store_dwordx4 v[166:167], v[112:115], off offset:256
	global_load_dwordx4 v[112:115], v[170:171], off offset:256
	v_add_u32_e32 v120, 32, v148
	v_ashrrev_i32_e32 v121, 31, v120
	v_lshlrev_b64 v[120:121], 12, v[120:121]
	v_lshl_add_u64 v[122:123], s[56:57], 0, v[168:169]
	v_lshl_add_u64 v[124:125], s[50:51], 0, v[120:121]
	v_lshl_add_u64 v[122:123], v[122:123], 0, v[146:147]
	v_lshl_add_u64 v[124:125], v[124:125], 0, v[146:147]
	s_waitcnt vmcnt(2)
	v_lshlrev_b32_e32 v158, 16, v118
	v_and_b32_e32 v159, 0xffff0000, v118
	v_lshlrev_b32_e32 v126, 16, v116
	v_and_b32_e32 v127, 0xffff0000, v116
	v_lshlrev_b32_e32 v116, 16, v117
	v_and_b32_e32 v117, 0xffff0000, v117
	v_lshlrev_b32_e32 v118, 16, v119
	v_and_b32_e32 v119, 0xffff0000, v119
	s_waitcnt vmcnt(0)
	v_lshlrev_b32_e32 v160, 16, v112
	v_and_b32_e32 v161, 0xffff0000, v112
	v_lshlrev_b32_e32 v112, 16, v113
	v_and_b32_e32 v113, 0xffff0000, v113
	v_lshlrev_b32_e32 v162, 16, v114
	v_and_b32_e32 v163, 0xffff0000, v114
	v_lshlrev_b32_e32 v114, 16, v115
	v_and_b32_e32 v115, 0xffff0000, v115
	v_pk_mul_f32 v[158:159], v[158:159], s[16:17] op_sel_hi:[1,0]
	v_pk_mul_f32 v[126:127], v[126:127], s[16:17] op_sel_hi:[1,0]
	v_pk_mul_f32 v[116:117], v[116:117], s[16:17] op_sel_hi:[1,0]
	v_pk_mul_f32 v[118:119], v[118:119], s[16:17] op_sel_hi:[1,0]
	v_pk_mul_f32 v[160:161], v[160:161], s[16:17] op_sel_hi:[1,0]
	v_pk_mul_f32 v[112:113], v[112:113], s[16:17] op_sel_hi:[1,0]
	v_pk_mul_f32 v[162:163], v[162:163], s[16:17] op_sel_hi:[1,0]
	v_pk_mul_f32 v[114:115], v[114:115], s[16:17] op_sel_hi:[1,0]
	v_pk_fma_f32 v[104:105], v[104:105], 0.5, v[158:159] op_sel_hi:[1,0,1]
	v_pk_fma_f32 v[110:111], v[110:111], 0.5, v[116:117] op_sel_hi:[1,0,1]
	v_pk_fma_f32 v[108:109], v[108:109], 0.5, v[126:127] op_sel_hi:[1,0,1]
	v_pk_fma_f32 v[106:107], v[106:107], 0.5, v[118:119] op_sel_hi:[1,0,1]
	v_pk_fma_f32 v[112:113], v[102:103], 0.5, v[112:113] op_sel_hi:[1,0,1]
	v_pk_fma_f32 v[116:117], v[100:101], 0.5, v[160:161] op_sel_hi:[1,0,1]
	v_cvt_pk_bf16_f32 v100, v108, v109
	v_cvt_pk_bf16_f32 v101, v110, v111
	v_cvt_pk_bf16_f32 v102, v104, v105
	v_cvt_pk_bf16_f32 v103, v106, v107
	global_store_dwordx4 v[122:123], v[100:103], off
	v_pk_fma_f32 v[104:105], v[98:99], 0.5, v[114:115] op_sel_hi:[1,0,1]
	v_pk_fma_f32 v[98:99], v[96:97], 0.5, v[162:163] op_sel_hi:[1,0,1]
	global_load_dwordx4 v[100:103], v[124:125], off
	v_cvt_pk_bf16_f32 v96, v116, v117
	v_cvt_pk_bf16_f32 v97, v112, v113
	v_cvt_pk_bf16_f32 v98, v98, v99
	v_cvt_pk_bf16_f32 v99, v104, v105
	global_store_dwordx4 v[122:123], v[96:99], off offset:256
	global_load_dwordx4 v[96:99], v[124:125], off offset:256
	v_add_u32_e32 v104, 48, v148
	v_ashrrev_i32_e32 v105, 31, v104
	v_lshlrev_b64 v[104:105], 12, v[104:105]
	v_lshl_add_u64 v[106:107], s[56:57], 0, v[120:121]
	v_lshl_add_u64 v[108:109], s[50:51], 0, v[104:105]
	v_lshl_add_u64 v[106:107], v[106:107], 0, v[146:147]
	v_lshl_add_u64 v[108:109], v[108:109], 0, v[146:147]
	s_waitcnt vmcnt(2)
	v_lshlrev_b32_e32 v112, 16, v102
	v_and_b32_e32 v113, 0xffff0000, v102
	v_lshlrev_b32_e32 v110, 16, v100
	v_and_b32_e32 v111, 0xffff0000, v100
	v_lshlrev_b32_e32 v100, 16, v101
	v_and_b32_e32 v101, 0xffff0000, v101
	v_lshlrev_b32_e32 v102, 16, v103
	v_and_b32_e32 v103, 0xffff0000, v103
	s_waitcnt vmcnt(0)
	v_lshlrev_b32_e32 v114, 16, v96
	v_and_b32_e32 v115, 0xffff0000, v96
	v_lshlrev_b32_e32 v96, 16, v97
	v_and_b32_e32 v97, 0xffff0000, v97
	v_lshlrev_b32_e32 v116, 16, v98
	v_and_b32_e32 v117, 0xffff0000, v98
	v_lshlrev_b32_e32 v98, 16, v99
	v_and_b32_e32 v99, 0xffff0000, v99
	v_pk_mul_f32 v[112:113], v[112:113], s[16:17] op_sel_hi:[1,0]
	v_pk_mul_f32 v[110:111], v[110:111], s[16:17] op_sel_hi:[1,0]
	v_pk_mul_f32 v[100:101], v[100:101], s[16:17] op_sel_hi:[1,0]
	v_pk_mul_f32 v[102:103], v[102:103], s[16:17] op_sel_hi:[1,0]
	v_pk_mul_f32 v[114:115], v[114:115], s[16:17] op_sel_hi:[1,0]
	v_pk_mul_f32 v[96:97], v[96:97], s[16:17] op_sel_hi:[1,0]
	v_pk_mul_f32 v[116:117], v[116:117], s[16:17] op_sel_hi:[1,0]
	v_pk_mul_f32 v[98:99], v[98:99], s[16:17] op_sel_hi:[1,0]
	v_pk_fma_f32 v[88:89], v[88:89], 0.5, v[112:113] op_sel_hi:[1,0,1]
	v_pk_fma_f32 v[94:95], v[94:95], 0.5, v[100:101] op_sel_hi:[1,0,1]
	v_pk_fma_f32 v[92:93], v[92:93], 0.5, v[110:111] op_sel_hi:[1,0,1]
	v_pk_fma_f32 v[90:91], v[90:91], 0.5, v[102:103] op_sel_hi:[1,0,1]
	v_pk_fma_f32 v[96:97], v[86:87], 0.5, v[96:97] op_sel_hi:[1,0,1]
	v_pk_fma_f32 v[100:101], v[84:85], 0.5, v[114:115] op_sel_hi:[1,0,1]
	v_cvt_pk_bf16_f32 v84, v92, v93
	v_cvt_pk_bf16_f32 v85, v94, v95
	v_cvt_pk_bf16_f32 v86, v88, v89
	v_cvt_pk_bf16_f32 v87, v90, v91
	global_store_dwordx4 v[106:107], v[84:87], off
	v_pk_fma_f32 v[88:89], v[82:83], 0.5, v[98:99] op_sel_hi:[1,0,1]
	v_pk_fma_f32 v[82:83], v[80:81], 0.5, v[116:117] op_sel_hi:[1,0,1]
	global_load_dwordx4 v[84:87], v[108:109], off
	v_cvt_pk_bf16_f32 v80, v100, v101
	v_cvt_pk_bf16_f32 v81, v96, v97
	v_cvt_pk_bf16_f32 v82, v82, v83
	v_cvt_pk_bf16_f32 v83, v88, v89
	global_store_dwordx4 v[106:107], v[80:83], off offset:256
	global_load_dwordx4 v[80:83], v[108:109], off offset:256
	v_add_u32_e32 v88, 0x80, v148
	v_ashrrev_i32_e32 v89, 31, v88
	v_lshlrev_b64 v[88:89], 12, v[88:89]
	v_lshl_add_u64 v[90:91], s[56:57], 0, v[104:105]
	v_lshl_add_u64 v[92:93], s[50:51], 0, v[88:89]
	v_lshl_add_u64 v[90:91], v[90:91], 0, v[146:147]
	v_lshl_add_u64 v[92:93], v[92:93], 0, v[146:147]
	s_waitcnt vmcnt(2)
	v_lshlrev_b32_e32 v96, 16, v86
	v_and_b32_e32 v97, 0xffff0000, v86
	v_lshlrev_b32_e32 v94, 16, v84
	v_and_b32_e32 v95, 0xffff0000, v84
	v_lshlrev_b32_e32 v84, 16, v85
	v_and_b32_e32 v85, 0xffff0000, v85
	v_lshlrev_b32_e32 v86, 16, v87
	v_and_b32_e32 v87, 0xffff0000, v87
	s_waitcnt vmcnt(0)
	v_lshlrev_b32_e32 v98, 16, v80
	v_and_b32_e32 v99, 0xffff0000, v80
	v_lshlrev_b32_e32 v80, 16, v81
	v_and_b32_e32 v81, 0xffff0000, v81
	v_lshlrev_b32_e32 v100, 16, v82
	v_and_b32_e32 v101, 0xffff0000, v82
	v_lshlrev_b32_e32 v82, 16, v83
	v_and_b32_e32 v83, 0xffff0000, v83
	v_pk_mul_f32 v[96:97], v[96:97], s[16:17] op_sel_hi:[1,0]
	v_pk_mul_f32 v[94:95], v[94:95], s[16:17] op_sel_hi:[1,0]
	v_pk_mul_f32 v[84:85], v[84:85], s[16:17] op_sel_hi:[1,0]
	v_pk_mul_f32 v[86:87], v[86:87], s[16:17] op_sel_hi:[1,0]
	v_pk_mul_f32 v[98:99], v[98:99], s[16:17] op_sel_hi:[1,0]
	v_pk_mul_f32 v[80:81], v[80:81], s[16:17] op_sel_hi:[1,0]
	v_pk_mul_f32 v[100:101], v[100:101], s[16:17] op_sel_hi:[1,0]
	v_pk_mul_f32 v[82:83], v[82:83], s[16:17] op_sel_hi:[1,0]
	v_pk_fma_f32 v[72:73], v[72:73], 0.5, v[96:97] op_sel_hi:[1,0,1]
	v_pk_fma_f32 v[78:79], v[78:79], 0.5, v[84:85] op_sel_hi:[1,0,1]
	v_pk_fma_f32 v[76:77], v[76:77], 0.5, v[94:95] op_sel_hi:[1,0,1]
	v_pk_fma_f32 v[74:75], v[74:75], 0.5, v[86:87] op_sel_hi:[1,0,1]
	v_pk_fma_f32 v[80:81], v[70:71], 0.5, v[80:81] op_sel_hi:[1,0,1]
	v_pk_fma_f32 v[84:85], v[68:69], 0.5, v[98:99] op_sel_hi:[1,0,1]
	v_cvt_pk_bf16_f32 v68, v76, v77
	v_cvt_pk_bf16_f32 v69, v78, v79
	v_cvt_pk_bf16_f32 v70, v72, v73
	v_cvt_pk_bf16_f32 v71, v74, v75
	global_store_dwordx4 v[90:91], v[68:71], off
	v_pk_fma_f32 v[72:73], v[66:67], 0.5, v[82:83] op_sel_hi:[1,0,1]
	v_pk_fma_f32 v[66:67], v[64:65], 0.5, v[100:101] op_sel_hi:[1,0,1]
	global_load_dwordx4 v[68:71], v[92:93], off
	v_cvt_pk_bf16_f32 v64, v84, v85
	v_cvt_pk_bf16_f32 v65, v80, v81
	v_cvt_pk_bf16_f32 v66, v66, v67
	v_cvt_pk_bf16_f32 v67, v72, v73
	global_store_dwordx4 v[90:91], v[64:67], off offset:256
	global_load_dwordx4 v[64:67], v[92:93], off offset:256
	v_add_u32_e32 v72, 0x90, v148
	v_ashrrev_i32_e32 v73, 31, v72
	v_lshlrev_b64 v[72:73], 12, v[72:73]
	v_lshl_add_u64 v[74:75], s[56:57], 0, v[88:89]
	v_lshl_add_u64 v[76:77], s[50:51], 0, v[72:73]
	v_lshl_add_u64 v[74:75], v[74:75], 0, v[146:147]
	v_lshl_add_u64 v[76:77], v[76:77], 0, v[146:147]
	s_waitcnt vmcnt(2)
	v_lshlrev_b32_e32 v80, 16, v70
	v_and_b32_e32 v81, 0xffff0000, v70
	v_lshlrev_b32_e32 v78, 16, v68
	v_and_b32_e32 v79, 0xffff0000, v68
	v_lshlrev_b32_e32 v68, 16, v69
	v_and_b32_e32 v69, 0xffff0000, v69
	v_lshlrev_b32_e32 v70, 16, v71
	v_and_b32_e32 v71, 0xffff0000, v71
	s_waitcnt vmcnt(0)
	v_lshlrev_b32_e32 v82, 16, v64
	v_and_b32_e32 v83, 0xffff0000, v64
	v_lshlrev_b32_e32 v64, 16, v65
	v_and_b32_e32 v65, 0xffff0000, v65
	v_lshlrev_b32_e32 v84, 16, v66
	v_and_b32_e32 v85, 0xffff0000, v66
	v_lshlrev_b32_e32 v66, 16, v67
	v_and_b32_e32 v67, 0xffff0000, v67
	v_pk_mul_f32 v[80:81], v[80:81], s[16:17] op_sel_hi:[1,0]
	v_pk_mul_f32 v[78:79], v[78:79], s[16:17] op_sel_hi:[1,0]
	v_pk_mul_f32 v[68:69], v[68:69], s[16:17] op_sel_hi:[1,0]
	v_pk_mul_f32 v[70:71], v[70:71], s[16:17] op_sel_hi:[1,0]
	v_pk_mul_f32 v[82:83], v[82:83], s[16:17] op_sel_hi:[1,0]
	v_pk_mul_f32 v[64:65], v[64:65], s[16:17] op_sel_hi:[1,0]
	v_pk_mul_f32 v[84:85], v[84:85], s[16:17] op_sel_hi:[1,0]
	v_pk_mul_f32 v[66:67], v[66:67], s[16:17] op_sel_hi:[1,0]
	v_pk_fma_f32 v[56:57], v[56:57], 0.5, v[80:81] op_sel_hi:[1,0,1]
	v_pk_fma_f32 v[62:63], v[62:63], 0.5, v[68:69] op_sel_hi:[1,0,1]
	v_pk_fma_f32 v[60:61], v[60:61], 0.5, v[78:79] op_sel_hi:[1,0,1]
	v_pk_fma_f32 v[58:59], v[58:59], 0.5, v[70:71] op_sel_hi:[1,0,1]
	v_pk_fma_f32 v[64:65], v[54:55], 0.5, v[64:65] op_sel_hi:[1,0,1]
	v_pk_fma_f32 v[68:69], v[52:53], 0.5, v[82:83] op_sel_hi:[1,0,1]
	v_cvt_pk_bf16_f32 v52, v60, v61
	v_cvt_pk_bf16_f32 v53, v62, v63
	v_cvt_pk_bf16_f32 v54, v56, v57
	v_cvt_pk_bf16_f32 v55, v58, v59
	global_store_dwordx4 v[74:75], v[52:55], off
	v_pk_fma_f32 v[56:57], v[50:51], 0.5, v[66:67] op_sel_hi:[1,0,1]
	v_pk_fma_f32 v[50:51], v[48:49], 0.5, v[84:85] op_sel_hi:[1,0,1]
	global_load_dwordx4 v[52:55], v[76:77], off
	v_cvt_pk_bf16_f32 v48, v68, v69
	v_cvt_pk_bf16_f32 v49, v64, v65
	v_cvt_pk_bf16_f32 v50, v50, v51
	v_cvt_pk_bf16_f32 v51, v56, v57
	global_store_dwordx4 v[74:75], v[48:51], off offset:256
	global_load_dwordx4 v[48:51], v[76:77], off offset:256
	v_add_u32_e32 v56, 0xa0, v148
	v_ashrrev_i32_e32 v57, 31, v56
	v_lshlrev_b64 v[56:57], 12, v[56:57]
	v_lshl_add_u64 v[58:59], s[56:57], 0, v[72:73]
	v_lshl_add_u64 v[60:61], s[50:51], 0, v[56:57]
	v_lshl_add_u64 v[58:59], v[58:59], 0, v[146:147]
	v_lshl_add_u64 v[60:61], v[60:61], 0, v[146:147]
	s_waitcnt vmcnt(2)
	v_lshlrev_b32_e32 v64, 16, v54
	v_and_b32_e32 v65, 0xffff0000, v54
	v_lshlrev_b32_e32 v62, 16, v52
	v_and_b32_e32 v63, 0xffff0000, v52
	v_lshlrev_b32_e32 v52, 16, v53
	v_and_b32_e32 v53, 0xffff0000, v53
	v_lshlrev_b32_e32 v54, 16, v55
	v_and_b32_e32 v55, 0xffff0000, v55
	s_waitcnt vmcnt(0)
	v_lshlrev_b32_e32 v66, 16, v48
	v_and_b32_e32 v67, 0xffff0000, v48
	v_lshlrev_b32_e32 v48, 16, v49
	v_and_b32_e32 v49, 0xffff0000, v49
	v_lshlrev_b32_e32 v68, 16, v50
	v_and_b32_e32 v69, 0xffff0000, v50
	v_lshlrev_b32_e32 v50, 16, v51
	v_and_b32_e32 v51, 0xffff0000, v51
	v_pk_mul_f32 v[64:65], v[64:65], s[16:17] op_sel_hi:[1,0]
	v_pk_mul_f32 v[62:63], v[62:63], s[16:17] op_sel_hi:[1,0]
	v_pk_mul_f32 v[52:53], v[52:53], s[16:17] op_sel_hi:[1,0]
	v_pk_mul_f32 v[54:55], v[54:55], s[16:17] op_sel_hi:[1,0]
	v_pk_mul_f32 v[66:67], v[66:67], s[16:17] op_sel_hi:[1,0]
	v_pk_mul_f32 v[48:49], v[48:49], s[16:17] op_sel_hi:[1,0]
	v_pk_mul_f32 v[68:69], v[68:69], s[16:17] op_sel_hi:[1,0]
	v_pk_mul_f32 v[50:51], v[50:51], s[16:17] op_sel_hi:[1,0]
	v_pk_fma_f32 v[40:41], v[40:41], 0.5, v[64:65] op_sel_hi:[1,0,1]
	v_pk_fma_f32 v[46:47], v[46:47], 0.5, v[52:53] op_sel_hi:[1,0,1]
	v_pk_fma_f32 v[44:45], v[44:45], 0.5, v[62:63] op_sel_hi:[1,0,1]
	v_pk_fma_f32 v[42:43], v[42:43], 0.5, v[54:55] op_sel_hi:[1,0,1]
	v_pk_fma_f32 v[48:49], v[38:39], 0.5, v[48:49] op_sel_hi:[1,0,1]
	v_pk_fma_f32 v[52:53], v[36:37], 0.5, v[66:67] op_sel_hi:[1,0,1]
	v_cvt_pk_bf16_f32 v36, v44, v45
	v_cvt_pk_bf16_f32 v37, v46, v47
	v_cvt_pk_bf16_f32 v38, v40, v41
	v_cvt_pk_bf16_f32 v39, v42, v43
	global_store_dwordx4 v[58:59], v[36:39], off
	v_pk_fma_f32 v[40:41], v[34:35], 0.5, v[50:51] op_sel_hi:[1,0,1]
	v_pk_fma_f32 v[34:35], v[32:33], 0.5, v[68:69] op_sel_hi:[1,0,1]
	global_load_dwordx4 v[36:39], v[60:61], off
	v_cvt_pk_bf16_f32 v32, v52, v53
	v_cvt_pk_bf16_f32 v33, v48, v49
	v_cvt_pk_bf16_f32 v34, v34, v35
	v_cvt_pk_bf16_f32 v35, v40, v41
	global_store_dwordx4 v[58:59], v[32:35], off offset:256
	global_load_dwordx4 v[32:35], v[60:61], off offset:256
	v_add_u32_e32 v40, 0xb0, v148
	v_ashrrev_i32_e32 v41, 31, v40
	v_lshlrev_b64 v[40:41], 12, v[40:41]
	v_lshl_add_u64 v[42:43], s[56:57], 0, v[56:57]
	v_lshl_add_u64 v[44:45], s[50:51], 0, v[40:41]
	v_lshl_add_u64 v[42:43], v[42:43], 0, v[146:147]
	v_lshl_add_u64 v[44:45], v[44:45], 0, v[146:147]
	s_waitcnt vmcnt(2)
	v_lshlrev_b32_e32 v48, 16, v38
	v_and_b32_e32 v49, 0xffff0000, v38
	v_pk_mul_f32 v[48:49], v[48:49], s[16:17] op_sel_hi:[1,0]
	v_lshlrev_b32_e32 v46, 16, v36
	v_and_b32_e32 v47, 0xffff0000, v36
	v_lshlrev_b32_e32 v36, 16, v37
	s_waitcnt vmcnt(0)
	v_lshlrev_b32_e32 v50, 16, v32
	v_and_b32_e32 v51, 0xffff0000, v32
	v_lshlrev_b32_e32 v32, 16, v33
	v_and_b32_e32 v33, 0xffff0000, v33
	v_lshlrev_b32_e32 v52, 16, v34
	v_and_b32_e32 v53, 0xffff0000, v34
	v_lshlrev_b32_e32 v34, 16, v35
	v_and_b32_e32 v35, 0xffff0000, v35
	v_and_b32_e32 v37, 0xffff0000, v37
	v_lshlrev_b32_e32 v38, 16, v39
	v_and_b32_e32 v39, 0xffff0000, v39
	v_pk_mul_f32 v[32:33], v[32:33], s[16:17] op_sel_hi:[1,0]
	v_pk_mul_f32 v[52:53], v[52:53], s[16:17] op_sel_hi:[1,0]
	v_pk_mul_f32 v[34:35], v[34:35], s[16:17] op_sel_hi:[1,0]
	v_pk_fma_f32 v[24:25], v[24:25], 0.5, v[48:49] op_sel_hi:[1,0,1]
	v_pk_mul_f32 v[46:47], v[46:47], s[16:17] op_sel_hi:[1,0]
	v_pk_mul_f32 v[36:37], v[36:37], s[16:17] op_sel_hi:[1,0]
	v_pk_mul_f32 v[38:39], v[38:39], s[16:17] op_sel_hi:[1,0]
	v_pk_mul_f32 v[50:51], v[50:51], s[16:17] op_sel_hi:[1,0]
	v_pk_fma_f32 v[32:33], v[22:23], 0.5, v[32:33] op_sel_hi:[1,0,1]
	v_cvt_pk_bf16_f32 v22, v24, v25
	v_pk_fma_f32 v[24:25], v[18:19], 0.5, v[34:35] op_sel_hi:[1,0,1]
	v_pk_fma_f32 v[18:19], v[16:17], 0.5, v[52:53] op_sel_hi:[1,0,1]
	v_pk_fma_f32 v[30:31], v[30:31], 0.5, v[36:37] op_sel_hi:[1,0,1]
	v_pk_fma_f32 v[28:29], v[28:29], 0.5, v[46:47] op_sel_hi:[1,0,1]
	v_pk_fma_f32 v[26:27], v[26:27], 0.5, v[38:39] op_sel_hi:[1,0,1]
	v_pk_fma_f32 v[36:37], v[20:21], 0.5, v[50:51] op_sel_hi:[1,0,1]
	v_cvt_pk_bf16_f32 v20, v28, v29
	v_cvt_pk_bf16_f32 v21, v30, v31
	v_cvt_pk_bf16_f32 v23, v26, v27
	global_store_dwordx4 v[42:43], v[20:23], off
	v_cvt_pk_bf16_f32 v16, v36, v37
	v_cvt_pk_bf16_f32 v17, v32, v33
	v_cvt_pk_bf16_f32 v18, v18, v19
	v_cvt_pk_bf16_f32 v19, v24, v25
	global_store_dwordx4 v[42:43], v[16:19], off offset:256
	global_load_dwordx4 v[20:23], v[44:45], off
	v_lshl_add_u64 v[24:25], s[56:57], 0, v[40:41]
	global_load_dwordx4 v[16:19], v[44:45], off offset:256
	v_lshl_add_u64 v[24:25], v[24:25], 0, v[146:147]
	s_waitcnt vmcnt(1)
	v_lshlrev_b32_e32 v26, 16, v20
	v_and_b32_e32 v27, 0xffff0000, v20
	v_lshlrev_b32_e32 v20, 16, v21
	v_and_b32_e32 v21, 0xffff0000, v21
	v_lshlrev_b32_e32 v28, 16, v22
	v_and_b32_e32 v29, 0xffff0000, v22
	v_lshlrev_b32_e32 v22, 16, v23
	v_and_b32_e32 v23, 0xffff0000, v23
	s_waitcnt vmcnt(0)
	v_lshlrev_b32_e32 v30, 16, v16
	v_and_b32_e32 v31, 0xffff0000, v16
	v_lshlrev_b32_e32 v16, 16, v17
	v_and_b32_e32 v17, 0xffff0000, v17
	v_lshlrev_b32_e32 v32, 16, v18
	v_and_b32_e32 v33, 0xffff0000, v18
	v_lshlrev_b32_e32 v18, 16, v19
	v_and_b32_e32 v19, 0xffff0000, v19
	v_pk_mul_f32 v[26:27], v[26:27], s[16:17] op_sel_hi:[1,0]
	v_pk_mul_f32 v[20:21], v[20:21], s[16:17] op_sel_hi:[1,0]
	v_pk_mul_f32 v[28:29], v[28:29], s[16:17] op_sel_hi:[1,0]
	v_pk_mul_f32 v[22:23], v[22:23], s[16:17] op_sel_hi:[1,0]
	v_pk_mul_f32 v[30:31], v[30:31], s[16:17] op_sel_hi:[1,0]
	v_pk_mul_f32 v[16:17], v[16:17], s[16:17] op_sel_hi:[1,0]
	v_pk_mul_f32 v[32:33], v[32:33], s[16:17] op_sel_hi:[1,0]
	v_pk_mul_f32 v[18:19], v[18:19], s[16:17] op_sel_hi:[1,0]
	v_pk_fma_f32 v[14:15], v[14:15], 0.5, v[20:21] op_sel_hi:[1,0,1]
	v_pk_fma_f32 v[12:13], v[12:13], 0.5, v[26:27] op_sel_hi:[1,0,1]
	v_pk_fma_f32 v[10:11], v[10:11], 0.5, v[22:23] op_sel_hi:[1,0,1]
	v_pk_fma_f32 v[8:9], v[8:9], 0.5, v[28:29] op_sel_hi:[1,0,1]
	v_pk_fma_f32 v[6:7], v[6:7], 0.5, v[16:17] op_sel_hi:[1,0,1]
	v_pk_fma_f32 v[4:5], v[4:5], 0.5, v[30:31] op_sel_hi:[1,0,1]
	v_pk_fma_f32 v[16:17], v[2:3], 0.5, v[18:19] op_sel_hi:[1,0,1]
	v_pk_fma_f32 v[18:19], v[0:1], 0.5, v[32:33] op_sel_hi:[1,0,1]
	v_cvt_pk_bf16_f32 v0, v12, v13
	v_cvt_pk_bf16_f32 v1, v14, v15
	v_cvt_pk_bf16_f32 v2, v8, v9
	v_cvt_pk_bf16_f32 v3, v10, v11
	v_cvt_pk_bf16_f32 v4, v4, v5
	v_cvt_pk_bf16_f32 v5, v6, v7
	s_nop 0
	v_cvt_pk_bf16_f32 v6, v18, v19
	v_cvt_pk_bf16_f32 v7, v16, v17
	global_store_dwordx4 v[24:25], v[0:3], off
	global_store_dwordx4 v[24:25], v[4:7], off offset:256
	s_cbranch_vccnz .LBB0_2368
	s_andn2_b64 vcc, exec, s[10:11]
	s_cbranch_vccnz .LBB0_2367
	s_barrier
	s_branch .LBB0_2367
